# v5_g1pre
# speedup vs baseline: 1.0002x; 1.0002x over previous
; #define WAIT_L(n) asm volatile("s_waitcnt lgkmcnt(" #n ")" ::: "memory")
; #define BAR __builtin_amdgcn_s_barrier()
; #define SCHED __builtin_amdgcn_sched_barrier(0)
;     ...
;   for (int t = 0; t < nt - 2; t += 2) {
;     LDB(B0, 0, 0); SCHED; LDA(At, 0, 0); STAGE(SA(1, 1), A, brow + HALF, t + 1);
;     WAIT_L(8); BAR; WAIT_L(0); MMA(0, 0, At, B0); BAR; SCHED;
;     LDB(B1, 0, 1); STAGE(SB(0, 0), Bt, bcol, t + 2);
;     BAR; WAIT_L(0); MMA(0, 1, At, B1); BAR;
;     LDA(At, 0, 1); STAGE(SA(0, 0), A, brow, t + 2);
;     BAR; WAIT_L(0); MMA(1, 0, At, B0); BAR; SCHED;
.LBB0_420:
	ds_read_b128 v[154:157], v152
	ds_read_b128 v[158:161], v152 offset:1024
	ds_read_b128 v[162:165], v152 offset:2048
	ds_read_b128 v[166:169], v152 offset:3072
	s_add_i32 s28, s4, s27
	v_readfirstlane_b32 s11, v150
	s_add_i32 s10, s28, 0x80080
	s_mov_b32 m0, s11
	v_readfirstlane_b32 s11, v149
	buffer_load_dwordx4 v132, s[88:91], s10 offen lds
	s_mov_b32 m0, s11
	s_nop 0
	buffer_load_dwordx4 v131, s[88:91], s10 offen lds
	ds_read_b128 v[170:173], v128
	ds_read_b128 v[174:177], v128 offset:1024
	ds_read_b128 v[178:181], v128 offset:2048
	ds_read_b128 v[182:185], v128 offset:3072
	ds_read_b128 v[186:189], v128 offset:4096
	ds_read_b128 v[190:193], v128 offset:5120
	ds_read_b128 v[194:197], v128 offset:6144
	ds_read_b128 v[198:201], v129 offset:7168
	s_waitcnt lgkmcnt(8)
	s_barrier
	s_setprio 1
	s_waitcnt lgkmcnt(7)
	v_mfma_f32_16x16x32_bf16 v[124:127], v[170:173], v[154:157], v[124:127]
	v_mfma_f32_16x16x32_bf16 v[120:123], v[170:173], v[162:165], v[120:123]
	s_waitcnt lgkmcnt(5)
	v_mfma_f32_16x16x32_bf16 v[116:119], v[178:181], v[154:157], v[116:119]
	v_mfma_f32_16x16x32_bf16 v[112:115], v[178:181], v[162:165], v[112:115]
	s_waitcnt lgkmcnt(3)
	v_mfma_f32_16x16x32_bf16 v[108:111], v[186:189], v[154:157], v[108:111]
	v_mfma_f32_16x16x32_bf16 v[104:107], v[186:189], v[162:165], v[104:107]
	s_waitcnt lgkmcnt(1)
	v_mfma_f32_16x16x32_bf16 v[100:103], v[194:197], v[154:157], v[100:103]
	v_mfma_f32_16x16x32_bf16 v[96:99], v[194:197], v[162:165], v[96:99]
	v_mfma_f32_16x16x32_bf16 v[124:127], v[174:177], v[158:161], v[124:127]
	v_mfma_f32_16x16x32_bf16 v[120:123], v[174:177], v[166:169], v[120:123]
	v_mfma_f32_16x16x32_bf16 v[116:119], v[182:185], v[158:161], v[116:119]
	v_mfma_f32_16x16x32_bf16 v[112:115], v[182:185], v[166:169], v[112:115]
	v_mfma_f32_16x16x32_bf16 v[108:111], v[190:193], v[158:161], v[108:111]
	v_mfma_f32_16x16x32_bf16 v[104:107], v[190:193], v[166:169], v[104:107]
	s_waitcnt lgkmcnt(0)
	v_mfma_f32_16x16x32_bf16 v[100:103], v[198:201], v[158:161], v[100:103]
	v_mfma_f32_16x16x32_bf16 v[96:99], v[198:201], v[166:169], v[96:99]
	s_setprio 0
	s_barrier
	s_add_i32 s29, s5, s27
	v_readfirstlane_b32 s31, v134
	s_add_i32 s30, s29, 0x100
	s_mov_b32 s10, s90
	s_mov_b32 s11, s91
	s_mov_b32 m0, s31
	v_readfirstlane_b32 s31, v135
	buffer_load_dwordx4 v132, s[8:11], s30 offen lds
	s_mov_b32 m0, s31
	s_nop 0
	buffer_load_dwordx4 v131, s[8:11], s30 offen lds
	ds_read_b128 v[202:205], v143
	ds_read_b128 v[206:209], v143 offset:1024
	ds_read_b128 v[212:215], v143 offset:2048
	ds_read_b128 v[216:219], v143 offset:3072
	s_barrier
	s_setprio 1
	s_waitcnt lgkmcnt(3)
	v_mfma_f32_16x16x32_bf16 v[92:95], v[170:173], v[202:205], v[92:95]
	s_waitcnt lgkmcnt(1)
	v_mfma_f32_16x16x32_bf16 v[88:91], v[170:173], v[212:215], v[88:91]
	v_mfma_f32_16x16x32_bf16 v[84:87], v[178:181], v[202:205], v[84:87]
	v_mfma_f32_16x16x32_bf16 v[80:83], v[178:181], v[212:215], v[80:83]
	v_mfma_f32_16x16x32_bf16 v[76:79], v[186:189], v[202:205], v[76:79]
	v_mfma_f32_16x16x32_bf16 v[72:75], v[186:189], v[212:215], v[72:75]
	v_mfma_f32_16x16x32_bf16 v[68:71], v[194:197], v[202:205], v[68:71]
	v_mfma_f32_16x16x32_bf16 v[64:67], v[194:197], v[212:215], v[64:67]
	v_mfma_f32_16x16x32_bf16 v[92:95], v[174:177], v[206:209], v[92:95]
	s_waitcnt lgkmcnt(0)
	v_mfma_f32_16x16x32_bf16 v[88:91], v[174:177], v[216:219], v[88:91]
	v_mfma_f32_16x16x32_bf16 v[84:87], v[182:185], v[206:209], v[84:87]
	v_mfma_f32_16x16x32_bf16 v[80:83], v[182:185], v[216:219], v[80:83]
	v_mfma_f32_16x16x32_bf16 v[76:79], v[190:193], v[206:209], v[76:79]
	v_mfma_f32_16x16x32_bf16 v[72:75], v[190:193], v[216:219], v[72:75]
	v_mfma_f32_16x16x32_bf16 v[68:71], v[198:201], v[206:209], v[68:71]
	v_mfma_f32_16x16x32_bf16 v[64:67], v[198:201], v[216:219], v[64:67]
	s_setprio 0
	v_readfirstlane_b32 s31, v136
	s_add_i32 s30, s28, 0x100
	s_mov_b32 m0, s31
	v_readfirstlane_b32 s31, v137
	s_barrier
	buffer_load_dwordx4 v132, s[88:91], s30 offen lds
	s_mov_b32 m0, s31
	s_nop 0
	buffer_load_dwordx4 v131, s[88:91], s30 offen lds
	ds_read_b128 v[170:173], v128 offset:16384
	ds_read_b128 v[174:177], v128 offset:17408
	ds_read_b128 v[178:181], v128 offset:18432
	ds_read_b128 v[182:185], v128 offset:19456
	ds_read_b128 v[186:189], v128 offset:20480
	ds_read_b128 v[190:193], v128 offset:21504
	ds_read_b128 v[194:197], v128 offset:22528
	ds_read_b128 v[198:201], v129 offset:23552
	s_barrier
	s_setprio 1
	s_waitcnt lgkmcnt(7)
	v_mfma_f32_16x16x32_bf16 v[60:63], v[170:173], v[154:157], v[60:63]
	v_mfma_f32_16x16x32_bf16 v[56:59], v[170:173], v[162:165], v[56:59]
	s_waitcnt lgkmcnt(5)
	v_mfma_f32_16x16x32_bf16 v[52:55], v[178:181], v[154:157], v[52:55]
	v_mfma_f32_16x16x32_bf16 v[48:51], v[178:181], v[162:165], v[48:51]
	s_waitcnt lgkmcnt(3)
	v_mfma_f32_16x16x32_bf16 v[44:47], v[186:189], v[154:157], v[44:47]
	v_mfma_f32_16x16x32_bf16 v[40:43], v[186:189], v[162:165], v[40:43]
	s_waitcnt lgkmcnt(1)
	v_mfma_f32_16x16x32_bf16 v[36:39], v[194:197], v[154:157], v[36:39]
	v_mfma_f32_16x16x32_bf16 v[32:35], v[194:197], v[162:165], v[32:35]
	v_mfma_f32_16x16x32_bf16 v[60:63], v[174:177], v[158:161], v[60:63]
	v_mfma_f32_16x16x32_bf16 v[56:59], v[174:177], v[166:169], v[56:59]
	v_mfma_f32_16x16x32_bf16 v[52:55], v[182:185], v[158:161], v[52:55]
	v_mfma_f32_16x16x32_bf16 v[48:51], v[182:185], v[166:169], v[48:51]
	v_mfma_f32_16x16x32_bf16 v[44:47], v[190:193], v[158:161], v[44:47]
	v_mfma_f32_16x16x32_bf16 v[40:43], v[190:193], v[166:169], v[40:43]
	s_waitcnt lgkmcnt(0)
	v_mfma_f32_16x16x32_bf16 v[36:39], v[198:201], v[158:161], v[36:39]
	v_mfma_f32_16x16x32_bf16 v[32:35], v[198:201], v[166:169], v[32:35]
	s_setprio 0
	s_barrier
; #define WAIT_V(n) asm volatile("s_waitcnt vmcnt(" #n ")" ::: "memory")
; #define WAIT_L(n) asm volatile("s_waitcnt lgkmcnt(" #n ")" ::: "memory")
; #define BAR __builtin_amdgcn_s_barrier()
; #define SCHED __builtin_amdgcn_sched_barrier(0)
;     ...
;     STAGE(SB(0, 1), Bt, bcol + HALF, t + 2);
;     WAIT_V(6); BAR; MMA(1, 1, At, B1); BAR;
;     LDB(B0, 1, 0); SCHED; LDA(At, 1, 0); STAGE(SA(0, 1), A, brow + HALF, t + 2);
;     WAIT_L(8); BAR; WAIT_L(0); MMA(0, 0, At, B0); BAR; SCHED;
;     LDB(B1, 1, 1); STAGE(SB(1, 0), Bt, bcol, t + 3);
;     BAR; WAIT_L(0); MMA(0, 1, At, B1); BAR;
;     LDA(At, 1, 1); STAGE(SA(1, 0), A, brow, t + 3);
	v_readfirstlane_b32 s31, v138
	s_add_i32 s30, s29, 0x80100
	s_mov_b32 m0, s31
	v_readfirstlane_b32 s31, v139
	buffer_load_dwordx4 v132, s[8:11], s30 offen lds
	s_mov_b32 m0, s31
	s_nop 0
	buffer_load_dwordx4 v131, s[8:11], s30 offen lds
	s_waitcnt vmcnt(6)
	s_barrier
	s_setprio 1
	v_mfma_f32_16x16x32_bf16 v[28:31], v[170:173], v[202:205], v[28:31]
	v_mfma_f32_16x16x32_bf16 v[24:27], v[170:173], v[212:215], v[24:27]
	v_mfma_f32_16x16x32_bf16 v[20:23], v[178:181], v[202:205], v[20:23]
	v_mfma_f32_16x16x32_bf16 v[16:19], v[178:181], v[212:215], v[16:19]
	v_mfma_f32_16x16x32_bf16 v[12:15], v[186:189], v[202:205], v[12:15]
	v_mfma_f32_16x16x32_bf16 v[8:11], v[186:189], v[212:215], v[8:11]
	v_mfma_f32_16x16x32_bf16 v[4:7], v[194:197], v[202:205], v[4:7]
	v_mfma_f32_16x16x32_bf16 v[0:3], v[194:197], v[212:215], v[0:3]
	v_mfma_f32_16x16x32_bf16 v[28:31], v[174:177], v[206:209], v[28:31]
	v_mfma_f32_16x16x32_bf16 v[24:27], v[174:177], v[216:219], v[24:27]
	v_mfma_f32_16x16x32_bf16 v[20:23], v[182:185], v[206:209], v[20:23]
	v_mfma_f32_16x16x32_bf16 v[16:19], v[182:185], v[216:219], v[16:19]
	v_mfma_f32_16x16x32_bf16 v[12:15], v[190:193], v[206:209], v[12:15]
	v_mfma_f32_16x16x32_bf16 v[8:11], v[190:193], v[216:219], v[8:11]
	v_mfma_f32_16x16x32_bf16 v[4:7], v[198:201], v[206:209], v[4:7]
	v_mfma_f32_16x16x32_bf16 v[0:3], v[198:201], v[216:219], v[0:3]
	s_setprio 0
	s_barrier
	ds_read_b128 v[154:157], v133
	ds_read_b128 v[158:161], v133 offset:1024
	ds_read_b128 v[162:165], v133 offset:2048
	ds_read_b128 v[166:169], v133 offset:3072
	v_readfirstlane_b32 s31, v140
	s_add_i32 s30, s28, 0x80100
	s_mov_b32 m0, s31
	v_readfirstlane_b32 s31, v141
	buffer_load_dwordx4 v132, s[88:91], s30 offen lds
	s_mov_b32 m0, s31
	s_nop 0
	buffer_load_dwordx4 v131, s[88:91], s30 offen lds
	ds_read_b128 v[170:173], v128 offset:32768
	ds_read_b128 v[174:177], v128 offset:33792
	ds_read_b128 v[178:181], v128 offset:34816
	ds_read_b128 v[182:185], v128 offset:35840
	ds_read_b128 v[186:189], v128 offset:36864
	ds_read_b128 v[190:193], v128 offset:37888
	ds_read_b128 v[194:197], v128 offset:38912
	ds_read_b128 v[198:201], v129 offset:39936
	s_waitcnt lgkmcnt(8)
	s_barrier
	s_setprio 1
	s_waitcnt lgkmcnt(7)
	v_mfma_f32_16x16x32_bf16 v[124:127], v[170:173], v[154:157], v[124:127]
	v_mfma_f32_16x16x32_bf16 v[120:123], v[170:173], v[162:165], v[120:123]
	s_waitcnt lgkmcnt(5)
	v_mfma_f32_16x16x32_bf16 v[116:119], v[178:181], v[154:157], v[116:119]
	v_mfma_f32_16x16x32_bf16 v[112:115], v[178:181], v[162:165], v[112:115]
	s_waitcnt lgkmcnt(3)
	v_mfma_f32_16x16x32_bf16 v[108:111], v[186:189], v[154:157], v[108:111]
	v_mfma_f32_16x16x32_bf16 v[104:107], v[186:189], v[162:165], v[104:107]
	s_waitcnt lgkmcnt(1)
	v_mfma_f32_16x16x32_bf16 v[100:103], v[194:197], v[154:157], v[100:103]
	v_mfma_f32_16x16x32_bf16 v[96:99], v[194:197], v[162:165], v[96:99]
	v_mfma_f32_16x16x32_bf16 v[124:127], v[174:177], v[158:161], v[124:127]
	v_mfma_f32_16x16x32_bf16 v[120:123], v[174:177], v[166:169], v[120:123]
	v_mfma_f32_16x16x32_bf16 v[116:119], v[182:185], v[158:161], v[116:119]
	v_mfma_f32_16x16x32_bf16 v[112:115], v[182:185], v[166:169], v[112:115]
	v_mfma_f32_16x16x32_bf16 v[108:111], v[190:193], v[158:161], v[108:111]
	v_mfma_f32_16x16x32_bf16 v[104:107], v[190:193], v[166:169], v[104:107]
	s_waitcnt lgkmcnt(0)
	v_mfma_f32_16x16x32_bf16 v[100:103], v[198:201], v[158:161], v[100:103]
	v_mfma_f32_16x16x32_bf16 v[96:99], v[198:201], v[166:169], v[96:99]
	s_setprio 0
	s_barrier
	v_readfirstlane_b32 s31, v142
	s_add_i32 s30, s29, 0x180
	s_mov_b32 m0, s31
	v_readfirstlane_b32 s31, v145
	buffer_load_dwordx4 v132, s[8:11], s30 offen lds
	s_mov_b32 m0, s31
	s_nop 0
	buffer_load_dwordx4 v131, s[8:11], s30 offen lds
	ds_read_b128 v[202:205], v130
	ds_read_b128 v[206:209], v130 offset:1024
	ds_read_b128 v[212:215], v130 offset:2048
	ds_read_b128 v[216:219], v130 offset:3072
	s_barrier
	s_setprio 1
	s_waitcnt lgkmcnt(3)
	v_mfma_f32_16x16x32_bf16 v[92:95], v[170:173], v[202:205], v[92:95]
	s_waitcnt lgkmcnt(1)
	v_mfma_f32_16x16x32_bf16 v[88:91], v[170:173], v[212:215], v[88:91]
	v_mfma_f32_16x16x32_bf16 v[84:87], v[178:181], v[202:205], v[84:87]
	v_mfma_f32_16x16x32_bf16 v[80:83], v[178:181], v[212:215], v[80:83]
	v_mfma_f32_16x16x32_bf16 v[76:79], v[186:189], v[202:205], v[76:79]
	v_mfma_f32_16x16x32_bf16 v[72:75], v[186:189], v[212:215], v[72:75]
	v_mfma_f32_16x16x32_bf16 v[68:71], v[194:197], v[202:205], v[68:71]
	v_mfma_f32_16x16x32_bf16 v[64:67], v[194:197], v[212:215], v[64:67]
	v_mfma_f32_16x16x32_bf16 v[92:95], v[174:177], v[206:209], v[92:95]
	s_waitcnt lgkmcnt(0)
	v_mfma_f32_16x16x32_bf16 v[88:91], v[174:177], v[216:219], v[88:91]
	v_mfma_f32_16x16x32_bf16 v[84:87], v[182:185], v[206:209], v[84:87]
	v_mfma_f32_16x16x32_bf16 v[80:83], v[182:185], v[216:219], v[80:83]
	v_mfma_f32_16x16x32_bf16 v[76:79], v[190:193], v[206:209], v[76:79]
	v_mfma_f32_16x16x32_bf16 v[72:75], v[190:193], v[216:219], v[72:75]
	v_mfma_f32_16x16x32_bf16 v[68:71], v[198:201], v[206:209], v[68:71]
	v_mfma_f32_16x16x32_bf16 v[64:67], v[198:201], v[216:219], v[64:67]
	s_setprio 0
	v_readfirstlane_b32 s30, v146
	s_addk_i32 s28, 0x180
	s_mov_b32 m0, s30
	v_readfirstlane_b32 s30, v147
	s_barrier
	buffer_load_dwordx4 v132, s[88:91], s28 offen lds
	s_mov_b32 m0, s30
	s_nop 0
	buffer_load_dwordx4 v131, s[88:91], s28 offen lds
	ds_read_b128 v[170:173], v128 offset:49152
	ds_read_b128 v[174:177], v128 offset:50176
	ds_read_b128 v[178:181], v128 offset:51200
	ds_read_b128 v[182:185], v128 offset:52224
	ds_read_b128 v[186:189], v128 offset:53248
	ds_read_b128 v[190:193], v128 offset:54272
	ds_read_b128 v[194:197], v128 offset:55296
	ds_read_b128 v[198:201], v129 offset:56320
	s_barrier
; #define WAIT_V(n) asm volatile("s_waitcnt vmcnt(" #n ")" ::: "memory")
; #define WAIT_L(n) asm volatile("s_waitcnt lgkmcnt(" #n ")" ::: "memory")
; #define BAR __builtin_amdgcn_s_barrier()
; #define SCHED __builtin_amdgcn_sched_barrier(0)
;     ...
;     LDA(At, 1, 1); STAGE(SA(1, 0), A, brow, t + 3);
;     BAR; WAIT_L(0); MMA(1, 0, At, B0); BAR; SCHED;
;     STAGE(SB(1, 1), Bt, bcol + HALF, t + 3);
;     WAIT_V(6); BAR; MMA(1, 1, At, B1); BAR;
;   }
;   { LDB(B0, 0, 0); LDA(At, 0, 0); STAGE(SA(1, 1), A, brow + HALF, nt - 1);
;     BAR; WAIT_L(0); MMA(0, 0, At, B0); BAR;
;     LDB(B1, 0, 1); BAR; WAIT_L(0); MMA(0, 1, At, B1); BAR;
;     LDA(At, 0, 1); WAIT_V(4); BAR; WAIT_L(0); MMA(1, 0, At, B0); MMA(1, 1, At, B1); BAR; }
	s_setprio 1
	s_waitcnt lgkmcnt(7)
	v_mfma_f32_16x16x32_bf16 v[60:63], v[170:173], v[154:157], v[60:63]
	v_mfma_f32_16x16x32_bf16 v[56:59], v[170:173], v[162:165], v[56:59]
	s_waitcnt lgkmcnt(5)
	v_mfma_f32_16x16x32_bf16 v[52:55], v[178:181], v[154:157], v[52:55]
	v_mfma_f32_16x16x32_bf16 v[48:51], v[178:181], v[162:165], v[48:51]
	s_waitcnt lgkmcnt(3)
	v_mfma_f32_16x16x32_bf16 v[44:47], v[186:189], v[154:157], v[44:47]
	v_mfma_f32_16x16x32_bf16 v[40:43], v[186:189], v[162:165], v[40:43]
	s_waitcnt lgkmcnt(1)
	v_mfma_f32_16x16x32_bf16 v[36:39], v[194:197], v[154:157], v[36:39]
	v_mfma_f32_16x16x32_bf16 v[32:35], v[194:197], v[162:165], v[32:35]
	v_mfma_f32_16x16x32_bf16 v[60:63], v[174:177], v[158:161], v[60:63]
	v_mfma_f32_16x16x32_bf16 v[56:59], v[174:177], v[166:169], v[56:59]
	v_mfma_f32_16x16x32_bf16 v[52:55], v[182:185], v[158:161], v[52:55]
	v_mfma_f32_16x16x32_bf16 v[48:51], v[182:185], v[166:169], v[48:51]
	v_mfma_f32_16x16x32_bf16 v[44:47], v[190:193], v[158:161], v[44:47]
	v_mfma_f32_16x16x32_bf16 v[40:43], v[190:193], v[166:169], v[40:43]
	s_waitcnt lgkmcnt(0)
	v_mfma_f32_16x16x32_bf16 v[36:39], v[198:201], v[158:161], v[36:39]
	v_mfma_f32_16x16x32_bf16 v[32:35], v[198:201], v[166:169], v[32:35]
	s_setprio 0
	s_barrier
	v_readfirstlane_b32 s28, v148
	s_add_i32 s29, s29, 0x80180
	s_mov_b32 m0, s28
	v_readfirstlane_b32 s28, v151
	buffer_load_dwordx4 v132, s[8:11], s29 offen lds
	s_mov_b32 m0, s28
	s_nop 0
	buffer_load_dwordx4 v131, s[8:11], s29 offen lds
	s_waitcnt vmcnt(6)
	s_barrier
	s_setprio 1
	v_mfma_f32_16x16x32_bf16 v[28:31], v[170:173], v[202:205], v[28:31]
	v_mfma_f32_16x16x32_bf16 v[24:27], v[170:173], v[212:215], v[24:27]
	v_mfma_f32_16x16x32_bf16 v[20:23], v[178:181], v[202:205], v[20:23]
	v_mfma_f32_16x16x32_bf16 v[16:19], v[178:181], v[212:215], v[16:19]
	v_mfma_f32_16x16x32_bf16 v[12:15], v[186:189], v[202:205], v[12:15]
	v_mfma_f32_16x16x32_bf16 v[8:11], v[186:189], v[212:215], v[8:11]
	v_mfma_f32_16x16x32_bf16 v[4:7], v[194:197], v[202:205], v[4:7]
	v_mfma_f32_16x16x32_bf16 v[0:3], v[194:197], v[212:215], v[0:3]
	v_mfma_f32_16x16x32_bf16 v[28:31], v[174:177], v[206:209], v[28:31]
	v_mfma_f32_16x16x32_bf16 v[24:27], v[174:177], v[216:219], v[24:27]
	v_mfma_f32_16x16x32_bf16 v[20:23], v[182:185], v[206:209], v[20:23]
	v_mfma_f32_16x16x32_bf16 v[16:19], v[182:185], v[216:219], v[16:19]
	v_mfma_f32_16x16x32_bf16 v[12:15], v[190:193], v[206:209], v[12:15]
	v_mfma_f32_16x16x32_bf16 v[8:11], v[190:193], v[216:219], v[8:11]
	v_mfma_f32_16x16x32_bf16 v[4:7], v[198:201], v[206:209], v[4:7]
	v_mfma_f32_16x16x32_bf16 v[0:3], v[198:201], v[216:219], v[0:3]
	s_setprio 0
	s_add_i32 s26, s26, 2
	s_addk_i32 s27, 0x100
	s_cmp_lt_u32 s26, 28
	s_barrier
	s_cbranch_scc1 .LBB0_420
	v_readfirstlane_b32 s5, v150
	s_or_b32 s4, s25, 0xf80
	s_mov_b32 m0, s5
	v_readfirstlane_b32 s5, v149
	buffer_load_dwordx4 v132, s[88:91], s4 offen lds
	s_mov_b32 m0, s5
	s_nop 0
	buffer_load_dwordx4 v131, s[88:91], s4 offen lds
	ds_read_b128 v[134:137], v152
	ds_read_b128 v[138:141], v152 offset:1024
	ds_read_b128 v[146:149], v152 offset:2048
	ds_read_b128 v[150:153], v152 offset:3072
	ds_read_b128 v[154:157], v128
	ds_read_b128 v[158:161], v128 offset:1024
	ds_read_b128 v[162:165], v128 offset:2048
	ds_read_b128 v[166:169], v128 offset:3072
	ds_read_b128 v[170:173], v128 offset:4096
	ds_read_b128 v[174:177], v128 offset:5120
	ds_read_b128 v[178:181], v128 offset:6144
	ds_read_b128 v[182:185], v129 offset:7168
	s_barrier
	s_setprio 1
	s_waitcnt lgkmcnt(7)
	v_mfma_f32_16x16x32_bf16 v[124:127], v[154:157], v[134:137], v[124:127]
	v_mfma_f32_16x16x32_bf16 v[120:123], v[154:157], v[146:149], v[120:123]
	s_waitcnt lgkmcnt(5)
	v_mfma_f32_16x16x32_bf16 v[116:119], v[162:165], v[134:137], v[116:119]
	v_mfma_f32_16x16x32_bf16 v[112:115], v[162:165], v[146:149], v[112:115]
	v_mfma_f32_16x16x32_bf16 v[124:127], v[158:161], v[138:141], v[124:127]
	v_mfma_f32_16x16x32_bf16 v[120:123], v[158:161], v[150:153], v[120:123]
	s_waitcnt lgkmcnt(4)
	v_mfma_f32_16x16x32_bf16 v[116:119], v[166:169], v[138:141], v[116:119]
	v_mfma_f32_16x16x32_bf16 v[112:115], v[166:169], v[150:153], v[112:115]
	s_waitcnt lgkmcnt(3)
	v_mfma_f32_16x16x32_bf16 v[108:111], v[170:173], v[134:137], v[108:111]
	v_mfma_f32_16x16x32_bf16 v[104:107], v[170:173], v[146:149], v[104:107]
	s_waitcnt lgkmcnt(1)
	v_mfma_f32_16x16x32_bf16 v[100:103], v[178:181], v[134:137], v[100:103]
	v_mfma_f32_16x16x32_bf16 v[96:99], v[178:181], v[146:149], v[96:99]
	v_mfma_f32_16x16x32_bf16 v[186:189], v[174:177], v[138:141], v[108:111]
	v_mfma_f32_16x16x32_bf16 v[190:193], v[174:177], v[150:153], v[104:107]
	s_waitcnt lgkmcnt(0)
	v_mfma_f32_16x16x32_bf16 v[194:197], v[182:185], v[138:141], v[100:103]
	v_mfma_f32_16x16x32_bf16 v[198:201], v[182:185], v[150:153], v[96:99]
	s_setprio 0
	s_barrier
	s_nop 0
	ds_read_b128 v[96:99], v143
	ds_read_b128 v[100:103], v143 offset:1024
	ds_read_b128 v[104:107], v143 offset:2048
	ds_read_b128 v[108:111], v143 offset:3072
	s_barrier
	s_setprio 1
	s_waitcnt lgkmcnt(3)
	v_mfma_f32_16x16x32_bf16 v[92:95], v[154:157], v[96:99], v[92:95]
	s_waitcnt lgkmcnt(1)
	v_mfma_f32_16x16x32_bf16 v[88:91], v[154:157], v[104:107], v[88:91]
	v_mfma_f32_16x16x32_bf16 v[84:87], v[162:165], v[96:99], v[84:87]
	v_mfma_f32_16x16x32_bf16 v[76:79], v[170:173], v[96:99], v[76:79]
	v_mfma_f32_16x16x32_bf16 v[92:95], v[158:161], v[100:103], v[92:95]
	s_waitcnt lgkmcnt(0)
	v_mfma_f32_16x16x32_bf16 v[88:91], v[158:161], v[108:111], v[88:91]
	v_mfma_f32_16x16x32_bf16 v[84:87], v[166:169], v[100:103], v[84:87]
	v_mfma_f32_16x16x32_bf16 v[80:83], v[162:165], v[104:107], v[80:83]
	v_mfma_f32_16x16x32_bf16 v[76:79], v[174:177], v[100:103], v[76:79]
	v_mfma_f32_16x16x32_bf16 v[72:75], v[170:173], v[104:107], v[72:75]
	v_mfma_f32_16x16x32_bf16 v[68:71], v[178:181], v[96:99], v[68:71]
	v_mfma_f32_16x16x32_bf16 v[64:67], v[178:181], v[104:107], v[64:67]
	v_mfma_f32_16x16x32_bf16 v[154:157], v[166:169], v[108:111], v[80:83]
	v_mfma_f32_16x16x32_bf16 v[158:161], v[174:177], v[108:111], v[72:75]
	v_mfma_f32_16x16x32_bf16 v[162:165], v[182:185], v[100:103], v[68:71]
	v_mfma_f32_16x16x32_bf16 v[166:169], v[182:185], v[108:111], v[64:67]
	s_setprio 0
	s_barrier
; #define WAIT_V(n) asm volatile("s_waitcnt vmcnt(" #n ")" ::: "memory")
; #define WAIT_L(n) asm volatile("s_waitcnt lgkmcnt(" #n ")" ::: "memory")
; #define BAR __builtin_amdgcn_s_barrier()
;     ...
;     LDA(At, 0, 1); WAIT_V(4); BAR; WAIT_L(0); MMA(1, 0, At, B0); MMA(1, 1, At, B1); BAR; }
;   { LDB(B0, 1, 0); LDA(At, 1, 0); WAIT_V(2); BAR;
;     if (has_next) {
;       STAGE(SB(0, 0), Bt, nbcol, 0); STAGE(SA(0, 0), A, nbrow, 0);
;       STAGE(SB(0, 1), Bt, nbcol + HALF, 0); STAGE(SA(0, 1), A, nbrow + HALF, 0);
;     }
;     WAIT_L(0); MMA(0, 0, At, B0); BAR;
	s_nop 1
	ds_read_b128 v[64:67], v128 offset:16384
	ds_read_b128 v[68:71], v128 offset:17408
	ds_read_b128 v[72:75], v128 offset:18432
	ds_read_b128 v[80:83], v128 offset:19456
	ds_read_b128 v[170:173], v128 offset:20480
	ds_read_b128 v[174:177], v128 offset:21504
	ds_read_b128 v[178:181], v128 offset:22528
	ds_read_b128 v[182:185], v129 offset:23552
	s_waitcnt vmcnt(4)
	s_barrier
	s_setprio 1
	s_waitcnt lgkmcnt(7)
	v_mfma_f32_16x16x32_bf16 v[60:63], v[64:67], v[134:137], v[60:63]
	v_mfma_f32_16x16x32_bf16 v[56:59], v[64:67], v[146:149], v[56:59]
	s_waitcnt lgkmcnt(5)
	v_mfma_f32_16x16x32_bf16 v[52:55], v[72:75], v[134:137], v[52:55]
	s_waitcnt lgkmcnt(3)
	v_mfma_f32_16x16x32_bf16 v[44:47], v[170:173], v[134:137], v[44:47]
	v_mfma_f32_16x16x32_bf16 v[60:63], v[68:71], v[138:141], v[60:63]
	v_mfma_f32_16x16x32_bf16 v[56:59], v[68:71], v[150:153], v[56:59]
	v_mfma_f32_16x16x32_bf16 v[52:55], v[80:83], v[138:141], v[52:55]
	v_mfma_f32_16x16x32_bf16 v[48:51], v[72:75], v[146:149], v[48:51]
	s_waitcnt lgkmcnt(2)
	v_mfma_f32_16x16x32_bf16 v[44:47], v[174:177], v[138:141], v[44:47]
	v_mfma_f32_16x16x32_bf16 v[40:43], v[170:173], v[146:149], v[40:43]
	s_waitcnt lgkmcnt(1)
	v_mfma_f32_16x16x32_bf16 v[36:39], v[178:181], v[134:137], v[36:39]
	v_mfma_f32_16x16x32_bf16 v[32:35], v[178:181], v[146:149], v[32:35]
	v_mfma_f32_16x16x32_bf16 v[202:205], v[80:83], v[150:153], v[48:51]
	v_mfma_f32_16x16x32_bf16 v[206:209], v[174:177], v[150:153], v[40:43]
	s_waitcnt lgkmcnt(0)
	v_mfma_f32_16x16x32_bf16 v[134:137], v[182:185], v[138:141], v[36:39]
	v_mfma_f32_16x16x32_bf16 v[138:141], v[182:185], v[150:153], v[32:35]
	s_setprio 0
	s_setprio 1
	v_mfma_f32_16x16x32_bf16 v[28:31], v[64:67], v[96:99], v[28:31]
	v_mfma_f32_16x16x32_bf16 v[24:27], v[64:67], v[104:107], v[24:27]
	v_mfma_f32_16x16x32_bf16 v[20:23], v[72:75], v[96:99], v[20:23]
	v_mfma_f32_16x16x32_bf16 v[12:15], v[170:173], v[96:99], v[12:15]
	v_mfma_f32_16x16x32_bf16 v[28:31], v[68:71], v[100:103], v[28:31]
	v_mfma_f32_16x16x32_bf16 v[24:27], v[68:71], v[108:111], v[24:27]
	v_mfma_f32_16x16x32_bf16 v[20:23], v[80:83], v[100:103], v[20:23]
	v_mfma_f32_16x16x32_bf16 v[16:19], v[72:75], v[104:107], v[16:19]
	v_mfma_f32_16x16x32_bf16 v[12:15], v[174:177], v[100:103], v[12:15]
	v_mfma_f32_16x16x32_bf16 v[8:11], v[170:173], v[104:107], v[8:11]
	v_mfma_f32_16x16x32_bf16 v[4:7], v[178:181], v[96:99], v[4:7]
	v_mfma_f32_16x16x32_bf16 v[0:3], v[178:181], v[104:107], v[0:3]
	v_mfma_f32_16x16x32_bf16 v[146:149], v[80:83], v[108:111], v[16:19]
	v_mfma_f32_16x16x32_bf16 v[150:153], v[174:177], v[108:111], v[8:11]
	v_mfma_f32_16x16x32_bf16 v[170:173], v[182:185], v[100:103], v[4:7]
	v_mfma_f32_16x16x32_bf16 v[174:177], v[182:185], v[108:111], v[0:3]
	s_setprio 0
	s_barrier
	s_nop 1
	ds_read_b128 v[0:3], v133
	ds_read_b128 v[4:7], v133 offset:1024
	ds_read_b128 v[8:11], v133 offset:2048
	ds_read_b128 v[16:19], v133 offset:3072
	ds_read_b128 v[32:35], v128 offset:32768
	ds_read_b128 v[36:39], v128 offset:33792
	ds_read_b128 v[40:43], v128 offset:34816
	ds_read_b128 v[48:51], v128 offset:35840
	ds_read_b128 v[178:181], v128 offset:36864
	ds_read_b128 v[182:185], v128 offset:37888
	ds_read_b128 v[212:215], v128 offset:38912
	ds_read_b128 v[216:219], v129 offset:39936
	s_waitcnt vmcnt(2)
	s_barrier
	s_setprio 1
	s_waitcnt lgkmcnt(7)
	v_mfma_f32_16x16x32_bf16 v[64:67], v[32:35], v[0:3], v[124:127]
	s_waitcnt lgkmcnt(6)
	v_mfma_f32_16x16x32_bf16 v[96:99], v[36:39], v[4:7], v[64:67]
	v_mfma_f32_16x16x32_bf16 v[64:67], v[32:35], v[8:11], v[120:123]
	v_mfma_f32_16x16x32_bf16 v[100:103], v[36:39], v[16:19], v[64:67]
	s_waitcnt lgkmcnt(5)
	v_mfma_f32_16x16x32_bf16 v[64:67], v[40:43], v[0:3], v[116:119]
	s_waitcnt lgkmcnt(4)
	v_mfma_f32_16x16x32_bf16 v[104:107], v[48:51], v[4:7], v[64:67]
	v_mfma_f32_16x16x32_bf16 v[64:67], v[40:43], v[8:11], v[112:115]
	v_mfma_f32_16x16x32_bf16 v[108:111], v[48:51], v[16:19], v[64:67]
	s_waitcnt lgkmcnt(3)
	v_mfma_f32_16x16x32_bf16 v[64:67], v[178:181], v[0:3], v[186:189]
	s_waitcnt lgkmcnt(2)
	v_mfma_f32_16x16x32_bf16 v[112:115], v[182:185], v[4:7], v[64:67]
	v_mfma_f32_16x16x32_bf16 v[64:67], v[178:181], v[8:11], v[190:193]
	v_mfma_f32_16x16x32_bf16 v[116:119], v[182:185], v[16:19], v[64:67]
	s_waitcnt lgkmcnt(1)
	v_mfma_f32_16x16x32_bf16 v[64:67], v[212:215], v[0:3], v[194:197]
	s_waitcnt lgkmcnt(0)
	v_mfma_f32_16x16x32_bf16 v[120:123], v[216:219], v[4:7], v[64:67]
	v_mfma_f32_16x16x32_bf16 v[64:67], v[212:215], v[8:11], v[198:201]
	v_mfma_f32_16x16x32_bf16 v[124:127], v[216:219], v[16:19], v[64:67]
	s_setprio 0
	s_barrier
; #define WAIT_V(n) asm volatile("s_waitcnt vmcnt(" #n ")" ::: "memory")
; #define WAIT_L(n) asm volatile("s_waitcnt lgkmcnt(" #n ")" ::: "memory")
; #define BAR __builtin_amdgcn_s_barrier()
;     ...
;     LDB(B1, 1, 1); if (has_next) { WAIT_V(8); } else { WAIT_V(0); } BAR; WAIT_L(0); MMA(0, 1, At, B1); BAR;
;     LDA(At, 1, 1); BAR; WAIT_L(0); MMA(1, 0, At, B0); MMA(1, 1, At, B1); BAR; }
;   if (wr == 0) BAR;
	ds_read_b128 v[186:189], v130
	ds_read_b128 v[190:193], v130 offset:1024
	ds_read_b128 v[194:197], v130 offset:2048
	ds_read_b128 v[130:133], v130 offset:3072
	s_waitcnt vmcnt(0)
	s_barrier
	s_setprio 1
	s_waitcnt lgkmcnt(3)
	v_mfma_f32_16x16x32_bf16 v[64:67], v[32:35], v[186:189], v[92:95]
	s_waitcnt lgkmcnt(1)
	v_mfma_f32_16x16x32_bf16 v[32:35], v[32:35], v[194:197], v[88:91]
	s_waitcnt lgkmcnt(0)
	v_mfma_f32_16x16x32_bf16 v[72:75], v[36:39], v[130:133], v[32:35]
	v_mfma_f32_16x16x32_bf16 v[32:35], v[40:43], v[186:189], v[84:87]
	v_mfma_f32_16x16x32_bf16 v[80:83], v[48:51], v[190:193], v[32:35]
	v_mfma_f32_16x16x32_bf16 v[32:35], v[40:43], v[194:197], v[154:157]
	v_mfma_f32_16x16x32_bf16 v[88:91], v[48:51], v[130:133], v[32:35]
	v_mfma_f32_16x16x32_bf16 v[32:35], v[178:181], v[186:189], v[76:79]
	v_mfma_f32_16x16x32_bf16 v[68:71], v[36:39], v[190:193], v[64:67]
	v_mfma_f32_16x16x32_bf16 v[64:67], v[182:185], v[190:193], v[32:35]
	v_mfma_f32_16x16x32_bf16 v[32:35], v[178:181], v[194:197], v[158:161]
	v_mfma_f32_16x16x32_bf16 v[76:79], v[182:185], v[130:133], v[32:35]
	v_mfma_f32_16x16x32_bf16 v[32:35], v[212:215], v[186:189], v[162:165]
	v_mfma_f32_16x16x32_bf16 v[84:87], v[216:219], v[190:193], v[32:35]
	v_mfma_f32_16x16x32_bf16 v[32:35], v[212:215], v[194:197], v[166:169]
	v_mfma_f32_16x16x32_bf16 v[92:95], v[216:219], v[130:133], v[32:35]
	s_setprio 0
	s_barrier
	ds_read_b128 v[154:157], v128 offset:49152
	ds_read_b128 v[158:161], v128 offset:50176
	ds_read_b128 v[162:165], v128 offset:51200
	ds_read_b128 v[166:169], v128 offset:52224
	ds_read_b128 v[178:181], v128 offset:53248
	ds_read_b128 v[182:185], v128 offset:54272
	ds_read_b128 v[198:201], v128 offset:55296
	ds_read_b128 v[212:215], v129 offset:56320
	s_barrier
	s_setprio 1
	s_waitcnt lgkmcnt(7)
	v_mfma_f32_16x16x32_bf16 v[32:35], v[154:157], v[0:3], v[60:63]
	s_waitcnt lgkmcnt(6)
	v_mfma_f32_16x16x32_bf16 v[36:39], v[158:161], v[4:7], v[32:35]
	v_mfma_f32_16x16x32_bf16 v[32:35], v[154:157], v[8:11], v[56:59]
	v_mfma_f32_16x16x32_bf16 v[40:43], v[158:161], v[16:19], v[32:35]
	s_waitcnt lgkmcnt(5)
	v_mfma_f32_16x16x32_bf16 v[32:35], v[162:165], v[0:3], v[52:55]
	s_waitcnt lgkmcnt(4)
	v_mfma_f32_16x16x32_bf16 v[48:51], v[166:169], v[4:7], v[32:35]
	v_mfma_f32_16x16x32_bf16 v[32:35], v[162:165], v[8:11], v[202:205]
	v_mfma_f32_16x16x32_bf16 v[56:59], v[166:169], v[16:19], v[32:35]
	s_waitcnt lgkmcnt(3)
	v_mfma_f32_16x16x32_bf16 v[32:35], v[178:181], v[0:3], v[44:47]
	s_waitcnt lgkmcnt(1)
	v_mfma_f32_16x16x32_bf16 v[0:3], v[198:201], v[0:3], v[134:137]
	v_mfma_f32_16x16x32_bf16 v[44:47], v[178:181], v[8:11], v[206:209]
	s_waitcnt lgkmcnt(0)
	v_mfma_f32_16x16x32_bf16 v[52:55], v[212:215], v[4:7], v[0:3]
	v_mfma_f32_16x16x32_bf16 v[0:3], v[198:201], v[8:11], v[138:141]
	v_mfma_f32_16x16x32_bf16 v[32:35], v[182:185], v[4:7], v[32:35]
	v_mfma_f32_16x16x32_bf16 v[44:47], v[182:185], v[16:19], v[44:47]
	v_mfma_f32_16x16x32_bf16 v[60:63], v[212:215], v[16:19], v[0:3]
	s_setprio 0
	s_setprio 1
	v_mfma_f32_16x16x32_bf16 v[0:3], v[154:157], v[186:189], v[28:31]
	v_mfma_f32_16x16x32_bf16 v[4:7], v[158:161], v[190:193], v[0:3]
	v_mfma_f32_16x16x32_bf16 v[0:3], v[154:157], v[194:197], v[24:27]
	v_mfma_f32_16x16x32_bf16 v[8:11], v[158:161], v[130:133], v[0:3]
	v_mfma_f32_16x16x32_bf16 v[0:3], v[162:165], v[186:189], v[20:23]
	v_mfma_f32_16x16x32_bf16 v[16:19], v[166:169], v[190:193], v[0:3]
	v_mfma_f32_16x16x32_bf16 v[0:3], v[162:165], v[194:197], v[146:149]
	v_mfma_f32_16x16x32_bf16 v[24:27], v[166:169], v[130:133], v[0:3]
	v_mfma_f32_16x16x32_bf16 v[0:3], v[178:181], v[186:189], v[12:15]
	v_mfma_f32_16x16x32_bf16 v[12:15], v[178:181], v[194:197], v[150:153]
	v_mfma_f32_16x16x32_bf16 v[20:23], v[198:201], v[186:189], v[170:173]
	v_mfma_f32_16x16x32_bf16 v[28:31], v[198:201], v[194:197], v[174:177]
	v_mfma_f32_16x16x32_bf16 v[0:3], v[182:185], v[190:193], v[0:3]
	v_mfma_f32_16x16x32_bf16 v[12:15], v[182:185], v[130:133], v[12:15]
	v_mfma_f32_16x16x32_bf16 v[20:23], v[212:215], v[190:193], v[20:23]
	v_mfma_f32_16x16x32_bf16 v[28:31], v[212:215], v[130:133], v[28:31]
	s_setprio 0
	s_barrier
	s_and_saveexec_b64 s[4:5], vcc
	s_cbranch_execz .LBB0_411
	s_barrier
	s_branch .LBB0_411

; #define WAIT_L(n) asm volatile("s_waitcnt lgkmcnt(" #n ")" ::: "memory")
; #define BAR __builtin_amdgcn_s_barrier()
; #define SCHED __builtin_amdgcn_sched_barrier(0)
;     ...
;   for (int t = 0; t < nt - 2; t += 2) {
;     LDB(B0, 0, 0); SCHED; LDA(At, 0, 0); STAGE(SA(1, 1), A, brow + HALF, t + 1);
;     WAIT_L(8); BAR; WAIT_L(0); MMA(0, 0, At, B0); BAR; SCHED;
;     LDB(B1, 0, 1); STAGE(SB(0, 0), Bt, bcol, t + 2);
;     BAR; WAIT_L(0); MMA(0, 1, At, B1); BAR;
;     LDA(At, 0, 1); STAGE(SA(0, 0), A, brow, t + 2);
;     BAR; WAIT_L(0); MMA(1, 0, At, B0); BAR; SCHED;
.LBB0_441:
	ds_read_b128 v[152:155], v151
	ds_read_b128 v[156:159], v151 offset:1024
	ds_read_b128 v[160:163], v151 offset:2048
	ds_read_b128 v[164:167], v151 offset:3072
	s_add_i32 s42, s31, s5
	v_readfirstlane_b32 s44, v148
	s_add_i32 s43, s42, 0x40080
	s_mov_b32 m0, s44
	v_readfirstlane_b32 s44, v147
	buffer_load_dwordx4 v131, s[8:11], s43 offen lds
	s_mov_b32 m0, s44
	s_nop 0
	buffer_load_dwordx4 v133, s[8:11], s43 offen lds
	ds_read_b128 v[168:171], v128
	ds_read_b128 v[172:175], v128 offset:1024
	ds_read_b128 v[176:179], v128 offset:2048
	ds_read_b128 v[180:183], v128 offset:3072
	ds_read_b128 v[184:187], v128 offset:4096
	ds_read_b128 v[188:191], v128 offset:5120
	ds_read_b128 v[192:195], v128 offset:6144
	ds_read_b128 v[196:199], v129 offset:7168
	s_waitcnt lgkmcnt(8)
	s_barrier
	s_setprio 1
	s_waitcnt lgkmcnt(7)
	v_mfma_f32_16x16x32_bf16 v[124:127], v[168:171], v[152:155], v[124:127]
	v_mfma_f32_16x16x32_bf16 v[120:123], v[168:171], v[160:163], v[120:123]
	s_waitcnt lgkmcnt(5)
	v_mfma_f32_16x16x32_bf16 v[116:119], v[176:179], v[152:155], v[116:119]
	v_mfma_f32_16x16x32_bf16 v[112:115], v[176:179], v[160:163], v[112:115]
	s_waitcnt lgkmcnt(3)
	v_mfma_f32_16x16x32_bf16 v[108:111], v[184:187], v[152:155], v[108:111]
	v_mfma_f32_16x16x32_bf16 v[104:107], v[184:187], v[160:163], v[104:107]
	s_waitcnt lgkmcnt(1)
	v_mfma_f32_16x16x32_bf16 v[100:103], v[192:195], v[152:155], v[100:103]
	v_mfma_f32_16x16x32_bf16 v[96:99], v[192:195], v[160:163], v[96:99]
	v_mfma_f32_16x16x32_bf16 v[124:127], v[172:175], v[156:159], v[124:127]
	v_mfma_f32_16x16x32_bf16 v[120:123], v[172:175], v[164:167], v[120:123]
	v_mfma_f32_16x16x32_bf16 v[116:119], v[180:183], v[156:159], v[116:119]
	v_mfma_f32_16x16x32_bf16 v[112:115], v[180:183], v[164:167], v[112:115]
	v_mfma_f32_16x16x32_bf16 v[108:111], v[188:191], v[156:159], v[108:111]
	v_mfma_f32_16x16x32_bf16 v[104:107], v[188:191], v[164:167], v[104:107]
	s_waitcnt lgkmcnt(0)
	v_mfma_f32_16x16x32_bf16 v[100:103], v[196:199], v[156:159], v[100:103]
	v_mfma_f32_16x16x32_bf16 v[96:99], v[196:199], v[164:167], v[96:99]
	s_setprio 0
	s_barrier
	s_add_i32 s43, s30, s5
	v_readfirstlane_b32 s45, v134
	s_add_i32 s44, s43, 0x100
	s_mov_b32 m0, s45
	v_readfirstlane_b32 s45, v135
	buffer_load_dwordx4 v131, s[88:91], s44 offen lds
	s_mov_b32 m0, s45
	s_nop 0
	buffer_load_dwordx4 v133, s[88:91], s44 offen lds
	ds_read_b128 v[200:203], v142
	ds_read_b128 v[204:207], v142 offset:1024
	ds_read_b128 v[212:215], v142 offset:2048
	ds_read_b128 v[216:219], v142 offset:3072
	s_barrier
	s_setprio 1
	s_waitcnt lgkmcnt(3)
	v_mfma_f32_16x16x32_bf16 v[92:95], v[168:171], v[200:203], v[92:95]
	s_waitcnt lgkmcnt(1)
	v_mfma_f32_16x16x32_bf16 v[88:91], v[168:171], v[212:215], v[88:91]
	v_mfma_f32_16x16x32_bf16 v[84:87], v[176:179], v[200:203], v[84:87]
	v_mfma_f32_16x16x32_bf16 v[80:83], v[176:179], v[212:215], v[80:83]
	v_mfma_f32_16x16x32_bf16 v[76:79], v[184:187], v[200:203], v[76:79]
	v_mfma_f32_16x16x32_bf16 v[72:75], v[184:187], v[212:215], v[72:75]
	v_mfma_f32_16x16x32_bf16 v[68:71], v[192:195], v[200:203], v[68:71]
	v_mfma_f32_16x16x32_bf16 v[64:67], v[192:195], v[212:215], v[64:67]
	v_mfma_f32_16x16x32_bf16 v[92:95], v[172:175], v[204:207], v[92:95]
	s_waitcnt lgkmcnt(0)
	v_mfma_f32_16x16x32_bf16 v[88:91], v[172:175], v[216:219], v[88:91]
	v_mfma_f32_16x16x32_bf16 v[84:87], v[180:183], v[204:207], v[84:87]
	v_mfma_f32_16x16x32_bf16 v[80:83], v[180:183], v[216:219], v[80:83]
	v_mfma_f32_16x16x32_bf16 v[76:79], v[188:191], v[204:207], v[76:79]
	v_mfma_f32_16x16x32_bf16 v[72:75], v[188:191], v[216:219], v[72:75]
	v_mfma_f32_16x16x32_bf16 v[68:71], v[196:199], v[204:207], v[68:71]
	v_mfma_f32_16x16x32_bf16 v[64:67], v[196:199], v[216:219], v[64:67]
	s_setprio 0
	v_readfirstlane_b32 s45, v136
	s_add_i32 s44, s42, 0x100
	s_mov_b32 m0, s45
	v_readfirstlane_b32 s45, v137
	s_barrier
	buffer_load_dwordx4 v131, s[8:11], s44 offen lds
	s_mov_b32 m0, s45
	s_nop 0
	buffer_load_dwordx4 v133, s[8:11], s44 offen lds
	ds_read_b128 v[168:171], v128 offset:16384
	ds_read_b128 v[172:175], v128 offset:17408
	ds_read_b128 v[176:179], v128 offset:18432
	ds_read_b128 v[180:183], v128 offset:19456
	ds_read_b128 v[184:187], v128 offset:20480
	ds_read_b128 v[188:191], v128 offset:21504
	ds_read_b128 v[192:195], v128 offset:22528
	ds_read_b128 v[196:199], v129 offset:23552
	s_barrier
	s_setprio 1
	s_waitcnt lgkmcnt(7)
	v_mfma_f32_16x16x32_bf16 v[60:63], v[168:171], v[152:155], v[60:63]
	v_mfma_f32_16x16x32_bf16 v[56:59], v[168:171], v[160:163], v[56:59]
	s_waitcnt lgkmcnt(5)
	v_mfma_f32_16x16x32_bf16 v[52:55], v[176:179], v[152:155], v[52:55]
	v_mfma_f32_16x16x32_bf16 v[48:51], v[176:179], v[160:163], v[48:51]
	s_waitcnt lgkmcnt(3)
	v_mfma_f32_16x16x32_bf16 v[44:47], v[184:187], v[152:155], v[44:47]
	v_mfma_f32_16x16x32_bf16 v[40:43], v[184:187], v[160:163], v[40:43]
	s_waitcnt lgkmcnt(1)
	v_mfma_f32_16x16x32_bf16 v[36:39], v[192:195], v[152:155], v[36:39]
	v_mfma_f32_16x16x32_bf16 v[32:35], v[192:195], v[160:163], v[32:35]
	v_mfma_f32_16x16x32_bf16 v[60:63], v[172:175], v[156:159], v[60:63]
	v_mfma_f32_16x16x32_bf16 v[56:59], v[172:175], v[164:167], v[56:59]
	v_mfma_f32_16x16x32_bf16 v[52:55], v[180:183], v[156:159], v[52:55]
	v_mfma_f32_16x16x32_bf16 v[48:51], v[180:183], v[164:167], v[48:51]
	v_mfma_f32_16x16x32_bf16 v[44:47], v[188:191], v[156:159], v[44:47]
	v_mfma_f32_16x16x32_bf16 v[40:43], v[188:191], v[164:167], v[40:43]
	s_waitcnt lgkmcnt(0)
	v_mfma_f32_16x16x32_bf16 v[36:39], v[196:199], v[156:159], v[36:39]
	v_mfma_f32_16x16x32_bf16 v[32:35], v[196:199], v[164:167], v[32:35]
	s_setprio 0
	s_barrier
; #define WAIT_V(n) asm volatile("s_waitcnt vmcnt(" #n ")" ::: "memory")
; #define WAIT_L(n) asm volatile("s_waitcnt lgkmcnt(" #n ")" ::: "memory")
; #define BAR __builtin_amdgcn_s_barrier()
; #define SCHED __builtin_amdgcn_sched_barrier(0)
;     ...
;     STAGE(SB(0, 1), Bt, bcol + HALF, t + 2);
;     WAIT_V(6); BAR; MMA(1, 1, At, B1); BAR;
;     LDB(B0, 1, 0); SCHED; LDA(At, 1, 0); STAGE(SA(0, 1), A, brow + HALF, t + 2);
;     WAIT_L(8); BAR; WAIT_L(0); MMA(0, 0, At, B0); BAR; SCHED;
;     LDB(B1, 1, 1); STAGE(SB(1, 0), Bt, bcol, t + 3);
;     BAR; WAIT_L(0); MMA(0, 1, At, B1); BAR;
;     LDA(At, 1, 1); STAGE(SA(1, 0), A, brow, t + 3);
	v_readfirstlane_b32 s45, v138
	s_add_i32 s44, s43, 0x40100
	s_mov_b32 m0, s45
	v_readfirstlane_b32 s45, v139
	buffer_load_dwordx4 v131, s[88:91], s44 offen lds
	s_mov_b32 m0, s45
	s_nop 0
	buffer_load_dwordx4 v133, s[88:91], s44 offen lds
	s_waitcnt vmcnt(6)
	s_barrier
	s_setprio 1
	v_mfma_f32_16x16x32_bf16 v[28:31], v[168:171], v[200:203], v[28:31]
	v_mfma_f32_16x16x32_bf16 v[24:27], v[168:171], v[212:215], v[24:27]
	v_mfma_f32_16x16x32_bf16 v[20:23], v[176:179], v[200:203], v[20:23]
	v_mfma_f32_16x16x32_bf16 v[16:19], v[176:179], v[212:215], v[16:19]
	v_mfma_f32_16x16x32_bf16 v[12:15], v[184:187], v[200:203], v[12:15]
	v_mfma_f32_16x16x32_bf16 v[8:11], v[184:187], v[212:215], v[8:11]
	v_mfma_f32_16x16x32_bf16 v[4:7], v[192:195], v[200:203], v[4:7]
	v_mfma_f32_16x16x32_bf16 v[0:3], v[192:195], v[212:215], v[0:3]
	v_mfma_f32_16x16x32_bf16 v[28:31], v[172:175], v[204:207], v[28:31]
	v_mfma_f32_16x16x32_bf16 v[24:27], v[172:175], v[216:219], v[24:27]
	v_mfma_f32_16x16x32_bf16 v[20:23], v[180:183], v[204:207], v[20:23]
	v_mfma_f32_16x16x32_bf16 v[16:19], v[180:183], v[216:219], v[16:19]
	v_mfma_f32_16x16x32_bf16 v[12:15], v[188:191], v[204:207], v[12:15]
	v_mfma_f32_16x16x32_bf16 v[8:11], v[188:191], v[216:219], v[8:11]
	v_mfma_f32_16x16x32_bf16 v[4:7], v[196:199], v[204:207], v[4:7]
	v_mfma_f32_16x16x32_bf16 v[0:3], v[196:199], v[216:219], v[0:3]
	s_setprio 0
	s_barrier
	ds_read_b128 v[152:155], v132
	ds_read_b128 v[156:159], v132 offset:1024
	ds_read_b128 v[160:163], v132 offset:2048
	ds_read_b128 v[164:167], v132 offset:3072
	v_readfirstlane_b32 s45, v140
	s_add_i32 s44, s42, 0x40100
	s_mov_b32 m0, s45
	v_readfirstlane_b32 s45, v141
	buffer_load_dwordx4 v131, s[8:11], s44 offen lds
	s_mov_b32 m0, s45
	s_nop 0
	buffer_load_dwordx4 v133, s[8:11], s44 offen lds
	ds_read_b128 v[168:171], v128 offset:32768
	ds_read_b128 v[172:175], v128 offset:33792
	ds_read_b128 v[176:179], v128 offset:34816
	ds_read_b128 v[180:183], v128 offset:35840
	ds_read_b128 v[184:187], v128 offset:36864
	ds_read_b128 v[188:191], v128 offset:37888
	ds_read_b128 v[192:195], v128 offset:38912
	ds_read_b128 v[196:199], v129 offset:39936
	s_waitcnt lgkmcnt(8)
	s_barrier
	s_setprio 1
	s_waitcnt lgkmcnt(7)
	v_mfma_f32_16x16x32_bf16 v[124:127], v[168:171], v[152:155], v[124:127]
	v_mfma_f32_16x16x32_bf16 v[120:123], v[168:171], v[160:163], v[120:123]
	s_waitcnt lgkmcnt(5)
	v_mfma_f32_16x16x32_bf16 v[116:119], v[176:179], v[152:155], v[116:119]
	v_mfma_f32_16x16x32_bf16 v[112:115], v[176:179], v[160:163], v[112:115]
	s_waitcnt lgkmcnt(3)
	v_mfma_f32_16x16x32_bf16 v[108:111], v[184:187], v[152:155], v[108:111]
	v_mfma_f32_16x16x32_bf16 v[104:107], v[184:187], v[160:163], v[104:107]
	s_waitcnt lgkmcnt(1)
	v_mfma_f32_16x16x32_bf16 v[100:103], v[192:195], v[152:155], v[100:103]
	v_mfma_f32_16x16x32_bf16 v[96:99], v[192:195], v[160:163], v[96:99]
	v_mfma_f32_16x16x32_bf16 v[124:127], v[172:175], v[156:159], v[124:127]
	v_mfma_f32_16x16x32_bf16 v[120:123], v[172:175], v[164:167], v[120:123]
	v_mfma_f32_16x16x32_bf16 v[116:119], v[180:183], v[156:159], v[116:119]
	v_mfma_f32_16x16x32_bf16 v[112:115], v[180:183], v[164:167], v[112:115]
	v_mfma_f32_16x16x32_bf16 v[108:111], v[188:191], v[156:159], v[108:111]
	v_mfma_f32_16x16x32_bf16 v[104:107], v[188:191], v[164:167], v[104:107]
	s_waitcnt lgkmcnt(0)
	v_mfma_f32_16x16x32_bf16 v[100:103], v[196:199], v[156:159], v[100:103]
	v_mfma_f32_16x16x32_bf16 v[96:99], v[196:199], v[164:167], v[96:99]
	s_setprio 0
	s_barrier
	v_readfirstlane_b32 s45, v143
	s_add_i32 s44, s43, 0x180
	s_mov_b32 m0, s45
	v_readfirstlane_b32 s45, v144
	buffer_load_dwordx4 v131, s[88:91], s44 offen lds
	s_mov_b32 m0, s45
	s_nop 0
	buffer_load_dwordx4 v133, s[88:91], s44 offen lds
	ds_read_b128 v[200:203], v130
	ds_read_b128 v[204:207], v130 offset:1024
	ds_read_b128 v[212:215], v130 offset:2048
	ds_read_b128 v[216:219], v130 offset:3072
	s_barrier
	s_setprio 1
	s_waitcnt lgkmcnt(3)
	v_mfma_f32_16x16x32_bf16 v[92:95], v[168:171], v[200:203], v[92:95]
	s_waitcnt lgkmcnt(1)
	v_mfma_f32_16x16x32_bf16 v[88:91], v[168:171], v[212:215], v[88:91]
	v_mfma_f32_16x16x32_bf16 v[84:87], v[176:179], v[200:203], v[84:87]
	v_mfma_f32_16x16x32_bf16 v[80:83], v[176:179], v[212:215], v[80:83]
	v_mfma_f32_16x16x32_bf16 v[76:79], v[184:187], v[200:203], v[76:79]
	v_mfma_f32_16x16x32_bf16 v[72:75], v[184:187], v[212:215], v[72:75]
	v_mfma_f32_16x16x32_bf16 v[68:71], v[192:195], v[200:203], v[68:71]
	v_mfma_f32_16x16x32_bf16 v[64:67], v[192:195], v[212:215], v[64:67]
	v_mfma_f32_16x16x32_bf16 v[92:95], v[172:175], v[204:207], v[92:95]
	s_waitcnt lgkmcnt(0)
	v_mfma_f32_16x16x32_bf16 v[88:91], v[172:175], v[216:219], v[88:91]
	v_mfma_f32_16x16x32_bf16 v[84:87], v[180:183], v[204:207], v[84:87]
	v_mfma_f32_16x16x32_bf16 v[80:83], v[180:183], v[216:219], v[80:83]
	v_mfma_f32_16x16x32_bf16 v[76:79], v[188:191], v[204:207], v[76:79]
	v_mfma_f32_16x16x32_bf16 v[72:75], v[188:191], v[216:219], v[72:75]
	v_mfma_f32_16x16x32_bf16 v[68:71], v[196:199], v[204:207], v[68:71]
	v_mfma_f32_16x16x32_bf16 v[64:67], v[196:199], v[216:219], v[64:67]
	s_setprio 0
	v_readfirstlane_b32 s44, v145
	s_addk_i32 s42, 0x180
	s_mov_b32 m0, s44
	v_readfirstlane_b32 s44, v146
	s_barrier
	buffer_load_dwordx4 v131, s[8:11], s42 offen lds
	s_mov_b32 m0, s44
	s_nop 0
	buffer_load_dwordx4 v133, s[8:11], s42 offen lds
	ds_read_b128 v[168:171], v128 offset:49152
	ds_read_b128 v[172:175], v128 offset:50176
	ds_read_b128 v[176:179], v128 offset:51200
	ds_read_b128 v[180:183], v128 offset:52224
	ds_read_b128 v[184:187], v128 offset:53248
	ds_read_b128 v[188:191], v128 offset:54272
	ds_read_b128 v[192:195], v128 offset:55296
	ds_read_b128 v[196:199], v129 offset:56320
	s_barrier
; #define WAIT_V(n) asm volatile("s_waitcnt vmcnt(" #n ")" ::: "memory")
; #define WAIT_L(n) asm volatile("s_waitcnt lgkmcnt(" #n ")" ::: "memory")
; #define BAR __builtin_amdgcn_s_barrier()
; #define SCHED __builtin_amdgcn_sched_barrier(0)
;     ...
;     LDA(At, 1, 1); STAGE(SA(1, 0), A, brow, t + 3);
;     BAR; WAIT_L(0); MMA(1, 0, At, B0); BAR; SCHED;
;     STAGE(SB(1, 1), Bt, bcol + HALF, t + 3);
;     WAIT_V(6); BAR; MMA(1, 1, At, B1); BAR;
;   }
;   { LDB(B0, 0, 0); LDA(At, 0, 0); STAGE(SA(1, 1), A, brow + HALF, nt - 1);
;     BAR; WAIT_L(0); MMA(0, 0, At, B0); BAR;
;     LDB(B1, 0, 1); BAR; WAIT_L(0); MMA(0, 1, At, B1); BAR;
;     LDA(At, 0, 1); WAIT_V(4); BAR; WAIT_L(0); MMA(1, 0, At, B0); MMA(1, 1, At, B1); BAR; }
	s_setprio 1
	s_waitcnt lgkmcnt(7)
	v_mfma_f32_16x16x32_bf16 v[60:63], v[168:171], v[152:155], v[60:63]
	v_mfma_f32_16x16x32_bf16 v[56:59], v[168:171], v[160:163], v[56:59]
	s_waitcnt lgkmcnt(5)
	v_mfma_f32_16x16x32_bf16 v[52:55], v[176:179], v[152:155], v[52:55]
	v_mfma_f32_16x16x32_bf16 v[48:51], v[176:179], v[160:163], v[48:51]
	s_waitcnt lgkmcnt(3)
	v_mfma_f32_16x16x32_bf16 v[44:47], v[184:187], v[152:155], v[44:47]
	v_mfma_f32_16x16x32_bf16 v[40:43], v[184:187], v[160:163], v[40:43]
	s_waitcnt lgkmcnt(1)
	v_mfma_f32_16x16x32_bf16 v[36:39], v[192:195], v[152:155], v[36:39]
	v_mfma_f32_16x16x32_bf16 v[32:35], v[192:195], v[160:163], v[32:35]
	v_mfma_f32_16x16x32_bf16 v[60:63], v[172:175], v[156:159], v[60:63]
	v_mfma_f32_16x16x32_bf16 v[56:59], v[172:175], v[164:167], v[56:59]
	v_mfma_f32_16x16x32_bf16 v[52:55], v[180:183], v[156:159], v[52:55]
	v_mfma_f32_16x16x32_bf16 v[48:51], v[180:183], v[164:167], v[48:51]
	v_mfma_f32_16x16x32_bf16 v[44:47], v[188:191], v[156:159], v[44:47]
	v_mfma_f32_16x16x32_bf16 v[40:43], v[188:191], v[164:167], v[40:43]
	s_waitcnt lgkmcnt(0)
	v_mfma_f32_16x16x32_bf16 v[36:39], v[196:199], v[156:159], v[36:39]
	v_mfma_f32_16x16x32_bf16 v[32:35], v[196:199], v[164:167], v[32:35]
	s_setprio 0
	s_barrier
	v_readfirstlane_b32 s42, v149
	s_add_i32 s43, s43, 0x40180
	s_mov_b32 m0, s42
	v_readfirstlane_b32 s42, v150
	buffer_load_dwordx4 v131, s[88:91], s43 offen lds
	s_mov_b32 m0, s42
	s_nop 0
	buffer_load_dwordx4 v133, s[88:91], s43 offen lds
	s_waitcnt vmcnt(6)
	s_barrier
	s_setprio 1
	v_mfma_f32_16x16x32_bf16 v[28:31], v[168:171], v[200:203], v[28:31]
	v_mfma_f32_16x16x32_bf16 v[24:27], v[168:171], v[212:215], v[24:27]
	v_mfma_f32_16x16x32_bf16 v[20:23], v[176:179], v[200:203], v[20:23]
	v_mfma_f32_16x16x32_bf16 v[16:19], v[176:179], v[212:215], v[16:19]
	v_mfma_f32_16x16x32_bf16 v[12:15], v[184:187], v[200:203], v[12:15]
	v_mfma_f32_16x16x32_bf16 v[8:11], v[184:187], v[212:215], v[8:11]
	v_mfma_f32_16x16x32_bf16 v[4:7], v[192:195], v[200:203], v[4:7]
	v_mfma_f32_16x16x32_bf16 v[0:3], v[192:195], v[212:215], v[0:3]
	v_mfma_f32_16x16x32_bf16 v[28:31], v[172:175], v[204:207], v[28:31]
	v_mfma_f32_16x16x32_bf16 v[24:27], v[172:175], v[216:219], v[24:27]
	v_mfma_f32_16x16x32_bf16 v[20:23], v[180:183], v[204:207], v[20:23]
	v_mfma_f32_16x16x32_bf16 v[16:19], v[180:183], v[216:219], v[16:19]
	v_mfma_f32_16x16x32_bf16 v[12:15], v[188:191], v[204:207], v[12:15]
	v_mfma_f32_16x16x32_bf16 v[8:11], v[188:191], v[216:219], v[8:11]
	v_mfma_f32_16x16x32_bf16 v[4:7], v[196:199], v[204:207], v[4:7]
	v_mfma_f32_16x16x32_bf16 v[0:3], v[196:199], v[216:219], v[0:3]
	s_setprio 0
	s_add_i32 s4, s4, 2
	s_addk_i32 s5, 0x100
	s_cmp_lt_u32 s4, 12
	s_barrier
	s_cbranch_scc1 .LBB0_441
	v_readfirstlane_b32 s4, v148
	s_mov_b32 s10, s90
	s_mov_b32 s11, s91
	s_mov_b32 m0, s4
	v_readfirstlane_b32 s4, v147
	buffer_load_dwordx4 v131, s[8:11], s39 offen lds
	s_mov_b32 m0, s4
	s_nop 0
	buffer_load_dwordx4 v133, s[8:11], s39 offen lds
	ds_read_b128 v[134:137], v151
	ds_read_b128 v[138:141], v151 offset:1024
	ds_read_b128 v[144:147], v151 offset:2048
	ds_read_b128 v[148:151], v151 offset:3072
	ds_read_b128 v[152:155], v128
	ds_read_b128 v[156:159], v128 offset:1024
	ds_read_b128 v[160:163], v128 offset:2048
	ds_read_b128 v[164:167], v128 offset:3072
	ds_read_b128 v[168:171], v128 offset:4096
	ds_read_b128 v[172:175], v128 offset:5120
	ds_read_b128 v[176:179], v128 offset:6144
	ds_read_b128 v[180:183], v129 offset:7168
	s_barrier
	s_setprio 1
	s_waitcnt lgkmcnt(7)
	v_mfma_f32_16x16x32_bf16 v[124:127], v[152:155], v[134:137], v[124:127]
	s_waitcnt lgkmcnt(5)
	v_mfma_f32_16x16x32_bf16 v[112:115], v[160:163], v[144:147], v[112:115]
	s_waitcnt lgkmcnt(3)
	v_mfma_f32_16x16x32_bf16 v[104:107], v[168:171], v[144:147], v[104:107]
	s_waitcnt lgkmcnt(1)
	v_mfma_f32_16x16x32_bf16 v[100:103], v[176:179], v[134:137], v[100:103]
	v_mfma_f32_16x16x32_bf16 v[124:127], v[156:159], v[138:141], v[124:127]
	v_mfma_f32_16x16x32_bf16 v[120:123], v[152:155], v[144:147], v[120:123]
	v_mfma_f32_16x16x32_bf16 v[116:119], v[160:163], v[134:137], v[116:119]
	v_mfma_f32_16x16x32_bf16 v[112:115], v[164:167], v[148:151], v[112:115]
	v_mfma_f32_16x16x32_bf16 v[108:111], v[168:171], v[134:137], v[108:111]
	v_mfma_f32_16x16x32_bf16 v[104:107], v[172:175], v[148:151], v[104:107]
	s_waitcnt lgkmcnt(0)
	v_mfma_f32_16x16x32_bf16 v[100:103], v[180:183], v[138:141], v[100:103]
	v_mfma_f32_16x16x32_bf16 v[96:99], v[176:179], v[144:147], v[96:99]
	v_mfma_f32_16x16x32_bf16 v[120:123], v[156:159], v[148:151], v[120:123]
	v_mfma_f32_16x16x32_bf16 v[116:119], v[164:167], v[138:141], v[116:119]
	v_mfma_f32_16x16x32_bf16 v[108:111], v[172:175], v[138:141], v[108:111]
	v_mfma_f32_16x16x32_bf16 v[96:99], v[180:183], v[148:151], v[96:99]
	s_setprio 0
	s_barrier
	ds_read_b128 v[184:187], v142
	ds_read_b128 v[188:191], v142 offset:1024
	ds_read_b128 v[192:195], v142 offset:2048
	ds_read_b128 v[196:199], v142 offset:3072
	s_barrier
	s_setprio 1
	s_waitcnt lgkmcnt(3)
	v_mfma_f32_16x16x32_bf16 v[92:95], v[152:155], v[184:187], v[92:95]
	v_mfma_f32_16x16x32_bf16 v[76:79], v[168:171], v[184:187], v[76:79]
	s_waitcnt lgkmcnt(1)
	v_mfma_f32_16x16x32_bf16 v[72:75], v[168:171], v[192:195], v[72:75]
	v_mfma_f32_16x16x32_bf16 v[64:67], v[176:179], v[192:195], v[64:67]
	v_mfma_f32_16x16x32_bf16 v[92:95], v[156:159], v[188:191], v[92:95]
	v_mfma_f32_16x16x32_bf16 v[88:91], v[152:155], v[192:195], v[88:91]
	v_mfma_f32_16x16x32_bf16 v[84:87], v[160:163], v[184:187], v[84:87]
	v_mfma_f32_16x16x32_bf16 v[80:83], v[160:163], v[192:195], v[80:83]
	v_mfma_f32_16x16x32_bf16 v[76:79], v[172:175], v[188:191], v[76:79]
	s_waitcnt lgkmcnt(0)
	v_mfma_f32_16x16x32_bf16 v[72:75], v[172:175], v[196:199], v[72:75]
	v_mfma_f32_16x16x32_bf16 v[68:71], v[176:179], v[184:187], v[68:71]
	v_mfma_f32_16x16x32_bf16 v[64:67], v[180:183], v[196:199], v[64:67]
	v_mfma_f32_16x16x32_bf16 v[88:91], v[156:159], v[196:199], v[88:91]
	v_mfma_f32_16x16x32_bf16 v[152:155], v[164:167], v[188:191], v[84:87]
	v_mfma_f32_16x16x32_bf16 v[156:159], v[164:167], v[196:199], v[80:83]
	v_mfma_f32_16x16x32_bf16 v[160:163], v[180:183], v[188:191], v[68:71]
	s_setprio 0
	s_barrier
; #define WAIT_V(n) asm volatile("s_waitcnt vmcnt(" #n ")" ::: "memory")
; #define WAIT_L(n) asm volatile("s_waitcnt lgkmcnt(" #n ")" ::: "memory")
; #define BAR __builtin_amdgcn_s_barrier()
;     ...
;     LDA(At, 0, 1); WAIT_V(4); BAR; WAIT_L(0); MMA(1, 0, At, B0); MMA(1, 1, At, B1); BAR; }
;   { LDB(B0, 1, 0); LDA(At, 1, 0); WAIT_V(2); BAR;
;     if (has_next) {
;       STAGE(SB(0, 0), Bt, nbcol, 0); STAGE(SA(0, 0), A, nbrow, 0);
;       STAGE(SB(0, 1), Bt, nbcol + HALF, 0); STAGE(SA(0, 1), A, nbrow + HALF, 0);
;     }
;     WAIT_L(0); MMA(0, 0, At, B0); BAR;
	s_nop 0
	ds_read_b128 v[68:71], v128 offset:16384
	ds_read_b128 v[80:83], v128 offset:17408
	ds_read_b128 v[84:87], v128 offset:18432
	ds_read_b128 v[164:167], v128 offset:19456
	ds_read_b128 v[168:171], v128 offset:20480
	ds_read_b128 v[172:175], v128 offset:21504
	ds_read_b128 v[176:179], v128 offset:22528
	ds_read_b128 v[180:183], v129 offset:23552
	s_waitcnt vmcnt(4)
	s_barrier
	s_setprio 1
	s_waitcnt lgkmcnt(7)
	v_mfma_f32_16x16x32_bf16 v[56:59], v[68:71], v[144:147], v[56:59]
	s_waitcnt lgkmcnt(5)
	v_mfma_f32_16x16x32_bf16 v[52:55], v[84:87], v[134:137], v[52:55]
	v_mfma_f32_16x16x32_bf16 v[48:51], v[84:87], v[144:147], v[48:51]
	s_waitcnt lgkmcnt(3)
	v_mfma_f32_16x16x32_bf16 v[44:47], v[168:171], v[134:137], v[44:47]
	v_mfma_f32_16x16x32_bf16 v[40:43], v[168:171], v[144:147], v[40:43]
	s_waitcnt lgkmcnt(1)
	v_mfma_f32_16x16x32_bf16 v[36:39], v[176:179], v[134:137], v[36:39]
	v_mfma_f32_16x16x32_bf16 v[32:35], v[176:179], v[144:147], v[32:35]
	v_mfma_f32_16x16x32_bf16 v[60:63], v[68:71], v[134:137], v[60:63]
	v_mfma_f32_16x16x32_bf16 v[56:59], v[80:83], v[148:151], v[56:59]
	v_mfma_f32_16x16x32_bf16 v[52:55], v[164:167], v[138:141], v[52:55]
	v_mfma_f32_16x16x32_bf16 v[48:51], v[164:167], v[148:151], v[48:51]
	v_mfma_f32_16x16x32_bf16 v[44:47], v[172:175], v[138:141], v[44:47]
	v_mfma_f32_16x16x32_bf16 v[40:43], v[172:175], v[148:151], v[40:43]
	s_waitcnt lgkmcnt(0)
	v_mfma_f32_16x16x32_bf16 v[36:39], v[180:183], v[138:141], v[36:39]
	v_mfma_f32_16x16x32_bf16 v[32:35], v[180:183], v[148:151], v[32:35]
	v_mfma_f32_16x16x32_bf16 v[200:203], v[80:83], v[138:141], v[60:63]
	s_setprio 0
	s_setprio 1
	v_mfma_f32_16x16x32_bf16 v[28:31], v[68:71], v[184:187], v[28:31]
	v_mfma_f32_16x16x32_bf16 v[24:27], v[68:71], v[192:195], v[24:27]
	v_mfma_f32_16x16x32_bf16 v[20:23], v[84:87], v[184:187], v[20:23]
	v_mfma_f32_16x16x32_bf16 v[16:19], v[84:87], v[192:195], v[16:19]
	v_mfma_f32_16x16x32_bf16 v[12:15], v[168:171], v[184:187], v[12:15]
	v_mfma_f32_16x16x32_bf16 v[8:11], v[168:171], v[192:195], v[8:11]
	v_mfma_f32_16x16x32_bf16 v[4:7], v[176:179], v[184:187], v[4:7]
	v_mfma_f32_16x16x32_bf16 v[0:3], v[176:179], v[192:195], v[0:3]
	v_mfma_f32_16x16x32_bf16 v[28:31], v[80:83], v[188:191], v[28:31]
	v_mfma_f32_16x16x32_bf16 v[24:27], v[80:83], v[196:199], v[24:27]
	v_mfma_f32_16x16x32_bf16 v[20:23], v[164:167], v[188:191], v[20:23]
	v_mfma_f32_16x16x32_bf16 v[16:19], v[164:167], v[196:199], v[16:19]
	v_mfma_f32_16x16x32_bf16 v[12:15], v[172:175], v[188:191], v[12:15]
	v_mfma_f32_16x16x32_bf16 v[8:11], v[172:175], v[196:199], v[8:11]
	v_mfma_f32_16x16x32_bf16 v[4:7], v[180:183], v[188:191], v[4:7]
	v_mfma_f32_16x16x32_bf16 v[0:3], v[180:183], v[196:199], v[0:3]
	s_setprio 0
	s_barrier
	ds_read_b128 v[140:143], v132
	ds_read_b128 v[148:151], v132 offset:1024
	ds_read_b128 v[164:167], v132 offset:2048
	ds_read_b128 v[172:175], v132 offset:3072
	ds_read_b128 v[132:135], v128 offset:32768
	ds_read_b128 v[176:179], v128 offset:33792
	ds_read_b128 v[180:183], v128 offset:34816
	ds_read_b128 v[184:187], v128 offset:35840
	ds_read_b128 v[188:191], v128 offset:36864
	ds_read_b128 v[204:207], v128 offset:37888
	ds_read_b128 v[212:215], v128 offset:38912
	ds_read_b128 v[216:219], v129 offset:39936
	s_waitcnt vmcnt(2)
	s_barrier
	s_setprio 1
	s_waitcnt lgkmcnt(7)
	v_mfma_f32_16x16x32_bf16 v[60:63], v[132:135], v[140:143], v[124:127]
	s_waitcnt lgkmcnt(6)
	v_mfma_f32_16x16x32_bf16 v[194:197], v[176:179], v[148:151], v[60:63]
	v_mfma_f32_16x16x32_bf16 v[60:63], v[132:135], v[164:167], v[120:123]
	v_mfma_f32_16x16x32_bf16 v[168:171], v[176:179], v[172:175], v[60:63]
	s_waitcnt lgkmcnt(5)
	v_mfma_f32_16x16x32_bf16 v[60:63], v[180:183], v[140:143], v[116:119]
	s_waitcnt lgkmcnt(4)
	v_mfma_f32_16x16x32_bf16 v[136:139], v[184:187], v[148:151], v[60:63]
	v_mfma_f32_16x16x32_bf16 v[60:63], v[180:183], v[164:167], v[112:115]
	v_mfma_f32_16x16x32_bf16 v[124:127], v[184:187], v[172:175], v[60:63]
	s_waitcnt lgkmcnt(3)
	v_mfma_f32_16x16x32_bf16 v[60:63], v[188:191], v[140:143], v[108:111]
	s_waitcnt lgkmcnt(2)
	v_mfma_f32_16x16x32_bf16 v[84:87], v[204:207], v[148:151], v[60:63]
	v_mfma_f32_16x16x32_bf16 v[60:63], v[188:191], v[164:167], v[104:107]
	v_mfma_f32_16x16x32_bf16 v[80:83], v[204:207], v[172:175], v[60:63]
	s_waitcnt lgkmcnt(1)
	v_mfma_f32_16x16x32_bf16 v[60:63], v[212:215], v[140:143], v[100:103]
	s_waitcnt lgkmcnt(0)
	v_mfma_f32_16x16x32_bf16 v[68:71], v[216:219], v[148:151], v[60:63]
	v_mfma_f32_16x16x32_bf16 v[60:63], v[212:215], v[164:167], v[96:99]
	v_mfma_f32_16x16x32_bf16 v[60:63], v[216:219], v[172:175], v[60:63]
	s_setprio 0
	s_barrier
; #define WAIT_V(n) asm volatile("s_waitcnt vmcnt(" #n ")" ::: "memory")
; #define WAIT_L(n) asm volatile("s_waitcnt lgkmcnt(" #n ")" ::: "memory")
; #define BAR __builtin_amdgcn_s_barrier()
;     ...
;     LDB(B1, 1, 1); if (has_next) { WAIT_V(8); } else { WAIT_V(0); } BAR; WAIT_L(0); MMA(0, 1, At, B1); BAR;
;     LDA(At, 1, 1); BAR; WAIT_L(0); MMA(1, 0, At, B0); MMA(1, 1, At, B1); BAR; }
;   if (wr == 0) BAR;
	ds_read_b128 v[96:99], v130
	ds_read_b128 v[108:111], v130 offset:1024
	ds_read_b128 v[116:119], v130 offset:2048
	ds_read_b128 v[120:123], v130 offset:3072
	s_waitcnt vmcnt(0)
	s_barrier
	s_setprio 1
	s_waitcnt lgkmcnt(1)
	v_mfma_f32_16x16x32_bf16 v[88:91], v[132:135], v[116:119], v[88:91]
	v_mfma_f32_16x16x32_bf16 v[92:95], v[132:135], v[96:99], v[92:95]
	s_waitcnt lgkmcnt(0)
	v_mfma_f32_16x16x32_bf16 v[132:135], v[176:179], v[120:123], v[88:91]
	v_mfma_f32_16x16x32_bf16 v[88:91], v[180:183], v[96:99], v[152:155]
	v_mfma_f32_16x16x32_bf16 v[72:75], v[188:191], v[116:119], v[72:75]
	v_mfma_f32_16x16x32_bf16 v[144:147], v[176:179], v[108:111], v[92:95]
	v_mfma_f32_16x16x32_bf16 v[112:115], v[184:187], v[108:111], v[88:91]
	v_mfma_f32_16x16x32_bf16 v[88:91], v[180:183], v[116:119], v[156:159]
	v_mfma_f32_16x16x32_bf16 v[76:79], v[188:191], v[96:99], v[76:79]
	v_mfma_f32_16x16x32_bf16 v[92:95], v[204:207], v[120:123], v[72:75]
	v_mfma_f32_16x16x32_bf16 v[72:75], v[212:215], v[96:99], v[160:163]
	v_mfma_f32_16x16x32_bf16 v[64:67], v[212:215], v[116:119], v[64:67]
	v_mfma_f32_16x16x32_bf16 v[104:107], v[184:187], v[120:123], v[88:91]
	v_mfma_f32_16x16x32_bf16 v[100:103], v[204:207], v[108:111], v[76:79]
	v_mfma_f32_16x16x32_bf16 v[76:79], v[216:219], v[108:111], v[72:75]
	v_mfma_f32_16x16x32_bf16 v[72:75], v[216:219], v[120:123], v[64:67]
	s_setprio 0
	s_barrier
	ds_read_b128 v[88:91], v128 offset:49152
	ds_read_b128 v[152:155], v128 offset:50176
	ds_read_b128 v[156:159], v128 offset:51200
	ds_read_b128 v[160:163], v128 offset:52224
	ds_read_b128 v[176:179], v128 offset:53248
	ds_read_b128 v[180:183], v128 offset:54272
	ds_read_b128 v[184:187], v128 offset:55296
	ds_read_b128 v[128:131], v129 offset:56320
	s_barrier
	s_setprio 1
	s_waitcnt lgkmcnt(7)
	v_mfma_f32_16x16x32_bf16 v[64:67], v[88:91], v[140:143], v[200:203]
	v_mfma_f32_16x16x32_bf16 v[56:59], v[88:91], v[164:167], v[56:59]
	s_waitcnt lgkmcnt(5)
	v_mfma_f32_16x16x32_bf16 v[52:55], v[156:159], v[140:143], v[52:55]
	v_mfma_f32_16x16x32_bf16 v[48:51], v[156:159], v[164:167], v[48:51]
	s_waitcnt lgkmcnt(3)
	v_mfma_f32_16x16x32_bf16 v[44:47], v[176:179], v[140:143], v[44:47]
	v_mfma_f32_16x16x32_bf16 v[40:43], v[176:179], v[164:167], v[40:43]
	s_waitcnt lgkmcnt(1)
	v_mfma_f32_16x16x32_bf16 v[36:39], v[184:187], v[140:143], v[36:39]
	v_mfma_f32_16x16x32_bf16 v[32:35], v[184:187], v[164:167], v[32:35]
	v_mfma_f32_16x16x32_bf16 v[64:67], v[152:155], v[148:151], v[64:67]
	v_mfma_f32_16x16x32_bf16 v[56:59], v[152:155], v[172:175], v[56:59]
	v_mfma_f32_16x16x32_bf16 v[52:55], v[160:163], v[148:151], v[52:55]
	v_mfma_f32_16x16x32_bf16 v[48:51], v[160:163], v[172:175], v[48:51]
	v_mfma_f32_16x16x32_bf16 v[44:47], v[180:183], v[148:151], v[44:47]
	v_mfma_f32_16x16x32_bf16 v[40:43], v[180:183], v[172:175], v[40:43]
	s_waitcnt lgkmcnt(0)
	v_mfma_f32_16x16x32_bf16 v[36:39], v[128:131], v[148:151], v[36:39]
	v_mfma_f32_16x16x32_bf16 v[32:35], v[128:131], v[172:175], v[32:35]
	s_setprio 0
	s_setprio 1
	v_mfma_f32_16x16x32_bf16 v[28:31], v[88:91], v[96:99], v[28:31]
	v_mfma_f32_16x16x32_bf16 v[24:27], v[88:91], v[116:119], v[24:27]
	v_mfma_f32_16x16x32_bf16 v[20:23], v[156:159], v[96:99], v[20:23]
	v_mfma_f32_16x16x32_bf16 v[16:19], v[156:159], v[116:119], v[16:19]
	v_mfma_f32_16x16x32_bf16 v[12:15], v[176:179], v[96:99], v[12:15]
	v_mfma_f32_16x16x32_bf16 v[8:11], v[176:179], v[116:119], v[8:11]
	v_mfma_f32_16x16x32_bf16 v[4:7], v[184:187], v[96:99], v[4:7]
	v_mfma_f32_16x16x32_bf16 v[0:3], v[184:187], v[116:119], v[0:3]
	v_mfma_f32_16x16x32_bf16 v[28:31], v[152:155], v[108:111], v[28:31]
	v_mfma_f32_16x16x32_bf16 v[24:27], v[152:155], v[120:123], v[24:27]
	v_mfma_f32_16x16x32_bf16 v[20:23], v[160:163], v[108:111], v[20:23]
	v_mfma_f32_16x16x32_bf16 v[16:19], v[160:163], v[120:123], v[16:19]
	v_mfma_f32_16x16x32_bf16 v[12:15], v[180:183], v[108:111], v[12:15]
	v_mfma_f32_16x16x32_bf16 v[8:11], v[180:183], v[120:123], v[8:11]
	v_mfma_f32_16x16x32_bf16 v[4:7], v[128:131], v[108:111], v[4:7]
	v_mfma_f32_16x16x32_bf16 v[0:3], v[128:131], v[120:123], v[0:3]
	s_setprio 0
	s_barrier
	s_and_saveexec_b64 s[4:5], vcc
	s_cbranch_execz .LBB0_444
	s_barrier

; DEVI float bf2f(u16 h) { return __uint_as_float(((unsigned)h) << 16); }
; DEVI void gla_local_item(const Params& p, int l, int item) {
;     ...
; #pragma unroll
;   for (int i = 0; i < 2; ++i) {
;     int idx = tid + i * 512, tok = idx >> 4, dg = idx & 15;
;     q8[i] = *(const bf16x8*)(proj + (t0 + tok) * NP + C_AQ + h * 128 + dg * 8);
;     k8[i] = *(const bf16x8*)(proj + (t0 + tok) * NP + C_AK + h * 128 + dg * 8);
;   }
; #pragma unroll
;   for (int i = 0; i < 4; ++i) {
;     int idx = tid + i * 512, tok = idx >> 5, dg = idx & 31;
;     v8[i] = *(const bf16x8*)(proj + (t0 + tok) * NP + C_AV + h * 256 + dg * 8);
;   }
; #pragma unroll
;   for (int i = 0; i < 2; ++i) {
;     int idx = tid + i * 512;
;     alr_s[idx] = bf2f(proj[(t0 + (idx >> 4)) * NP + C_ALR + (idx & 15)]);
;   }
; #pragma unroll
;   for (int i = 0; i < 4; ++i) {
;     int idx = tid + i * 512, tok = idx >> 5, dg = idx & 31;
;     *(bf16x8*)(vS + tok * 272 + dg * 8) = v8[i];
;   }
;   __syncthreads();
;   {
;     const int d = tid & 127, grp = tid >> 7;
;     float wv[16];
; #pragma unroll
;     for (int r = 0; r < 16; ++r) wv[r] = p.gla_w_up[(long)(l * 16 + r) * 512 + h * 128 + d];
;     const float bias = p.gla_b[l * 512 + h * 128 + d];
;     float bloc[16];
;     float run = 0.f;
; #pragma unroll
;     for (int ii = 0; ii < 16; ++ii) {
;       const float* ar = alr_s + (grp * 16 + ii) * 16;
;       float z = bias;
; #pragma unroll
;       for (int r = 0; r < 16; ++r) z += ar[r] * wv[r];
.LBB0_734:
	s_ashr_i32 s2, s12, 8
	s_ashr_i32 s3, s2, 31
	s_lshl_b32 s4, s12, 6
	s_waitcnt vmcnt(0)
	v_mov_b32_e32 v22, v234
	s_lshl_b64 s[2:3], s[2:3], 12
	s_and_b32 s4, s4, 0xfc0
	s_or_b32 s2, s2, s4
	v_lshrrev_b32_e32 v23, 4, v22
	v_or_b32_e32 v18, s2, v23
	v_mov_b64_e32 v[20:21], s[92:93]
	v_or_b32_e32 v30, 0x200, v22
	s_bfe_u32 s7, s12, 0x20006
	v_mad_u64_u32 v[42:43], s[4:5], v18, s97, v[20:21]
	v_mov_b32_e32 v39, 0x7c00
	v_lshrrev_b32_e32 v25, 4, v30
	v_mad_i32_i24 v43, s3, v39, v43
	s_lshl_b32 s98, s7, 8
	v_lshlrev_b32_e32 v17, 4, v22
	v_or_b32_e32 v16, s2, v25
	v_lshl_add_u64 v[0:1], v[42:43], 0, s[98:99]
	v_and_b32_e32 v210, 0xf0, v17
	v_mad_u64_u32 v[44:45], s[4:5], v16, s97, v[20:21]
	v_lshl_add_u64 v[0:1], v[0:1], 0, v[210:211]
	v_mad_i32_i24 v45, s3, v39, v45
	global_load_dwordx4 v[8:11], v[0:1], off
	global_load_dwordx4 v[12:15], v[0:1], off offset:1024
	v_lshl_add_u64 v[0:1], v[44:45], 0, s[98:99]
	v_lshrrev_b32_e32 v72, 5, v22
	v_lshrrev_b32_e32 v46, 5, v30
	v_lshl_add_u64 v[4:5], v[0:1], 0, v[210:211]
	v_or_b32_e32 v38, s2, v72
	v_and_b32_e32 v210, 0x1f0, v17
	v_or_b32_e32 v17, s2, v46
	v_mad_u64_u32 v[30:31], s[4:5], v17, s97, v[20:21]
	v_or_b32_e32 v17, 32, v38
	v_mad_u64_u32 v[34:35], s[4:5], v17, s97, v[20:21]
	v_or_b32_e32 v17, 48, v38
	v_mad_u64_u32 v[26:27], s[4:5], v38, s97, v[20:21]
	v_mad_u64_u32 v[20:21], s[4:5], v17, s97, v[20:21]
	v_mad_i32_i24 v27, s3, v39, v27
	s_lshl_b32 s98, s7, 9
	v_mad_i32_i24 v21, s3, v39, v21
	v_lshl_add_u64 v[26:27], v[26:27], 0, s[98:99]
	v_lshl_add_u64 v[20:21], v[20:21], 0, s[98:99]
	v_and_b32_e32 v24, 15, v22
	v_lshl_add_u64 v[26:27], v[26:27], 0, v[210:211]
	v_lshl_add_u64 v[20:21], v[20:21], 0, v[210:211]
	global_load_dwordx4 v[0:3], v[4:5], off
	s_nop 0
	global_load_dwordx4 v[4:7], v[4:5], off offset:1024
	v_mad_i32_i24 v31, s3, v39, v31
	global_load_dwordx4 v[26:29], v[26:27], off offset:2048
	v_mad_i32_i24 v35, s3, v39, v35
	global_load_dwordx4 v[38:41], v[20:21], off offset:2048
	v_lshlrev_b32_e32 v20, 1, v24
	v_mov_b32_e32 v21, v211
	v_lshl_add_u64 v[42:43], v[42:43], 0, v[20:21]
	v_add_co_u32_e32 v42, vcc, s83, v42
	v_lshl_add_u64 v[20:21], v[44:45], 0, v[20:21]
	s_nop 0
	v_addc_co_u32_e32 v43, vcc, 0, v43, vcc
	v_lshl_add_u64 v[30:31], v[30:31], 0, s[98:99]
	v_lshl_add_u64 v[34:35], v[34:35], 0, s[98:99]
	v_add_co_u32_e32 v20, vcc, s83, v20
	v_lshl_add_u64 v[30:31], v[30:31], 0, v[210:211]
	v_lshl_add_u64 v[34:35], v[34:35], 0, v[210:211]
	v_addc_co_u32_e32 v21, vcc, 0, v21, vcc
	global_load_dwordx4 v[30:33], v[30:31], off offset:2048
	s_lshl_b32 s6, s7, 7
	global_load_dwordx4 v[34:37], v[34:35], off offset:2048
	s_add_u32 s2, s8, s98
	global_load_ushort v17, v[42:43], off offset:2560
	v_mov_b32_e32 v19, s3
	global_load_ushort v20, v[20:21], off offset:2560
	s_addc_u32 s3, s9, 0
	v_mov_b32_e32 v64, 0x41b17218
	s_waitcnt vmcnt(1)
	v_lshlrev_b32_e32 v42, 16, v17
	v_lshl_add_u32 v17, v22, 2, 0
	s_waitcnt vmcnt(0)
	v_lshlrev_b32_e32 v20, 16, v20
	ds_write2st64_b32 v17, v42, v20 offset1:8
	v_add_u32_e32 v20, 0, v210
	v_mad_u32_u24 v21, v72, s82, v20
	v_mad_u32_u24 v20, v46, s82, v20
	ds_write_b128 v21, v[26:29] offset:57344
	ds_write_b128 v20, v[30:33] offset:57344
	v_add_u32_e32 v20, 0x12400, v21
	ds_write_b128 v20, v[34:37]
	v_add_u32_e32 v20, 0x14600, v21
	ds_write_b128 v20, v[38:41]
	v_and_b32_e32 v20, 0x7f, v22
	v_lshlrev_b32_e32 v210, 2, v20
	v_lshl_add_u64 v[42:43], s[2:3], 0, v[210:211]
	v_lshl_add_u64 v[26:27], v[42:43], 0, s[18:19]
	s_waitcnt lgkmcnt(0)
	s_barrier
	global_load_dword v38, v[26:27], off
	v_lshl_add_u64 v[26:27], v[42:43], 0, s[20:21]
	global_load_dword v39, v[26:27], off
	v_lshl_add_u64 v[26:27], v[42:43], 0, s[22:23]
	global_load_dword v40, v[26:27], off
	v_lshl_add_u64 v[26:27], v[42:43], 0, s[24:25]
	global_load_dword v41, v[26:27], off
	v_lshl_add_u64 v[26:27], v[42:43], 0, s[28:29]
	global_load_dword v34, v[26:27], off
	v_lshl_add_u64 v[26:27], v[42:43], 0, s[30:31]
	global_load_dword v35, v[26:27], off
	v_lshl_add_u64 v[26:27], v[42:43], 0, s[34:35]
	global_load_dword v36, v[26:27], off
	v_lshl_add_u64 v[26:27], v[42:43], 0, s[36:37]
	global_load_dword v37, v[26:27], off
	v_lshl_add_u64 v[26:27], v[42:43], 0, s[38:39]
	global_load_dword v30, v[26:27], off
	v_lshl_add_u64 v[26:27], v[42:43], 0, s[46:47]
	global_load_dword v31, v[26:27], off
	v_lshl_add_u64 v[26:27], v[42:43], 0, s[48:49]
	global_load_dword v32, v[26:27], off
	v_lshl_add_u64 v[26:27], v[42:43], 0, s[50:51]
	v_readlane_b32 s2, v254, 13
	global_load_dword v33, v[26:27], off
	v_lshl_add_u64 v[26:27], v[42:43], 0, s[76:77]
	v_lshl_add_u64 v[28:29], v[42:43], 0, s[88:89]
	v_readlane_b32 s3, v254, 14
	global_load_dword v26, v[26:27], off
	v_lshrrev_b32_e32 v21, 7, v22
	global_load_dword v27, v[28:29], off
	v_lshl_add_u64 v[28:29], v[42:43], 0, s[2:3]
	v_readlane_b32 s2, v254, 17
	v_readlane_b32 s3, v254, 18
	global_load_dword v28, v[28:29], off
	v_lshl_add_u32 v44, v21, 10, 0
	v_lshl_add_u64 v[42:43], v[42:43], 0, s[2:3]
	v_readlane_b32 s2, v254, 19
	s_or_b32 s2, s6, s2
	global_load_dword v29, v[42:43], off
	v_or_b32_e32 v42, s2, v20
	v_ashrrev_i32_e32 v43, 31, v42
	v_lshl_add_u64 v[42:43], v[42:43], 2, s[10:11]
	global_load_dword v42, v[42:43], off
	ds_read_b128 v[46:49], v44
	ds_read_b128 v[50:53], v44 offset:16
	ds_read_b128 v[54:57], v44 offset:32
	ds_read_b128 v[58:61], v44 offset:48
	ds_read_b128 v[96:99], v44 offset:64
	ds_read_b128 v[100:103], v44 offset:80
	ds_read_b128 v[104:107], v44 offset:96
	ds_read_b128 v[108:111], v44 offset:112
	s_mov_b32 s2, 0x3d800000
	s_waitcnt vmcnt(0) lgkmcnt(7)
	v_fma_f32 v43, v38, v46, v42
	v_fmac_f32_e32 v43, v39, v47
	v_fmac_f32_e32 v43, v40, v48
	v_fmac_f32_e32 v43, v41, v49
	s_waitcnt lgkmcnt(6)
; DEVI float logsig_f(float z) { return fminf(z, 0.f) - __logf(1.f + __expf(-fabsf(z))); }
; DEVI void gla_local_item(const Params& p, int l, int item) {
;     ...
; #pragma unroll
;     for (int ii = 0; ii < 16; ++ii) {
;       const float* ar = alr_s + (grp * 16 + ii) * 16;
;       float z = bias;
; #pragma unroll
;       for (int r = 0; r < 16; ++r) z += ar[r] * wv[r];
;       run += logsig_f(z) * (1.f / 16.f);
;       bloc[ii] = run;
;     }
	v_fmac_f32_e32 v43, v34, v50
	v_fmac_f32_e32 v43, v35, v51
	v_fmac_f32_e32 v43, v36, v52
	v_fmac_f32_e32 v43, v37, v53
	s_waitcnt lgkmcnt(5)
	v_fmac_f32_e32 v43, v30, v54
	v_fmac_f32_e32 v43, v31, v55
	v_fmac_f32_e32 v43, v32, v56
	v_fmac_f32_e32 v43, v33, v57
	s_waitcnt lgkmcnt(4)
	v_fmac_f32_e32 v43, v26, v58
	v_fmac_f32_e32 v43, v27, v59
	v_fmac_f32_e32 v43, v28, v60
	v_fmac_f32_e32 v43, v29, v61
	v_min_f32_e32 v45, 0, v43
	v_mul_f32_e64 v43, |v43|, s69
	v_exp_f32_e32 v43, v43
	s_nop 0
	v_add_f32_e32 v43, 1.0, v43
	v_cmp_gt_f32_e32 vcc, s60, v43
	s_nop 1
	v_cndmask_b32_e64 v46, 0, 32, vcc
	v_ldexp_f32 v43, v43, v46
	v_log_f32_e32 v43, v43
	s_nop 0
	v_mul_f32_e32 v46, 0x3f317217, v43
	v_fma_f32 v46, v43, s85, -v46
	v_fmac_f32_e32 v46, 0x3377d1cf, v43
	v_fmac_f32_e32 v46, 0x3f317217, v43
	v_cmp_lt_f32_e64 s[4:5], |v43|, s86
	s_nop 1
	v_cndmask_b32_e64 v43, v43, v46, s[4:5]
	v_cndmask_b32_e32 v46, 0, v64, vcc
	v_sub_f32_e32 v43, v43, v46
	ds_read_b128 v[80:83], v44 offset:128
	ds_read_b128 v[84:87], v44 offset:144
	ds_read_b128 v[88:91], v44 offset:160
	ds_read_b128 v[92:95], v44 offset:176
	v_sub_f32_e32 v43, v45, v43
	v_fma_f32 v43, v43, s2, 0
	s_waitcnt lgkmcnt(7)
	v_fma_f32 v45, v38, v96, v42
	v_fmac_f32_e32 v45, v39, v97
	v_fmac_f32_e32 v45, v40, v98
	v_fmac_f32_e32 v45, v41, v99
	s_waitcnt lgkmcnt(6)
	v_fmac_f32_e32 v45, v34, v100
	v_fmac_f32_e32 v45, v35, v101
	v_fmac_f32_e32 v45, v36, v102
	v_fmac_f32_e32 v45, v37, v103
	s_waitcnt lgkmcnt(5)
	v_fmac_f32_e32 v45, v30, v104
	v_fmac_f32_e32 v45, v31, v105
	v_fmac_f32_e32 v45, v32, v106
	v_fmac_f32_e32 v45, v33, v107
	s_waitcnt lgkmcnt(4)
	v_fmac_f32_e32 v45, v26, v108
	v_fmac_f32_e32 v45, v27, v109
	v_fmac_f32_e32 v45, v28, v110
	v_fmac_f32_e32 v45, v29, v111
	v_min_f32_e32 v46, 0, v45
	v_mul_f32_e64 v45, |v45|, s69
	v_exp_f32_e32 v45, v45
	s_nop 0
	v_add_f32_e32 v45, 1.0, v45
	v_cmp_gt_f32_e32 vcc, s60, v45
	s_nop 1
	v_cndmask_b32_e64 v47, 0, 32, vcc
	v_ldexp_f32 v45, v45, v47
	v_log_f32_e32 v45, v45
	s_nop 0
	v_mul_f32_e32 v47, 0x3f317217, v45
	v_fma_f32 v47, v45, s85, -v47
	v_fmac_f32_e32 v47, 0x3377d1cf, v45
	v_fmac_f32_e32 v47, 0x3f317217, v45
	v_cmp_lt_f32_e64 s[4:5], |v45|, s86
	s_nop 1
	v_cndmask_b32_e64 v45, v45, v47, s[4:5]
	v_cndmask_b32_e32 v47, 0, v64, vcc
	v_sub_f32_e32 v45, v45, v47
	v_sub_f32_e32 v45, v46, v45
	ds_read_b128 v[96:99], v44 offset:192
	ds_read_b128 v[100:103], v44 offset:208
	ds_read_b128 v[104:107], v44 offset:224
	ds_read_b128 v[108:111], v44 offset:240
	v_fmamk_f32 v45, v45, 0x3d800000, v43
	s_waitcnt lgkmcnt(7)
	v_fma_f32 v50, v38, v80, v42
	v_fmac_f32_e32 v50, v39, v81
	v_fmac_f32_e32 v50, v40, v82
	v_fmac_f32_e32 v50, v41, v83
	s_waitcnt lgkmcnt(6)
	v_fmac_f32_e32 v50, v34, v84
	v_fmac_f32_e32 v50, v35, v85
	v_fmac_f32_e32 v50, v36, v86
	v_fmac_f32_e32 v50, v37, v87
	s_waitcnt lgkmcnt(5)
	v_fmac_f32_e32 v50, v30, v88
	v_fmac_f32_e32 v50, v31, v89
	v_fmac_f32_e32 v50, v32, v90
	v_fmac_f32_e32 v50, v33, v91
	s_waitcnt lgkmcnt(4)
	v_fmac_f32_e32 v50, v26, v92
	v_fmac_f32_e32 v50, v27, v93
	v_fmac_f32_e32 v50, v28, v94
	v_fmac_f32_e32 v50, v29, v95
	v_mul_f32_e64 v47, |v50|, s69
	v_exp_f32_e32 v47, v47
	v_min_f32_e32 v46, 0, v50
	v_add_f32_e32 v47, 1.0, v47
	v_cmp_gt_f32_e32 vcc, s60, v47
	s_nop 1
	v_cndmask_b32_e64 v48, 0, 32, vcc
	v_ldexp_f32 v47, v47, v48
	v_log_f32_e32 v47, v47
	s_nop 0
	v_mul_f32_e32 v48, 0x3f317217, v47
	v_fma_f32 v48, v47, s85, -v48
	v_fmac_f32_e32 v48, 0x3377d1cf, v47
	v_fmac_f32_e32 v48, 0x3f317217, v47
	v_cmp_lt_f32_e64 s[4:5], |v47|, s86
	s_nop 1
	v_cndmask_b32_e64 v47, v47, v48, s[4:5]
	v_cndmask_b32_e32 v48, 0, v64, vcc
	v_sub_f32_e32 v47, v47, v48
	ds_read_b128 v[80:83], v44 offset:256
	ds_read_b128 v[84:87], v44 offset:272
	ds_read_b128 v[88:91], v44 offset:288
	ds_read_b128 v[92:95], v44 offset:304
	v_sub_f32_e32 v46, v46, v47
	v_fmamk_f32 v46, v46, 0x3d800000, v45
	s_waitcnt lgkmcnt(7)
	v_fma_f32 v47, v38, v96, v42
	v_fmac_f32_e32 v47, v39, v97
	v_fmac_f32_e32 v47, v40, v98
	v_fmac_f32_e32 v47, v41, v99
	s_waitcnt lgkmcnt(6)
	v_fmac_f32_e32 v47, v34, v100
	v_fmac_f32_e32 v47, v35, v101
	v_fmac_f32_e32 v47, v36, v102
	v_fmac_f32_e32 v47, v37, v103
	s_waitcnt lgkmcnt(5)
	v_fmac_f32_e32 v47, v30, v104
	v_fmac_f32_e32 v47, v31, v105
	v_fmac_f32_e32 v47, v32, v106
	v_fmac_f32_e32 v47, v33, v107
	s_waitcnt lgkmcnt(4)
	v_fmac_f32_e32 v47, v26, v108
	v_fmac_f32_e32 v47, v27, v109
	v_fmac_f32_e32 v47, v28, v110
	v_fmac_f32_e32 v47, v29, v111
	v_min_f32_e32 v48, 0, v47
	v_mul_f32_e64 v47, |v47|, s69
	v_exp_f32_e32 v47, v47
	s_nop 0
	v_add_f32_e32 v47, 1.0, v47
	v_cmp_gt_f32_e32 vcc, s60, v47
	s_nop 1
	v_cndmask_b32_e64 v49, 0, 32, vcc
	v_ldexp_f32 v47, v47, v49
	v_log_f32_e32 v47, v47
	s_nop 0
	v_mul_f32_e32 v49, 0x3f317217, v47
	v_fma_f32 v49, v47, s85, -v49
	v_fmac_f32_e32 v49, 0x3377d1cf, v47
	v_fmac_f32_e32 v49, 0x3f317217, v47
	v_cmp_lt_f32_e64 s[4:5], |v47|, s86
	s_nop 1
	v_cndmask_b32_e64 v47, v47, v49, s[4:5]
	v_cndmask_b32_e32 v49, 0, v64, vcc
	v_sub_f32_e32 v47, v47, v49
	v_sub_f32_e32 v47, v48, v47
	ds_read_b128 v[96:99], v44 offset:320
	ds_read_b128 v[100:103], v44 offset:336
	ds_read_b128 v[104:107], v44 offset:352
	ds_read_b128 v[108:111], v44 offset:368
	v_fmamk_f32 v47, v47, 0x3d800000, v46
	s_waitcnt lgkmcnt(7)
	v_fma_f32 v52, v38, v80, v42
	v_fmac_f32_e32 v52, v39, v81
	v_fmac_f32_e32 v52, v40, v82
	v_fmac_f32_e32 v52, v41, v83
	s_waitcnt lgkmcnt(6)
	v_fmac_f32_e32 v52, v34, v84
	v_fmac_f32_e32 v52, v35, v85
	v_fmac_f32_e32 v52, v36, v86
	v_fmac_f32_e32 v52, v37, v87
	s_waitcnt lgkmcnt(5)
	v_fmac_f32_e32 v52, v30, v88
	v_fmac_f32_e32 v52, v31, v89
	v_fmac_f32_e32 v52, v32, v90
	v_fmac_f32_e32 v52, v33, v91
	s_waitcnt lgkmcnt(4)
; DEVI float logsig_f(float z) { return fminf(z, 0.f) - __logf(1.f + __expf(-fabsf(z))); }
; DEVI void gla_local_item(const Params& p, int l, int item) {
;     ...
; #pragma unroll
;     for (int ii = 0; ii < 16; ++ii) {
;       const float* ar = alr_s + (grp * 16 + ii) * 16;
;       float z = bias;
; #pragma unroll
;       for (int r = 0; r < 16; ++r) z += ar[r] * wv[r];
;       run += logsig_f(z) * (1.f / 16.f);
;       bloc[ii] = run;
;     }
	v_fmac_f32_e32 v52, v26, v92
	v_fmac_f32_e32 v52, v27, v93
	v_fmac_f32_e32 v52, v28, v94
	v_fmac_f32_e32 v52, v29, v95
	v_mul_f32_e64 v49, |v52|, s69
	v_exp_f32_e32 v49, v49
	v_min_f32_e32 v48, 0, v52
	v_add_f32_e32 v49, 1.0, v49
	v_cmp_gt_f32_e32 vcc, s60, v49
	s_nop 1
	v_cndmask_b32_e64 v50, 0, 32, vcc
	v_ldexp_f32 v49, v49, v50
	v_log_f32_e32 v49, v49
	s_nop 0
	v_mul_f32_e32 v50, 0x3f317217, v49
	v_fma_f32 v50, v49, s85, -v50
	v_fmac_f32_e32 v50, 0x3377d1cf, v49
	v_fmac_f32_e32 v50, 0x3f317217, v49
	v_cmp_lt_f32_e64 s[4:5], |v49|, s86
	s_nop 1
	v_cndmask_b32_e64 v49, v49, v50, s[4:5]
	v_cndmask_b32_e32 v50, 0, v64, vcc
	v_sub_f32_e32 v49, v49, v50
	ds_read_b128 v[80:83], v44 offset:384
	ds_read_b128 v[84:87], v44 offset:400
	ds_read_b128 v[88:91], v44 offset:416
	ds_read_b128 v[92:95], v44 offset:432
	v_sub_f32_e32 v48, v48, v49
	v_fmamk_f32 v48, v48, 0x3d800000, v47
	s_waitcnt lgkmcnt(7)
	v_fma_f32 v49, v38, v96, v42
	v_fmac_f32_e32 v49, v39, v97
	v_fmac_f32_e32 v49, v40, v98
	v_fmac_f32_e32 v49, v41, v99
	s_waitcnt lgkmcnt(6)
	v_fmac_f32_e32 v49, v34, v100
	v_fmac_f32_e32 v49, v35, v101
	v_fmac_f32_e32 v49, v36, v102
	v_fmac_f32_e32 v49, v37, v103
	s_waitcnt lgkmcnt(5)
	v_fmac_f32_e32 v49, v30, v104
	v_fmac_f32_e32 v49, v31, v105
	v_fmac_f32_e32 v49, v32, v106
	v_fmac_f32_e32 v49, v33, v107
	s_waitcnt lgkmcnt(4)
	v_fmac_f32_e32 v49, v26, v108
	v_fmac_f32_e32 v49, v27, v109
	v_fmac_f32_e32 v49, v28, v110
	v_fmac_f32_e32 v49, v29, v111
	v_min_f32_e32 v50, 0, v49
	v_mul_f32_e64 v49, |v49|, s69
	v_exp_f32_e32 v49, v49
	s_nop 0
	v_add_f32_e32 v49, 1.0, v49
	v_cmp_gt_f32_e32 vcc, s60, v49
	s_nop 1
	v_cndmask_b32_e64 v51, 0, 32, vcc
	v_ldexp_f32 v49, v49, v51
	v_log_f32_e32 v49, v49
	s_nop 0
	v_mul_f32_e32 v51, 0x3f317217, v49
	v_fma_f32 v51, v49, s85, -v51
	v_fmac_f32_e32 v51, 0x3377d1cf, v49
	v_fmac_f32_e32 v51, 0x3f317217, v49
	v_cmp_lt_f32_e64 s[4:5], |v49|, s86
	s_nop 1
	v_cndmask_b32_e64 v49, v49, v51, s[4:5]
	v_cndmask_b32_e32 v51, 0, v64, vcc
	v_sub_f32_e32 v49, v49, v51
	v_sub_f32_e32 v49, v50, v49
	ds_read_b128 v[96:99], v44 offset:448
	ds_read_b128 v[100:103], v44 offset:464
	ds_read_b128 v[104:107], v44 offset:480
	ds_read_b128 v[108:111], v44 offset:496
	v_fmamk_f32 v49, v49, 0x3d800000, v48
	s_waitcnt lgkmcnt(7)
	v_fma_f32 v54, v38, v80, v42
	v_fmac_f32_e32 v54, v39, v81
	v_fmac_f32_e32 v54, v40, v82
	v_fmac_f32_e32 v54, v41, v83
	s_waitcnt lgkmcnt(6)
	v_fmac_f32_e32 v54, v34, v84
	v_fmac_f32_e32 v54, v35, v85
	v_fmac_f32_e32 v54, v36, v86
	v_fmac_f32_e32 v54, v37, v87
	s_waitcnt lgkmcnt(5)
	v_fmac_f32_e32 v54, v30, v88
	v_fmac_f32_e32 v54, v31, v89
	v_fmac_f32_e32 v54, v32, v90
	v_fmac_f32_e32 v54, v33, v91
	s_waitcnt lgkmcnt(4)
	v_fmac_f32_e32 v54, v26, v92
	v_fmac_f32_e32 v54, v27, v93
	v_fmac_f32_e32 v54, v28, v94
	v_fmac_f32_e32 v54, v29, v95
	v_mul_f32_e64 v51, |v54|, s69
	v_exp_f32_e32 v51, v51
	v_min_f32_e32 v50, 0, v54
	v_add_f32_e32 v51, 1.0, v51
	v_cmp_gt_f32_e32 vcc, s60, v51
	s_nop 1
	v_cndmask_b32_e64 v52, 0, 32, vcc
	v_ldexp_f32 v51, v51, v52
	v_log_f32_e32 v51, v51
	s_nop 0
	v_mul_f32_e32 v52, 0x3f317217, v51
	v_fma_f32 v52, v51, s85, -v52
	v_fmac_f32_e32 v52, 0x3377d1cf, v51
	v_fmac_f32_e32 v52, 0x3f317217, v51
	v_cmp_lt_f32_e64 s[4:5], |v51|, s86
	s_nop 1
	v_cndmask_b32_e64 v51, v51, v52, s[4:5]
	v_cndmask_b32_e32 v52, 0, v64, vcc
	v_sub_f32_e32 v51, v51, v52
	ds_read_b128 v[80:83], v44 offset:512
	ds_read_b128 v[84:87], v44 offset:528
	ds_read_b128 v[88:91], v44 offset:544
	ds_read_b128 v[92:95], v44 offset:560
	v_sub_f32_e32 v50, v50, v51
	v_fmamk_f32 v50, v50, 0x3d800000, v49
	s_waitcnt lgkmcnt(7)
	v_fma_f32 v51, v38, v96, v42
	v_fmac_f32_e32 v51, v39, v97
	v_fmac_f32_e32 v51, v40, v98
	v_fmac_f32_e32 v51, v41, v99
	s_waitcnt lgkmcnt(6)
	v_fmac_f32_e32 v51, v34, v100
	v_fmac_f32_e32 v51, v35, v101
	v_fmac_f32_e32 v51, v36, v102
	v_fmac_f32_e32 v51, v37, v103
	s_waitcnt lgkmcnt(5)
	v_fmac_f32_e32 v51, v30, v104
	v_fmac_f32_e32 v51, v31, v105
	v_fmac_f32_e32 v51, v32, v106
	v_fmac_f32_e32 v51, v33, v107
	s_waitcnt lgkmcnt(4)
	v_fmac_f32_e32 v51, v26, v108
	v_fmac_f32_e32 v51, v27, v109
	v_fmac_f32_e32 v51, v28, v110
	v_fmac_f32_e32 v51, v29, v111
	v_min_f32_e32 v52, 0, v51
	v_mul_f32_e64 v51, |v51|, s69
	v_exp_f32_e32 v51, v51
	s_nop 0
	v_add_f32_e32 v51, 1.0, v51
	v_cmp_gt_f32_e32 vcc, s60, v51
	s_nop 1
	v_cndmask_b32_e64 v53, 0, 32, vcc
	v_ldexp_f32 v51, v51, v53
	v_log_f32_e32 v51, v51
	s_nop 0
	v_mul_f32_e32 v53, 0x3f317217, v51
	v_fma_f32 v53, v51, s85, -v53
	v_fmac_f32_e32 v53, 0x3377d1cf, v51
	v_fmac_f32_e32 v53, 0x3f317217, v51
	v_cmp_lt_f32_e64 s[4:5], |v51|, s86
	s_nop 1
	v_cndmask_b32_e64 v51, v51, v53, s[4:5]
	v_cndmask_b32_e32 v53, 0, v64, vcc
	v_sub_f32_e32 v51, v51, v53
	v_sub_f32_e32 v51, v52, v51
	ds_read_b128 v[96:99], v44 offset:576
	ds_read_b128 v[100:103], v44 offset:592
	ds_read_b128 v[104:107], v44 offset:608
	ds_read_b128 v[108:111], v44 offset:624
	v_fmamk_f32 v51, v51, 0x3d800000, v50
	s_waitcnt lgkmcnt(7)
	v_fma_f32 v56, v38, v80, v42
	v_fmac_f32_e32 v56, v39, v81
	v_fmac_f32_e32 v56, v40, v82
	v_fmac_f32_e32 v56, v41, v83
	s_waitcnt lgkmcnt(6)
	v_fmac_f32_e32 v56, v34, v84
	v_fmac_f32_e32 v56, v35, v85
	v_fmac_f32_e32 v56, v36, v86
	v_fmac_f32_e32 v56, v37, v87
	s_waitcnt lgkmcnt(5)
	v_fmac_f32_e32 v56, v30, v88
	v_fmac_f32_e32 v56, v31, v89
	v_fmac_f32_e32 v56, v32, v90
	v_fmac_f32_e32 v56, v33, v91
	s_waitcnt lgkmcnt(4)
; DEVI float logsig_f(float z) { return fminf(z, 0.f) - __logf(1.f + __expf(-fabsf(z))); }
; DEVI void gla_local_item(const Params& p, int l, int item) {
;     ...
; #pragma unroll
;     for (int ii = 0; ii < 16; ++ii) {
;       const float* ar = alr_s + (grp * 16 + ii) * 16;
;       float z = bias;
; #pragma unroll
;       for (int r = 0; r < 16; ++r) z += ar[r] * wv[r];
;       run += logsig_f(z) * (1.f / 16.f);
;       bloc[ii] = run;
;     }
	v_fmac_f32_e32 v56, v26, v92
	v_fmac_f32_e32 v56, v27, v93
	v_fmac_f32_e32 v56, v28, v94
	v_fmac_f32_e32 v56, v29, v95
	v_mul_f32_e64 v53, |v56|, s69
	v_exp_f32_e32 v53, v53
	v_min_f32_e32 v52, 0, v56
	v_add_f32_e32 v53, 1.0, v53
	v_cmp_gt_f32_e32 vcc, s60, v53
	s_nop 1
	v_cndmask_b32_e64 v54, 0, 32, vcc
	v_ldexp_f32 v53, v53, v54
	v_log_f32_e32 v53, v53
	s_nop 0
	v_mul_f32_e32 v54, 0x3f317217, v53
	v_fma_f32 v54, v53, s85, -v54
	v_fmac_f32_e32 v54, 0x3377d1cf, v53
	v_fmac_f32_e32 v54, 0x3f317217, v53
	v_cmp_lt_f32_e64 s[4:5], |v53|, s86
	s_nop 1
	v_cndmask_b32_e64 v53, v53, v54, s[4:5]
	v_cndmask_b32_e32 v54, 0, v64, vcc
	v_sub_f32_e32 v53, v53, v54
	ds_read_b128 v[80:83], v44 offset:640
	ds_read_b128 v[84:87], v44 offset:656
	ds_read_b128 v[88:91], v44 offset:672
	ds_read_b128 v[92:95], v44 offset:688
	v_sub_f32_e32 v52, v52, v53
	v_fmamk_f32 v52, v52, 0x3d800000, v51
	s_waitcnt lgkmcnt(7)
	v_fma_f32 v53, v38, v96, v42
	v_fmac_f32_e32 v53, v39, v97
	v_fmac_f32_e32 v53, v40, v98
	v_fmac_f32_e32 v53, v41, v99
	s_waitcnt lgkmcnt(6)
	v_fmac_f32_e32 v53, v34, v100
	v_fmac_f32_e32 v53, v35, v101
	v_fmac_f32_e32 v53, v36, v102
	v_fmac_f32_e32 v53, v37, v103
	s_waitcnt lgkmcnt(5)
	v_fmac_f32_e32 v53, v30, v104
	v_fmac_f32_e32 v53, v31, v105
	v_fmac_f32_e32 v53, v32, v106
	v_fmac_f32_e32 v53, v33, v107
	s_waitcnt lgkmcnt(4)
	v_fmac_f32_e32 v53, v26, v108
	v_fmac_f32_e32 v53, v27, v109
	v_fmac_f32_e32 v53, v28, v110
	v_fmac_f32_e32 v53, v29, v111
	v_min_f32_e32 v54, 0, v53
	v_mul_f32_e64 v53, |v53|, s69
	v_exp_f32_e32 v53, v53
	s_nop 0
	v_add_f32_e32 v53, 1.0, v53
	v_cmp_gt_f32_e32 vcc, s60, v53
	s_nop 1
	v_cndmask_b32_e64 v55, 0, 32, vcc
	v_ldexp_f32 v53, v53, v55
	v_log_f32_e32 v53, v53
	s_nop 0
	v_mul_f32_e32 v55, 0x3f317217, v53
	v_fma_f32 v55, v53, s85, -v55
	v_fmac_f32_e32 v55, 0x3377d1cf, v53
	v_fmac_f32_e32 v55, 0x3f317217, v53
	v_cmp_lt_f32_e64 s[4:5], |v53|, s86
	s_nop 1
	v_cndmask_b32_e64 v53, v53, v55, s[4:5]
	v_cndmask_b32_e32 v55, 0, v64, vcc
	v_sub_f32_e32 v53, v53, v55
	v_sub_f32_e32 v53, v54, v53
	ds_read_b128 v[96:99], v44 offset:704
	ds_read_b128 v[100:103], v44 offset:720
	ds_read_b128 v[104:107], v44 offset:736
	ds_read_b128 v[108:111], v44 offset:752
	v_fmamk_f32 v53, v53, 0x3d800000, v52
	s_waitcnt lgkmcnt(7)
	v_fma_f32 v58, v38, v80, v42
	v_fmac_f32_e32 v58, v39, v81
	v_fmac_f32_e32 v58, v40, v82
	v_fmac_f32_e32 v58, v41, v83
	s_waitcnt lgkmcnt(6)
	v_fmac_f32_e32 v58, v34, v84
	v_fmac_f32_e32 v58, v35, v85
	v_fmac_f32_e32 v58, v36, v86
	v_fmac_f32_e32 v58, v37, v87
	s_waitcnt lgkmcnt(5)
	v_fmac_f32_e32 v58, v30, v88
	v_fmac_f32_e32 v58, v31, v89
	v_fmac_f32_e32 v58, v32, v90
	v_fmac_f32_e32 v58, v33, v91
	s_waitcnt lgkmcnt(4)
	v_fmac_f32_e32 v58, v26, v92
	v_fmac_f32_e32 v58, v27, v93
	v_fmac_f32_e32 v58, v28, v94
	v_fmac_f32_e32 v58, v29, v95
	v_mul_f32_e64 v55, |v58|, s69
	v_exp_f32_e32 v55, v55
	v_min_f32_e32 v54, 0, v58
	v_add_f32_e32 v55, 1.0, v55
	v_cmp_gt_f32_e32 vcc, s60, v55
	s_nop 1
	v_cndmask_b32_e64 v56, 0, 32, vcc
	v_ldexp_f32 v55, v55, v56
	v_log_f32_e32 v55, v55
	s_nop 0
	v_mul_f32_e32 v56, 0x3f317217, v55
	v_fma_f32 v56, v55, s85, -v56
	v_fmac_f32_e32 v56, 0x3377d1cf, v55
	v_fmac_f32_e32 v56, 0x3f317217, v55
	v_cmp_lt_f32_e64 s[4:5], |v55|, s86
	s_nop 1
	v_cndmask_b32_e64 v55, v55, v56, s[4:5]
	v_cndmask_b32_e32 v56, 0, v64, vcc
	v_sub_f32_e32 v55, v55, v56
	ds_read_b128 v[80:83], v44 offset:768
	ds_read_b128 v[84:87], v44 offset:784
	ds_read_b128 v[88:91], v44 offset:800
	ds_read_b128 v[92:95], v44 offset:816
	v_sub_f32_e32 v54, v54, v55
	v_fmamk_f32 v54, v54, 0x3d800000, v53
	s_waitcnt lgkmcnt(7)
	v_fma_f32 v55, v38, v96, v42
	v_fmac_f32_e32 v55, v39, v97
	v_fmac_f32_e32 v55, v40, v98
	v_fmac_f32_e32 v55, v41, v99
	s_waitcnt lgkmcnt(6)
	v_fmac_f32_e32 v55, v34, v100
	v_fmac_f32_e32 v55, v35, v101
	v_fmac_f32_e32 v55, v36, v102
	v_fmac_f32_e32 v55, v37, v103
	s_waitcnt lgkmcnt(5)
	v_fmac_f32_e32 v55, v30, v104
	v_fmac_f32_e32 v55, v31, v105
	v_fmac_f32_e32 v55, v32, v106
	v_fmac_f32_e32 v55, v33, v107
	s_waitcnt lgkmcnt(4)
	v_fmac_f32_e32 v55, v26, v108
	v_fmac_f32_e32 v55, v27, v109
	v_fmac_f32_e32 v55, v28, v110
	v_fmac_f32_e32 v55, v29, v111
	v_min_f32_e32 v56, 0, v55
	v_mul_f32_e64 v55, |v55|, s69
	v_exp_f32_e32 v55, v55
	s_nop 0
	v_add_f32_e32 v55, 1.0, v55
	v_cmp_gt_f32_e32 vcc, s60, v55
	s_nop 1
	v_cndmask_b32_e64 v57, 0, 32, vcc
	v_ldexp_f32 v55, v55, v57
	v_log_f32_e32 v55, v55
	s_nop 0
	v_mul_f32_e32 v57, 0x3f317217, v55
	v_fma_f32 v57, v55, s85, -v57
	v_fmac_f32_e32 v57, 0x3377d1cf, v55
	v_fmac_f32_e32 v57, 0x3f317217, v55
	v_cmp_lt_f32_e64 s[4:5], |v55|, s86
	s_nop 1
	v_cndmask_b32_e64 v55, v55, v57, s[4:5]
	v_cndmask_b32_e32 v57, 0, v64, vcc
	v_sub_f32_e32 v55, v55, v57
	v_sub_f32_e32 v55, v56, v55
	ds_read_b128 v[96:99], v44 offset:832
	ds_read_b128 v[100:103], v44 offset:848
	ds_read_b128 v[104:107], v44 offset:864
	ds_read_b128 v[108:111], v44 offset:880
	v_fmamk_f32 v55, v55, 0x3d800000, v54
	s_waitcnt lgkmcnt(7)
	v_fma_f32 v60, v38, v80, v42
	v_fmac_f32_e32 v60, v39, v81
	v_fmac_f32_e32 v60, v40, v82
	v_fmac_f32_e32 v60, v41, v83
	s_waitcnt lgkmcnt(6)
; DEVI float logsig_f(float z) { return fminf(z, 0.f) - __logf(1.f + __expf(-fabsf(z))); }
; DEVI void gla_local_item(const Params& p, int l, int item) {
;     ...
; #pragma unroll
;     for (int ii = 0; ii < 16; ++ii) {
;       const float* ar = alr_s + (grp * 16 + ii) * 16;
;       float z = bias;
; #pragma unroll
;       for (int r = 0; r < 16; ++r) z += ar[r] * wv[r];
;       run += logsig_f(z) * (1.f / 16.f);
;       bloc[ii] = run;
;     }
;     gt[grp * 128 + d] = run;
;     __syncthreads();
;     float off = 0.f;
;     for (int g2 = 0; g2 < grp; ++g2) off += gt[g2 * 128 + d];
	v_fmac_f32_e32 v60, v34, v84
	v_fmac_f32_e32 v60, v35, v85
	v_fmac_f32_e32 v60, v36, v86
	v_fmac_f32_e32 v60, v37, v87
	s_waitcnt lgkmcnt(5)
	v_fmac_f32_e32 v60, v30, v88
	v_fmac_f32_e32 v60, v31, v89
	v_fmac_f32_e32 v60, v32, v90
	v_fmac_f32_e32 v60, v33, v91
	s_waitcnt lgkmcnt(4)
	v_fmac_f32_e32 v60, v26, v92
	v_fmac_f32_e32 v60, v27, v93
	v_fmac_f32_e32 v60, v28, v94
	v_fmac_f32_e32 v60, v29, v95
	v_mul_f32_e64 v57, |v60|, s69
	v_exp_f32_e32 v57, v57
	v_min_f32_e32 v56, 0, v60
	v_add_f32_e32 v57, 1.0, v57
	v_cmp_gt_f32_e32 vcc, s60, v57
	s_nop 1
	v_cndmask_b32_e64 v58, 0, 32, vcc
	v_ldexp_f32 v57, v57, v58
	v_log_f32_e32 v57, v57
	s_nop 0
	v_mul_f32_e32 v58, 0x3f317217, v57
	v_fma_f32 v58, v57, s85, -v58
	v_fmac_f32_e32 v58, 0x3377d1cf, v57
	v_fmac_f32_e32 v58, 0x3f317217, v57
	v_cmp_lt_f32_e64 s[4:5], |v57|, s86
	s_nop 1
	v_cndmask_b32_e64 v57, v57, v58, s[4:5]
	v_cndmask_b32_e32 v58, 0, v64, vcc
	v_sub_f32_e32 v57, v57, v58
	ds_read_b128 v[80:83], v44 offset:896
	ds_read_b128 v[84:87], v44 offset:912
	ds_read_b128 v[88:91], v44 offset:928
	ds_read_b128 v[92:95], v44 offset:944
	v_sub_f32_e32 v56, v56, v57
	v_fmamk_f32 v56, v56, 0x3d800000, v55
	s_waitcnt lgkmcnt(7)
	v_fma_f32 v57, v38, v96, v42
	v_fmac_f32_e32 v57, v39, v97
	v_fmac_f32_e32 v57, v40, v98
	v_fmac_f32_e32 v57, v41, v99
	s_waitcnt lgkmcnt(6)
	v_fmac_f32_e32 v57, v34, v100
	v_fmac_f32_e32 v57, v35, v101
	v_fmac_f32_e32 v57, v36, v102
	v_fmac_f32_e32 v57, v37, v103
	s_waitcnt lgkmcnt(5)
	v_fmac_f32_e32 v57, v30, v104
	v_fmac_f32_e32 v57, v31, v105
	v_fmac_f32_e32 v57, v32, v106
	v_fmac_f32_e32 v57, v33, v107
	s_waitcnt lgkmcnt(4)
	v_fmac_f32_e32 v57, v26, v108
	v_fmac_f32_e32 v57, v27, v109
	v_fmac_f32_e32 v57, v28, v110
	v_fmac_f32_e32 v57, v29, v111
	v_min_f32_e32 v58, 0, v57
	v_mul_f32_e64 v57, |v57|, s69
	v_exp_f32_e32 v57, v57
	s_nop 0
	v_add_f32_e32 v57, 1.0, v57
	v_cmp_gt_f32_e32 vcc, s60, v57
	s_nop 1
	v_cndmask_b32_e64 v59, 0, 32, vcc
	v_ldexp_f32 v57, v57, v59
	v_log_f32_e32 v57, v57
	s_nop 0
	v_mul_f32_e32 v59, 0x3f317217, v57
	v_fma_f32 v59, v57, s85, -v59
	v_fmac_f32_e32 v59, 0x3377d1cf, v57
	v_fmac_f32_e32 v59, 0x3f317217, v57
	v_cmp_lt_f32_e64 s[4:5], |v57|, s86
	s_nop 1
	v_cndmask_b32_e64 v57, v57, v59, s[4:5]
	v_cndmask_b32_e32 v59, 0, v64, vcc
	v_sub_f32_e32 v57, v57, v59
	v_sub_f32_e32 v57, v58, v57
	ds_read_b128 v[96:99], v44 offset:960
	ds_read_b128 v[100:103], v44 offset:976
	ds_read_b128 v[104:107], v44 offset:992
	ds_read_b128 v[108:111], v44 offset:1008
	v_fmamk_f32 v57, v57, 0x3d800000, v56
	s_waitcnt lgkmcnt(7)
	v_fma_f32 v62, v38, v80, v42
	v_fmac_f32_e32 v62, v39, v81
	v_fmac_f32_e32 v62, v40, v82
	v_fmac_f32_e32 v62, v41, v83
	s_waitcnt lgkmcnt(6)
	v_fmac_f32_e32 v62, v34, v84
	v_fmac_f32_e32 v62, v35, v85
	v_fmac_f32_e32 v62, v36, v86
	v_fmac_f32_e32 v62, v37, v87
	s_waitcnt lgkmcnt(5)
	v_fmac_f32_e32 v62, v30, v88
	v_fmac_f32_e32 v62, v31, v89
	v_fmac_f32_e32 v62, v32, v90
	v_fmac_f32_e32 v62, v33, v91
	s_waitcnt lgkmcnt(4)
	v_fmac_f32_e32 v62, v26, v92
	v_fmac_f32_e32 v62, v27, v93
	v_fmac_f32_e32 v62, v28, v94
	v_fmac_f32_e32 v62, v29, v95
	v_mul_f32_e64 v59, |v62|, s69
	v_exp_f32_e32 v59, v59
	v_min_f32_e32 v58, 0, v62
	v_add_f32_e32 v59, 1.0, v59
	v_cmp_gt_f32_e32 vcc, s60, v59
	s_nop 1
	v_cndmask_b32_e64 v60, 0, 32, vcc
	v_ldexp_f32 v59, v59, v60
	v_log_f32_e32 v59, v59
	s_nop 0
	v_mul_f32_e32 v60, 0x3f317217, v59
	v_fma_f32 v60, v59, s85, -v60
	v_fmac_f32_e32 v60, 0x3377d1cf, v59
	v_fmac_f32_e32 v60, 0x3f317217, v59
	v_cmp_lt_f32_e64 s[4:5], |v59|, s86
	s_nop 1
	v_cndmask_b32_e64 v59, v59, v60, s[4:5]
	v_cndmask_b32_e32 v60, 0, v64, vcc
	v_sub_f32_e32 v59, v59, v60
	v_sub_f32_e32 v58, v58, v59
	v_fmamk_f32 v58, v58, 0x3d800000, v57
	s_waitcnt lgkmcnt(3)
	v_fmac_f32_e32 v42, v38, v96
	v_fmac_f32_e32 v42, v39, v97
	v_fmac_f32_e32 v42, v40, v98
	v_fmac_f32_e32 v42, v41, v99
	s_waitcnt lgkmcnt(2)
	v_fmac_f32_e32 v42, v34, v100
	v_fmac_f32_e32 v42, v35, v101
	v_fmac_f32_e32 v42, v36, v102
	v_fmac_f32_e32 v42, v37, v103
	s_waitcnt lgkmcnt(1)
	v_fmac_f32_e32 v42, v30, v104
	v_fmac_f32_e32 v42, v31, v105
	v_fmac_f32_e32 v42, v32, v106
	v_fmac_f32_e32 v42, v33, v107
	s_waitcnt lgkmcnt(0)
	v_fmac_f32_e32 v42, v26, v108
	v_fmac_f32_e32 v42, v27, v109
	v_fmac_f32_e32 v42, v28, v110
	v_fmac_f32_e32 v42, v29, v111
	v_mul_f32_e64 v27, |v42|, s69
	v_exp_f32_e32 v27, v27
	v_min_f32_e32 v26, 0, v42
	v_add_f32_e32 v27, 1.0, v27
	v_cmp_gt_f32_e32 vcc, s60, v27
	s_nop 1
	v_cndmask_b32_e64 v28, 0, 32, vcc
	v_ldexp_f32 v27, v27, v28
	v_log_f32_e32 v27, v27
	s_nop 0
	v_mul_f32_e32 v28, 0x3f317217, v27
	v_fma_f32 v28, v27, s85, -v28
	v_fmac_f32_e32 v28, 0x3377d1cf, v27
	v_fmac_f32_e32 v28, 0x3f317217, v27
	v_cmp_lt_f32_e64 s[4:5], |v27|, s86
	s_nop 1
	v_cndmask_b32_e64 v27, v27, v28, s[4:5]
	v_cndmask_b32_e32 v28, 0, v64, vcc
	v_sub_f32_e32 v27, v27, v28
	v_sub_f32_e32 v26, v26, v27
	v_fmamk_f32 v26, v26, 0x3d800000, v58
	v_cmp_lt_u32_e32 vcc, s81, v22
	v_mov_b32_e32 v27, 0
	ds_write_b32 v17, v26 offset:36864
	s_waitcnt lgkmcnt(0)
	s_barrier
	s_and_saveexec_b64 s[2:3], vcc
	s_cbranch_execz .LBB0_738
	v_readlane_b32 s4, v253, 55
	v_mov_b32_e32 v27, 0
	s_nop 0
	v_lshl_add_u32 v17, v20, 2, s4
	s_mov_b64 s[4:5], 0
	v_mov_b32_e32 v20, v21

; DEVI unsigned pk2bf(float a, float b) { hf2 v = {a, b}; hbf2 r = __builtin_convertvector(v, hbf2); return __builtin_bit_cast(unsigned, r); }
; #define WAIT_V(n) asm volatile("s_waitcnt vmcnt(" #n ")" ::: "memory")
; #define BAR __builtin_amdgcn_s_barrier()
; #define SCHED __builtin_amdgcn_sched_barrier(0)
;     ...
;   STAGE(SB(1, 0), Bt, bcol, 1); STAGE(SA(1, 0), A, brow, 1); STAGE(SB(1, 1), Bt, bcol + HALF, 1);
;   WAIT_V(6); BAR;
;   for (int t = 0; t < nt - 2; t += 2) {
;     LDB(B0, 0, 0); SCHED; LDA(At, 0, 0); STAGE(SA(1, 1), A, brow + HALF, t + 1);
; DEVI void phase_g1(const Params& p, int l) {
;     ...
;     {
;       int tide = tid_;
;       asm volatile("" : "+v"(tide));
;       const int wid = tide >> 6, lane = tide & 63, wr = wid >> 2, wc = wid & 3, fr = lane & 15, fq = lane >> 4;
;       typedef __attribute__((ext_vector_type(2))) unsigned u32x2;
;       typedef __attribute__((ext_vector_type(4))) unsigned u32x4;
; #pragma unroll
;       for (int ai = 0; ai < 2; ++ai)
; #pragma unroll
;         for (int bj = 0; bj < 2; ++bj)
; #pragma unroll
;           for (int m = 0; m < 4; ++m) {
;             const f32x4 v0 = acc[ai][bj][m][0], v1 = acc[ai][bj][m][1];
;             const unsigned x0 = pk2bf(v0[0], v0[1]), x1 = pk2bf(v0[2], v0[3]);
;             const unsigned y0 = pk2bf(v1[0], v1[1]), y1 = pk2bf(v1[2], v1[3]);
;             const u32x2 s0 = __builtin_amdgcn_permlane16_swap(x0, y0, false, false);
;             const u32x2 s1 = __builtin_amdgcn_permlane16_swap(x1, y1, false, false);
;             const int feat = brow + ai * 128 + wr * 64 + m * 16 + (fq >> 1) * 8;
;             const int tok = bcol + bj * 128 + wc * 32 + (fq & 1) * 16 + fr;
;             const u32x4 o = {s0[0], s1[0], s0[1], s1[1]};
;             *(u32x4*)(p.proj + (long)tok * NP + feat) = o;
;           }
;     }
;     pre = hn; have = hn; pm = npm; pn = npn;
.LBB0_764:
	s_or_b64 exec, exec, s[10:11]
	s_andn2_b64 vcc, exec, s[6:7]
	s_cbranch_vccz .Lmy_g1_nostage
	v_lshrrev_b32_e32 v110, 3, v234
	v_bfe_u32 v111, v234, 2, 4
	v_lshlrev_b32_e32 v112, 4, v234
	v_and_b32_e32 v113, 32, v234
	v_and_or_b32 v110, v110, 48, v111
	v_bitop3_b32 v113, v112, v113, 48 bitop3:0x6c
	v_and_b32_e32 v111, 64, v234
	v_lshlrev_b32_e32 v110, 12, v110
	v_or3_b32 v108, v111, v113, v110
	v_or_b32_e32 v109, 0x40000, v108
	s_lshl_b32 s21, s18, 20
	s_lshl_b32 s22, s17, 20
	s_mov_b32 s10, s90
	s_mov_b32 s11, s91
	v_readfirstlane_b32 s24, v112
	s_or_b32 s23, s21, 0x80
	s_add_i32 s25, s24, s1
	s_mov_b32 m0, s25
	s_nop 0
	buffer_load_dwordx4 v108, s[88:91], s23 offen lds
	s_add_i32 s25, s25, 0x2000
	s_mov_b32 m0, s25
	s_nop 0
	buffer_load_dwordx4 v109, s[88:91], s23 offen lds
	s_or_b32 s23, s22, 0x80
	s_add_i32 s25, s24, 0x8000
	s_mov_b32 m0, s25
	s_nop 0
	buffer_load_dwordx4 v108, s[8:11], s23 offen lds
	s_add_i32 s25, s25, 0x2000
	s_mov_b32 m0, s25
	s_nop 0
	buffer_load_dwordx4 v109, s[8:11], s23 offen lds
	s_or_b32 s23, s21, 0x80080
	s_add_i32 s25, s24, s96
	s_mov_b32 m0, s25
	s_nop 0
	buffer_load_dwordx4 v108, s[88:91], s23 offen lds
	s_add_i32 s25, s25, 0x2000
	s_mov_b32 m0, s25
	s_nop 0
	buffer_load_dwordx4 v109, s[88:91], s23 offen lds
	s_or_b32 s23, s22, 0x80080
	s_add_i32 s25, s24, 0xc000
	s_mov_b32 m0, s25
	s_nop 0
	buffer_load_dwordx4 v108, s[8:11], s23 offen lds
	s_add_i32 s25, s25, 0x2000
	s_mov_b32 m0, s25
	s_nop 0
	buffer_load_dwordx4 v109, s[8:11], s23 offen lds
.Lmy_g1_nostage:
	v_mov_b32_e32 v96, v200
	s_lshl_b32 s4, s20, 8
	v_ashrrev_i32_e32 v97, 2, v96
	v_and_b32_e32 v97, 0xffffffc0, v97
	v_lshl_add_u32 v97, s19, 8, v97
	v_lshrrev_b32_e32 v98, 2, v96
	v_and_or_b32 v100, v98, 8, v97
	v_lshrrev_b32_e32 v97, 1, v96
	v_and_b32_e32 v97, 0x60, v97
	v_and_b32_e32 v96, 31, v96
	v_or3_b32 v106, v96, v97, s4
	v_mov_b64_e32 v[102:103], s[92:93]
	v_ashrrev_i32_e32 v101, 31, v100
	v_cvt_pk_bf16_f32 v96, v184, v185
	v_cvt_pk_bf16_f32 v97, v186, v187
	v_cvt_pk_bf16_f32 v98, v188, v189
	v_cvt_pk_bf16_f32 v99, v190, v191
	v_mad_i64_i32 v[104:105], s[4:5], v106, s97, v[102:103]
	v_lshlrev_b64 v[100:101], 1, v[100:101]
	v_cvt_pk_bf16_f32 v80, v80, v81
	v_cvt_pk_bf16_f32 v81, v82, v83
	v_cvt_pk_bf16_f32 v82, v84, v85
	v_cvt_pk_bf16_f32 v83, v86, v87
	v_permlane16_swap_b32_e32 v96, v98
	v_permlane16_swap_b32_e32 v97, v99
	v_lshl_add_u64 v[104:105], v[104:105], 0, v[100:101]
	v_permlane16_swap_b32_e32 v80, v82
	v_permlane16_swap_b32_e32 v81, v83
	v_or_b32_e32 v84, 0x80, v106
	global_store_dwordx4 v[104:105], v[96:99], off
	global_store_dwordx4 v[104:105], v[80:83], off offset:96
	v_mad_i64_i32 v[84:85], s[4:5], v84, s97, v[102:103]
	v_cvt_pk_bf16_f32 v96, v160, v161
	v_cvt_pk_bf16_f32 v97, v162, v163
	v_cvt_pk_bf16_f32 v98, v164, v165
	v_cvt_pk_bf16_f32 v99, v166, v167
	v_cvt_pk_bf16_f32 v80, v152, v153
	v_cvt_pk_bf16_f32 v81, v154, v155
	v_cvt_pk_bf16_f32 v82, v156, v157
	v_cvt_pk_bf16_f32 v83, v158, v159
	v_cvt_pk_bf16_f32 v56, v56, v57
	v_cvt_pk_bf16_f32 v57, v58, v59
	v_cvt_pk_bf16_f32 v58, v60, v61
	v_cvt_pk_bf16_f32 v59, v62, v63
	v_permlane16_swap_b32_e32 v96, v98
	v_permlane16_swap_b32_e32 v97, v99
	v_permlane16_swap_b32_e32 v80, v82
	v_permlane16_swap_b32_e32 v81, v83
	v_lshl_add_u64 v[84:85], v[84:85], 0, v[100:101]
	v_permlane16_swap_b32_e32 v56, v58
	v_permlane16_swap_b32_e32 v57, v59
	global_store_dwordx4 v[104:105], v[96:99], off offset:32
	global_store_dwordx4 v[84:85], v[80:83], off
	v_cvt_pk_bf16_f32 v72, v72, v73
	v_cvt_pk_bf16_f32 v96, v144, v145
	v_cvt_pk_bf16_f32 v97, v146, v147
	v_cvt_pk_bf16_f32 v98, v148, v149
	v_cvt_pk_bf16_f32 v99, v150, v151
	v_cvt_pk_bf16_f32 v80, v88, v89
	v_cvt_pk_bf16_f32 v81, v90, v91
	v_cvt_pk_bf16_f32 v82, v92, v93
	v_cvt_pk_bf16_f32 v83, v94, v95
	v_cvt_pk_bf16_f32 v73, v74, v75
	v_cvt_pk_bf16_f32 v74, v76, v77
	v_cvt_pk_bf16_f32 v75, v78, v79
	global_store_dwordx4 v[84:85], v[56:59], off offset:96
	v_cvt_pk_bf16_f32 v48, v48, v49
	v_cvt_pk_bf16_f32 v49, v50, v51
	v_cvt_pk_bf16_f32 v56, v64, v65
	v_cvt_pk_bf16_f32 v57, v66, v67
	v_cvt_pk_bf16_f32 v58, v68, v69
	v_cvt_pk_bf16_f32 v59, v70, v71
	v_cvt_pk_bf16_f32 v50, v52, v53
	v_cvt_pk_bf16_f32 v51, v54, v55
	v_cvt_pk_bf16_f32 v40, v40, v41
	v_cvt_pk_bf16_f32 v41, v42, v43
	v_cvt_pk_bf16_f32 v42, v44, v45
	v_cvt_pk_bf16_f32 v43, v46, v47
	v_cvt_pk_bf16_f32 v32, v32, v33
	v_cvt_pk_bf16_f32 v33, v34, v35
	v_cvt_pk_bf16_f32 v34, v36, v37
	v_cvt_pk_bf16_f32 v35, v38, v39
	v_cvt_pk_bf16_f32 v24, v24, v25
	v_cvt_pk_bf16_f32 v25, v26, v27
	v_cvt_pk_bf16_f32 v26, v28, v29
	v_cvt_pk_bf16_f32 v27, v30, v31
	v_cvt_pk_bf16_f32 v16, v16, v17
	v_cvt_pk_bf16_f32 v17, v18, v19
	v_cvt_pk_bf16_f32 v18, v20, v21
	v_cvt_pk_bf16_f32 v19, v22, v23
	v_cvt_pk_bf16_f32 v8, v8, v9
	v_cvt_pk_bf16_f32 v9, v10, v11
	v_cvt_pk_bf16_f32 v10, v12, v13
	v_cvt_pk_bf16_f32 v11, v14, v15
	v_cvt_pk_bf16_f32 v0, v0, v1
	v_cvt_pk_bf16_f32 v1, v2, v3
	v_cvt_pk_bf16_f32 v2, v4, v5
	v_cvt_pk_bf16_f32 v3, v6, v7
	v_permlane16_swap_b32_e32 v96, v98
	v_permlane16_swap_b32_e32 v97, v99
	v_permlane16_swap_b32_e32 v80, v82
	v_permlane16_swap_b32_e32 v81, v83
	v_permlane16_swap_b32_e32 v72, v74
	v_permlane16_swap_b32_e32 v73, v75
	v_permlane16_swap_b32_e32 v56, v58
	v_permlane16_swap_b32_e32 v57, v59
	v_permlane16_swap_b32_e32 v48, v50
	v_permlane16_swap_b32_e32 v49, v51
	v_permlane16_swap_b32_e32 v40, v42
	v_permlane16_swap_b32_e32 v41, v43
	v_permlane16_swap_b32_e32 v32, v34
	v_permlane16_swap_b32_e32 v33, v35
	v_permlane16_swap_b32_e32 v24, v26
	v_permlane16_swap_b32_e32 v25, v27
	v_permlane16_swap_b32_e32 v16, v18
	v_permlane16_swap_b32_e32 v17, v19
	v_permlane16_swap_b32_e32 v8, v10
	v_permlane16_swap_b32_e32 v9, v11
	v_permlane16_swap_b32_e32 v0, v2
	v_permlane16_swap_b32_e32 v1, v3
	s_mov_b64 s[4:5], -1
	s_andn2_b64 vcc, exec, s[6:7]
	s_mov_b32 s20, s18
	s_mov_b32 s19, s17
	global_store_dwordx4 v[104:105], v[96:99], off offset:64
	global_store_dwordx4 v[84:85], v[80:83], off offset:32
	global_store_dwordx4 v[84:85], v[72:75], off offset:64
	global_store_dwordx4 v[104:105], v[56:59], off offset:256
	global_store_dwordx4 v[104:105], v[48:51], off offset:288
	global_store_dwordx4 v[104:105], v[40:43], off offset:320
	global_store_dwordx4 v[104:105], v[32:35], off offset:352
	global_store_dwordx4 v[84:85], v[24:27], off offset:256
	global_store_dwordx4 v[84:85], v[16:19], off offset:288
	global_store_dwordx4 v[84:85], v[8:11], off offset:320
	global_store_dwordx4 v[84:85], v[0:3], off offset:352
	s_cbranch_vccz .LBB0_790

;   const int tid_ = get_tid();
;   const __amdgpu_buffer_rsrc_t A = __builtin_amdgcn_make_buffer_rsrc((void*)Ap, (short)0, 0x7fffffff, 0x00020000);
;   const __amdgpu_buffer_rsrc_t Bt = __builtin_amdgcn_make_buffer_rsrc((void*)Btp, (short)0, 0x7fffffff, 0x00020000);
;   int voff0, voff1;
;   { int r_, c_; stage_rc(tid_ * 16, r_, c_); voff0 = (r_ * K + c_) * 2; stage_rc(tid_ * 16 + 8192, r_, c_); voff1 = (r_ * K + c_) * 2; }
;   const int wid = tid_ >> 6, lane = tid_ & 63, wr = wid >> 2, wc = wid & 3, fr = lane & 15, fq = lane >> 4;
.LBB0_772:
	v_mov_b32_e32 v0, v234
	s_xor_b64 s[6:7], s[4:5], -1
	s_cmp_lg_u64 s[4:5], 0
	s_cselect_b32 s29, 1, 0
	v_lshrrev_b32_e32 v3, 3, v0
	v_bfe_u32 v4, v0, 2, 4
	v_lshlrev_b32_e32 v1, 4, v0
	v_and_b32_e32 v2, 32, v0
	v_and_or_b32 v3, v3, 48, v4
	v_bitop3_b32 v2, v1, v2, 48 bitop3:0x6c
	v_and_b32_e32 v4, 64, v0
	v_lshlrev_b32_e32 v3, 12, v3
	v_or3_b32 v161, v4, v2, v3
	v_add_u32_e32 v166, 0, v1
	v_or_b32_e32 v160, 0x40000, v161
	s_andn2_b64 vcc, exec, s[6:7]
	v_add_u32_e32 v167, s33, v1
	v_add_u32_e32 v165, 0x2000, v166
	v_add_u32_e32 v164, s0, v1
	v_add_u32_e32 v163, 0x4000, v166
	v_add_u32_e32 v162, 0x6000, v166
	s_cbranch_vccz .LBB0_787
	v_cmp_gt_u32_e64 s[4:5], s56, v0
	v_cmp_lt_u32_e32 vcc, s80, v0
	s_and_saveexec_b64 s[10:11], vcc
	s_cbranch_execnz .LBB0_788

; #define WAIT_V(n) asm volatile("s_waitcnt vmcnt(" #n ")" ::: "memory")
; #define BAR __builtin_amdgcn_s_barrier()
;     ...
;         for (int n = 0; n < 2; ++n) acc[a][b][m][n] = f32x4{0.f, 0.f, 0.f, 0.f};
;   if (!pre) {
;     STAGE(SB(0, 0), Bt, bcol, 0); STAGE(SA(0, 0), A, brow, 0);
;     STAGE(SB(0, 1), Bt, bcol + HALF, 0); STAGE(SA(0, 1), A, brow + HALF, 0);
;   }
;   if (wr == 1) BAR;
;   if (pre) { WAIT_V(20); } else { WAIT_V(4); }
;   BAR;
;   STAGE(SB(1, 0), Bt, bcol, 1); STAGE(SA(1, 0), A, brow, 1); STAGE(SB(1, 1), Bt, bcol + HALF, 1);
;   WAIT_V(6); BAR;
.LBB0_776:
	s_waitcnt vmcnt(28)
.LBB0_777:
	v_add_u32_e32 v128, s1, v1
	s_lshl_b32 s21, s20, 20
	v_add_u32_e32 v130, 0x2000, v128
	v_add_u32_e32 v131, 0x8000, v166
	s_lshl_b32 s22, s19, 20
	v_add_u32_e32 v132, 0xa000, v166
	v_add_u32_e32 v133, s96, v1
	v_add_u32_e32 v134, 0x2000, v133
	s_barrier
	s_cmp_lg_u32 s29, 0
	s_cbranch_scc1 .Lmy_g1_prestaged
	v_readfirstlane_b32 s11, v128
	s_or_b32 s10, s21, 0x80
	s_mov_b32 m0, s11
	v_readfirstlane_b32 s11, v130
	buffer_load_dwordx4 v161, s[88:91], s10 offen lds
	s_mov_b32 m0, s11
	v_readfirstlane_b32 s24, v131
	buffer_load_dwordx4 v160, s[88:91], s10 offen lds
	s_or_b32 s23, s22, 0x80
	s_mov_b32 s10, s90
	s_mov_b32 s11, s91
	s_mov_b32 m0, s24
	v_readfirstlane_b32 s24, v132
	buffer_load_dwordx4 v161, s[8:11], s23 offen lds
	s_mov_b32 m0, s24
	v_readfirstlane_b32 s24, v133
	buffer_load_dwordx4 v160, s[8:11], s23 offen lds
	s_or_b32 s23, s21, 0x80080
	s_mov_b32 m0, s24
	v_readfirstlane_b32 s24, v134
	buffer_load_dwordx4 v161, s[88:91], s23 offen lds
	s_mov_b32 m0, s24
	s_nop 0
	buffer_load_dwordx4 v160, s[88:91], s23 offen lds
	s_waitcnt vmcnt(6)
	s_branch .Lmy_g1_staged
.Lmy_g1_prestaged:
	s_mov_b32 s10, s90
	s_mov_b32 s11, s91
	s_waitcnt vmcnt(24)
.Lmy_g1_staged:
	v_lshlrev_b32_e32 v3, 6, v0
	v_lshlrev_b32_e32 v5, 2, v0
	v_lshrrev_b32_e32 v2, 2, v0
	v_and_b32_e32 v1, 48, v0
	v_and_b32_e32 v4, 0x3c0, v3
	v_and_b32_e32 v5, 32, v5
	v_bitop3_b32 v1, v4, v5, v1 bitop3:0x36
	v_lshlrev_b32_e32 v2, 7, v2
	v_lshlrev_b32_e32 v0, 5, v0
	v_add_u32_e32 v4, s33, v1
	v_add_u32_e32 v5, s0, v1
	v_add_u32_e32 v6, s1, v1
	v_add_u32_e32 v7, s96, v1
	v_and_b32_e32 v3, 0x3000, v3
	v_add_u32_e32 v1, 0, v1
	v_and_b32_e32 v2, 0x2000, v2
	v_and_b32_e32 v8, 0x2000, v0
	v_mov_b32_e32 v0, 0
	v_mov_b32_e32 v208, v226
	s_xor_b64 s[6:7], s[12:13], -1
	s_mov_b32 s23, -2
	s_mov_b32 s24, 0
	v_add_u32_e32 v135, v4, v3
	v_add_u32_e32 v201, v1, v2
	v_add_u32_e32 v202, v1, v8
	v_add_u32_e32 v129, v5, v3
	v_add_u32_e32 v184, v6, v3
	v_add_u32_e32 v203, v7, v3
	v_mov_b32_e32 v1, v0
	v_mov_b32_e32 v2, v0
	v_mov_b32_e32 v3, v0
	v_mov_b32_e32 v4, v0
	v_mov_b32_e32 v5, v0
	v_mov_b32_e32 v6, v0
	v_mov_b32_e32 v7, v0
	v_mov_b32_e32 v8, v0
	v_mov_b32_e32 v9, v0
	v_mov_b32_e32 v10, v0
	v_mov_b32_e32 v11, v0
	v_mov_b32_e32 v12, v0
	v_mov_b32_e32 v13, v0
	v_mov_b32_e32 v14, v0
	v_mov_b32_e32 v15, v0
	v_mov_b32_e32 v16, v0
	v_mov_b32_e32 v17, v0
	v_mov_b32_e32 v18, v0
	v_mov_b32_e32 v19, v0
	v_mov_b32_e32 v20, v0
	v_mov_b32_e32 v21, v0
	v_mov_b32_e32 v22, v0
	v_mov_b32_e32 v23, v0
	v_mov_b32_e32 v24, v0
	v_mov_b32_e32 v25, v0
	v_mov_b32_e32 v26, v0
	v_mov_b32_e32 v27, v0
	v_mov_b32_e32 v28, v0
	v_mov_b32_e32 v29, v0
	v_mov_b32_e32 v30, v0
	v_mov_b32_e32 v31, v0
	v_mov_b32_e32 v32, v0
	v_mov_b32_e32 v33, v0
	v_mov_b32_e32 v34, v0
	v_mov_b32_e32 v35, v0
	v_mov_b32_e32 v36, v0
	v_mov_b32_e32 v37, v0
	v_mov_b32_e32 v38, v0
	v_mov_b32_e32 v39, v0
	v_mov_b32_e32 v40, v0
	v_mov_b32_e32 v41, v0
	v_mov_b32_e32 v42, v0
	v_mov_b32_e32 v43, v0
	v_mov_b32_e32 v44, v0
	v_mov_b32_e32 v45, v0
	v_mov_b32_e32 v46, v0
	v_mov_b32_e32 v47, v0
	v_mov_b32_e32 v48, v0
	v_mov_b32_e32 v49, v0
	v_mov_b32_e32 v50, v0
	v_mov_b32_e32 v51, v0
	v_mov_b32_e32 v52, v0
	v_mov_b32_e32 v53, v0
	v_mov_b32_e32 v54, v0
	v_mov_b32_e32 v55, v0
	v_mov_b32_e32 v56, v0
	v_mov_b32_e32 v57, v0
	v_mov_b32_e32 v58, v0
	v_mov_b32_e32 v59, v0
	v_mov_b32_e32 v60, v0
	v_mov_b32_e32 v61, v0
	v_mov_b32_e32 v62, v0
	v_mov_b32_e32 v63, v0
	v_mov_b32_e32 v64, v0
	v_mov_b32_e32 v65, v0
	v_mov_b32_e32 v66, v0
	v_mov_b32_e32 v67, v0
	v_mov_b32_e32 v68, v0
	v_mov_b32_e32 v69, v0
	v_mov_b32_e32 v70, v0
	v_mov_b32_e32 v71, v0
	v_mov_b32_e32 v72, v0
	v_mov_b32_e32 v73, v0
	v_mov_b32_e32 v74, v0
	v_mov_b32_e32 v75, v0
	v_mov_b32_e32 v76, v0
	v_mov_b32_e32 v77, v0
	v_mov_b32_e32 v78, v0
	v_mov_b32_e32 v79, v0
	v_mov_b32_e32 v80, v0
	v_mov_b32_e32 v81, v0
	v_mov_b32_e32 v82, v0
	v_mov_b32_e32 v83, v0
	v_mov_b32_e32 v84, v0
	v_mov_b32_e32 v85, v0
	v_mov_b32_e32 v86, v0
	v_mov_b32_e32 v87, v0
	v_mov_b32_e32 v88, v0
	v_mov_b32_e32 v89, v0
	v_mov_b32_e32 v90, v0
	v_mov_b32_e32 v91, v0
	v_mov_b32_e32 v92, v0
	v_mov_b32_e32 v93, v0
	v_mov_b32_e32 v94, v0
	v_mov_b32_e32 v95, v0
	v_mov_b32_e32 v96, v0
	v_mov_b32_e32 v97, v0
	v_mov_b32_e32 v98, v0
	v_mov_b32_e32 v99, v0
	v_mov_b32_e32 v100, v0
	v_mov_b32_e32 v101, v0
	v_mov_b32_e32 v102, v0
	v_mov_b32_e32 v103, v0
	v_mov_b32_e32 v104, v0
	v_mov_b32_e32 v105, v0
	v_mov_b32_e32 v106, v0
	v_mov_b32_e32 v107, v0
	v_mov_b32_e32 v108, v0
	v_mov_b32_e32 v109, v0
	v_mov_b32_e32 v110, v0
	v_mov_b32_e32 v111, v0
	v_mov_b32_e32 v112, v0
	v_mov_b32_e32 v113, v0
	v_mov_b32_e32 v114, v0
	v_mov_b32_e32 v115, v0
	v_mov_b32_e32 v116, v0
	v_mov_b32_e32 v117, v0
	v_mov_b32_e32 v118, v0
	v_mov_b32_e32 v119, v0
	v_mov_b32_e32 v120, v0
	v_mov_b32_e32 v121, v0
	v_mov_b32_e32 v122, v0
	v_mov_b32_e32 v123, v0
	v_mov_b32_e32 v124, v0
	v_mov_b32_e32 v125, v0
	v_mov_b32_e32 v126, v0
	v_mov_b32_e32 v127, v0
	v_add_u32_e32 v137, 0xc000, v166
	v_add_u32_e32 v136, 0xe000, v166
	v_add_u32_e32 v186, 0x2000, v167
	v_add_u32_e32 v185, 0x2000, v164
	s_barrier
; #define WAIT_V(n) asm volatile("s_waitcnt vmcnt(" #n ")" ::: "memory")
; #define WAIT_L(n) asm volatile("s_waitcnt lgkmcnt(" #n ")" ::: "memory")
; #define BAR __builtin_amdgcn_s_barrier()
; #define SCHED __builtin_amdgcn_sched_barrier(0)
;     ...
;   for (int t = 0; t < nt - 2; t += 2) {
;     LDB(B0, 0, 0); SCHED; LDA(At, 0, 0); STAGE(SA(1, 1), A, brow + HALF, t + 1);
;     WAIT_L(8); BAR; WAIT_L(0); MMA(0, 0, At, B0); BAR; SCHED;
;     LDB(B1, 0, 1); STAGE(SB(0, 0), Bt, bcol, t + 2);
;     BAR; WAIT_L(0); MMA(0, 1, At, B1); BAR;
;     LDA(At, 0, 1); STAGE(SA(0, 0), A, brow, t + 2);
;     BAR; WAIT_L(0); MMA(1, 0, At, B0); BAR; SCHED;
;     STAGE(SB(0, 1), Bt, bcol + HALF, t + 2);
;     WAIT_V(6); BAR; MMA(1, 1, At, B1); BAR;
.LBB0_778:
	ds_read_b128 v[138:141], v135
	ds_read_b128 v[142:145], v135 offset:1024
	ds_read_b128 v[146:149], v135 offset:2048
	ds_read_b128 v[150:153], v135 offset:3072
	s_add_i32 s25, s22, s24
	v_readfirstlane_b32 s27, v137
	s_add_i32 s26, s25, 0x80080
	s_mov_b32 m0, s27
	v_readfirstlane_b32 s27, v136
	buffer_load_dwordx4 v161, s[8:11], s26 offen lds
	s_mov_b32 m0, s27
	s_nop 0
	buffer_load_dwordx4 v160, s[8:11], s26 offen lds
	ds_read_b128 v[154:157], v201
	ds_read_b128 v[168:171], v201 offset:1024
	ds_read_b128 v[172:175], v201 offset:2048
	ds_read_b128 v[176:179], v201 offset:3072
	ds_read_b128 v[180:183], v201 offset:4096
	ds_read_b128 v[188:191], v201 offset:5120
	ds_read_b128 v[192:195], v201 offset:6144
	ds_read_b128 v[196:199], v202 offset:7168
	s_waitcnt lgkmcnt(8)
	s_barrier
	s_setprio 1
	s_waitcnt lgkmcnt(7)
	v_mfma_f32_16x16x32_bf16 v[124:127], v[154:157], v[138:141], v[124:127]
	v_mfma_f32_16x16x32_bf16 v[120:123], v[154:157], v[146:149], v[120:123]
	s_waitcnt lgkmcnt(5)
	v_mfma_f32_16x16x32_bf16 v[116:119], v[172:175], v[138:141], v[116:119]
	v_mfma_f32_16x16x32_bf16 v[112:115], v[172:175], v[146:149], v[112:115]
	s_waitcnt lgkmcnt(3)
	v_mfma_f32_16x16x32_bf16 v[108:111], v[180:183], v[138:141], v[108:111]
	v_mfma_f32_16x16x32_bf16 v[104:107], v[180:183], v[146:149], v[104:107]
	s_waitcnt lgkmcnt(1)
	v_mfma_f32_16x16x32_bf16 v[100:103], v[192:195], v[138:141], v[100:103]
	v_mfma_f32_16x16x32_bf16 v[96:99], v[192:195], v[146:149], v[96:99]
	v_mfma_f32_16x16x32_bf16 v[124:127], v[168:171], v[142:145], v[124:127]
	v_mfma_f32_16x16x32_bf16 v[120:123], v[168:171], v[150:153], v[120:123]
	v_mfma_f32_16x16x32_bf16 v[116:119], v[176:179], v[142:145], v[116:119]
	v_mfma_f32_16x16x32_bf16 v[112:115], v[176:179], v[150:153], v[112:115]
	v_mfma_f32_16x16x32_bf16 v[108:111], v[188:191], v[142:145], v[108:111]
	v_mfma_f32_16x16x32_bf16 v[104:107], v[188:191], v[150:153], v[104:107]
	s_waitcnt lgkmcnt(0)
	v_mfma_f32_16x16x32_bf16 v[100:103], v[196:199], v[142:145], v[100:103]
	v_mfma_f32_16x16x32_bf16 v[96:99], v[196:199], v[150:153], v[96:99]
	s_setprio 0
	s_barrier
	s_add_i32 s26, s21, s24
	v_readfirstlane_b32 s28, v167
	s_add_i32 s27, s26, 0x100
	s_mov_b32 m0, s28
	v_readfirstlane_b32 s28, v186
	buffer_load_dwordx4 v161, s[88:91], s27 offen lds
	s_mov_b32 m0, s28
	s_nop 0
	buffer_load_dwordx4 v160, s[88:91], s27 offen lds
	ds_read_b128 v[204:207], v129
	ds_read_b128 v[212:215], v129 offset:1024
	ds_read_b128 v[216:219], v129 offset:2048
	ds_read_b128 v[236:239], v129 offset:3072
	s_barrier
	s_setprio 1
	s_waitcnt lgkmcnt(3)
	v_mfma_f32_16x16x32_bf16 v[92:95], v[154:157], v[204:207], v[92:95]
	s_waitcnt lgkmcnt(1)
	v_mfma_f32_16x16x32_bf16 v[88:91], v[154:157], v[216:219], v[88:91]
	v_mfma_f32_16x16x32_bf16 v[84:87], v[172:175], v[204:207], v[84:87]
	v_mfma_f32_16x16x32_bf16 v[80:83], v[172:175], v[216:219], v[80:83]
	v_mfma_f32_16x16x32_bf16 v[76:79], v[180:183], v[204:207], v[76:79]
	v_mfma_f32_16x16x32_bf16 v[72:75], v[180:183], v[216:219], v[72:75]
	v_mfma_f32_16x16x32_bf16 v[68:71], v[192:195], v[204:207], v[68:71]
	v_mfma_f32_16x16x32_bf16 v[64:67], v[192:195], v[216:219], v[64:67]
	v_mfma_f32_16x16x32_bf16 v[92:95], v[168:171], v[212:215], v[92:95]
	s_waitcnt lgkmcnt(0)
	v_mfma_f32_16x16x32_bf16 v[88:91], v[168:171], v[236:239], v[88:91]
	v_mfma_f32_16x16x32_bf16 v[84:87], v[176:179], v[212:215], v[84:87]
	v_mfma_f32_16x16x32_bf16 v[80:83], v[176:179], v[236:239], v[80:83]
	v_mfma_f32_16x16x32_bf16 v[76:79], v[188:191], v[212:215], v[76:79]
	v_mfma_f32_16x16x32_bf16 v[72:75], v[188:191], v[236:239], v[72:75]
	v_mfma_f32_16x16x32_bf16 v[68:71], v[196:199], v[212:215], v[68:71]
	v_mfma_f32_16x16x32_bf16 v[64:67], v[196:199], v[236:239], v[64:67]
	s_setprio 0
	v_readfirstlane_b32 s28, v166
	s_add_i32 s27, s25, 0x100
	s_mov_b32 m0, s28
	v_readfirstlane_b32 s28, v165
	s_barrier
	buffer_load_dwordx4 v161, s[8:11], s27 offen lds
	s_mov_b32 m0, s28
	s_nop 0
	buffer_load_dwordx4 v160, s[8:11], s27 offen lds
	ds_read_b128 v[154:157], v201 offset:16384
	ds_read_b128 v[168:171], v201 offset:17408
	ds_read_b128 v[172:175], v201 offset:18432
	ds_read_b128 v[176:179], v201 offset:19456
	ds_read_b128 v[180:183], v201 offset:20480
	ds_read_b128 v[188:191], v201 offset:21504
	ds_read_b128 v[192:195], v201 offset:22528
	ds_read_b128 v[196:199], v202 offset:23552
	s_barrier
	s_setprio 1
	s_waitcnt lgkmcnt(7)
	v_mfma_f32_16x16x32_bf16 v[60:63], v[154:157], v[138:141], v[60:63]
	v_mfma_f32_16x16x32_bf16 v[56:59], v[154:157], v[146:149], v[56:59]
	s_waitcnt lgkmcnt(5)
	v_mfma_f32_16x16x32_bf16 v[52:55], v[172:175], v[138:141], v[52:55]
	v_mfma_f32_16x16x32_bf16 v[48:51], v[172:175], v[146:149], v[48:51]
	s_waitcnt lgkmcnt(3)
	v_mfma_f32_16x16x32_bf16 v[44:47], v[180:183], v[138:141], v[44:47]
	v_mfma_f32_16x16x32_bf16 v[40:43], v[180:183], v[146:149], v[40:43]
	s_waitcnt lgkmcnt(1)
	v_mfma_f32_16x16x32_bf16 v[36:39], v[192:195], v[138:141], v[36:39]
	v_mfma_f32_16x16x32_bf16 v[32:35], v[192:195], v[146:149], v[32:35]
	v_mfma_f32_16x16x32_bf16 v[60:63], v[168:171], v[142:145], v[60:63]
	v_mfma_f32_16x16x32_bf16 v[56:59], v[168:171], v[150:153], v[56:59]
	v_mfma_f32_16x16x32_bf16 v[52:55], v[176:179], v[142:145], v[52:55]
	v_mfma_f32_16x16x32_bf16 v[48:51], v[176:179], v[150:153], v[48:51]
	v_mfma_f32_16x16x32_bf16 v[44:47], v[188:191], v[142:145], v[44:47]
	v_mfma_f32_16x16x32_bf16 v[40:43], v[188:191], v[150:153], v[40:43]
	s_waitcnt lgkmcnt(0)
	v_mfma_f32_16x16x32_bf16 v[36:39], v[196:199], v[142:145], v[36:39]
	v_mfma_f32_16x16x32_bf16 v[32:35], v[196:199], v[150:153], v[32:35]
	s_setprio 0
	s_barrier
	v_readfirstlane_b32 s28, v164
	s_add_i32 s27, s26, 0x80100
	s_mov_b32 m0, s28
	v_readfirstlane_b32 s28, v185
	buffer_load_dwordx4 v161, s[88:91], s27 offen lds
	s_mov_b32 m0, s28
	s_nop 0
	buffer_load_dwordx4 v160, s[88:91], s27 offen lds
	s_cmp_lg_u32 s29, 0
	s_cbranch_scc0 .Lmy_g1_w6
	s_mov_b32 s29, 0
	s_waitcnt vmcnt(24)
	s_branch .Lmy_g1_wdone
; #define WAIT_V(n) asm volatile("s_waitcnt vmcnt(" #n ")" ::: "memory")
; #define WAIT_L(n) asm volatile("s_waitcnt lgkmcnt(" #n ")" ::: "memory")
; #define BAR __builtin_amdgcn_s_barrier()
; #define SCHED __builtin_amdgcn_sched_barrier(0)
;     ...
;     WAIT_V(6); BAR; MMA(1, 1, At, B1); BAR;
;     LDB(B0, 1, 0); SCHED; LDA(At, 1, 0); STAGE(SA(0, 1), A, brow + HALF, t + 2);
;     WAIT_L(8); BAR; WAIT_L(0); MMA(0, 0, At, B0); BAR; SCHED;
;     LDB(B1, 1, 1); STAGE(SB(1, 0), Bt, bcol, t + 3);
;     BAR; WAIT_L(0); MMA(0, 1, At, B1); BAR;
;     LDA(At, 1, 1); STAGE(SA(1, 0), A, brow, t + 3);
;     BAR; WAIT_L(0); MMA(1, 0, At, B0); BAR; SCHED;
;     STAGE(SB(1, 1), Bt, bcol + HALF, t + 3);
.Lmy_g1_w6:
	s_waitcnt vmcnt(6)
.Lmy_g1_wdone:
	s_barrier
	s_setprio 1
	v_mfma_f32_16x16x32_bf16 v[28:31], v[154:157], v[204:207], v[28:31]
	v_mfma_f32_16x16x32_bf16 v[24:27], v[154:157], v[216:219], v[24:27]
	v_mfma_f32_16x16x32_bf16 v[20:23], v[172:175], v[204:207], v[20:23]
	v_mfma_f32_16x16x32_bf16 v[16:19], v[172:175], v[216:219], v[16:19]
	v_mfma_f32_16x16x32_bf16 v[12:15], v[180:183], v[204:207], v[12:15]
	v_mfma_f32_16x16x32_bf16 v[8:11], v[180:183], v[216:219], v[8:11]
	v_mfma_f32_16x16x32_bf16 v[4:7], v[192:195], v[204:207], v[4:7]
	v_mfma_f32_16x16x32_bf16 v[0:3], v[192:195], v[216:219], v[0:3]
	v_mfma_f32_16x16x32_bf16 v[28:31], v[168:171], v[212:215], v[28:31]
	v_mfma_f32_16x16x32_bf16 v[24:27], v[168:171], v[236:239], v[24:27]
	v_mfma_f32_16x16x32_bf16 v[20:23], v[176:179], v[212:215], v[20:23]
	v_mfma_f32_16x16x32_bf16 v[16:19], v[176:179], v[236:239], v[16:19]
	v_mfma_f32_16x16x32_bf16 v[12:15], v[188:191], v[212:215], v[12:15]
	v_mfma_f32_16x16x32_bf16 v[8:11], v[188:191], v[236:239], v[8:11]
	v_mfma_f32_16x16x32_bf16 v[4:7], v[196:199], v[212:215], v[4:7]
	v_mfma_f32_16x16x32_bf16 v[0:3], v[196:199], v[236:239], v[0:3]
	s_setprio 0
	s_barrier
	ds_read_b128 v[138:141], v184
	ds_read_b128 v[142:145], v184 offset:1024
	ds_read_b128 v[146:149], v184 offset:2048
	ds_read_b128 v[150:153], v184 offset:3072
	v_readfirstlane_b32 s28, v163
	s_add_i32 s27, s25, 0x80100
	s_mov_b32 m0, s28
	v_readfirstlane_b32 s28, v162
	buffer_load_dwordx4 v161, s[8:11], s27 offen lds
	s_mov_b32 m0, s28
	s_nop 0
	buffer_load_dwordx4 v160, s[8:11], s27 offen lds
	ds_read_b128 v[154:157], v201 offset:32768
	ds_read_b128 v[168:171], v201 offset:33792
	ds_read_b128 v[172:175], v201 offset:34816
	ds_read_b128 v[176:179], v201 offset:35840
	ds_read_b128 v[180:183], v201 offset:36864
	ds_read_b128 v[188:191], v201 offset:37888
	ds_read_b128 v[192:195], v201 offset:38912
	ds_read_b128 v[196:199], v202 offset:39936
	s_waitcnt lgkmcnt(8)
	s_barrier
	s_setprio 1
	s_waitcnt lgkmcnt(7)
	v_mfma_f32_16x16x32_bf16 v[124:127], v[154:157], v[138:141], v[124:127]
	v_mfma_f32_16x16x32_bf16 v[120:123], v[154:157], v[146:149], v[120:123]
	s_waitcnt lgkmcnt(5)
	v_mfma_f32_16x16x32_bf16 v[116:119], v[172:175], v[138:141], v[116:119]
	v_mfma_f32_16x16x32_bf16 v[112:115], v[172:175], v[146:149], v[112:115]
	s_waitcnt lgkmcnt(3)
	v_mfma_f32_16x16x32_bf16 v[108:111], v[180:183], v[138:141], v[108:111]
	v_mfma_f32_16x16x32_bf16 v[104:107], v[180:183], v[146:149], v[104:107]
	s_waitcnt lgkmcnt(1)
	v_mfma_f32_16x16x32_bf16 v[100:103], v[192:195], v[138:141], v[100:103]
	v_mfma_f32_16x16x32_bf16 v[96:99], v[192:195], v[146:149], v[96:99]
	v_mfma_f32_16x16x32_bf16 v[124:127], v[168:171], v[142:145], v[124:127]
	v_mfma_f32_16x16x32_bf16 v[120:123], v[168:171], v[150:153], v[120:123]
	v_mfma_f32_16x16x32_bf16 v[116:119], v[176:179], v[142:145], v[116:119]
	v_mfma_f32_16x16x32_bf16 v[112:115], v[176:179], v[150:153], v[112:115]
	v_mfma_f32_16x16x32_bf16 v[108:111], v[188:191], v[142:145], v[108:111]
	v_mfma_f32_16x16x32_bf16 v[104:107], v[188:191], v[150:153], v[104:107]
	s_waitcnt lgkmcnt(0)
	v_mfma_f32_16x16x32_bf16 v[100:103], v[196:199], v[142:145], v[100:103]
	v_mfma_f32_16x16x32_bf16 v[96:99], v[196:199], v[150:153], v[96:99]
	s_setprio 0
	s_barrier
	v_readfirstlane_b32 s28, v128
	s_add_i32 s27, s26, 0x180
	s_mov_b32 m0, s28
	v_readfirstlane_b32 s28, v130
	buffer_load_dwordx4 v161, s[88:91], s27 offen lds
	s_mov_b32 m0, s28
	s_nop 0
	buffer_load_dwordx4 v160, s[88:91], s27 offen lds
	ds_read_b128 v[204:207], v203
	ds_read_b128 v[212:215], v203 offset:1024
	ds_read_b128 v[216:219], v203 offset:2048
	ds_read_b128 v[236:239], v203 offset:3072
	s_barrier
	s_setprio 1
	s_waitcnt lgkmcnt(3)
	v_mfma_f32_16x16x32_bf16 v[92:95], v[154:157], v[204:207], v[92:95]
	s_waitcnt lgkmcnt(1)
	v_mfma_f32_16x16x32_bf16 v[88:91], v[154:157], v[216:219], v[88:91]
	v_mfma_f32_16x16x32_bf16 v[84:87], v[172:175], v[204:207], v[84:87]
	v_mfma_f32_16x16x32_bf16 v[80:83], v[172:175], v[216:219], v[80:83]
	v_mfma_f32_16x16x32_bf16 v[76:79], v[180:183], v[204:207], v[76:79]
	v_mfma_f32_16x16x32_bf16 v[72:75], v[180:183], v[216:219], v[72:75]
	v_mfma_f32_16x16x32_bf16 v[68:71], v[192:195], v[204:207], v[68:71]
	v_mfma_f32_16x16x32_bf16 v[64:67], v[192:195], v[216:219], v[64:67]
	v_mfma_f32_16x16x32_bf16 v[92:95], v[168:171], v[212:215], v[92:95]
	s_waitcnt lgkmcnt(0)
	v_mfma_f32_16x16x32_bf16 v[88:91], v[168:171], v[236:239], v[88:91]
	v_mfma_f32_16x16x32_bf16 v[84:87], v[176:179], v[212:215], v[84:87]
	v_mfma_f32_16x16x32_bf16 v[80:83], v[176:179], v[236:239], v[80:83]
	v_mfma_f32_16x16x32_bf16 v[76:79], v[188:191], v[212:215], v[76:79]
	v_mfma_f32_16x16x32_bf16 v[72:75], v[188:191], v[236:239], v[72:75]
	v_mfma_f32_16x16x32_bf16 v[68:71], v[196:199], v[212:215], v[68:71]
	v_mfma_f32_16x16x32_bf16 v[64:67], v[196:199], v[236:239], v[64:67]
	s_setprio 0
	v_readfirstlane_b32 s27, v131
	s_addk_i32 s25, 0x180
	s_mov_b32 m0, s27
	v_readfirstlane_b32 s27, v132
	s_barrier
	buffer_load_dwordx4 v161, s[8:11], s25 offen lds
	s_mov_b32 m0, s27
	s_nop 0
	buffer_load_dwordx4 v160, s[8:11], s25 offen lds
	ds_read_b128 v[154:157], v201 offset:49152
	ds_read_b128 v[168:171], v201 offset:50176
	ds_read_b128 v[172:175], v201 offset:51200
	ds_read_b128 v[176:179], v201 offset:52224
	ds_read_b128 v[180:183], v201 offset:53248
	ds_read_b128 v[188:191], v201 offset:54272
	ds_read_b128 v[192:195], v201 offset:55296
	ds_read_b128 v[196:199], v202 offset:56320
	s_barrier
; #define WAIT_V(n) asm volatile("s_waitcnt vmcnt(" #n ")" ::: "memory")
; #define WAIT_L(n) asm volatile("s_waitcnt lgkmcnt(" #n ")" ::: "memory")
; #define BAR __builtin_amdgcn_s_barrier()
;     ...
;     STAGE(SB(1, 1), Bt, bcol + HALF, t + 3);
;     WAIT_V(6); BAR; MMA(1, 1, At, B1); BAR;
;   }
;   { LDB(B0, 0, 0); LDA(At, 0, 0); STAGE(SA(1, 1), A, brow + HALF, nt - 1);
;     BAR; WAIT_L(0); MMA(0, 0, At, B0); BAR;
;     LDB(B1, 0, 1); BAR; WAIT_L(0); MMA(0, 1, At, B1); BAR;
;     LDA(At, 0, 1); WAIT_V(4); BAR; WAIT_L(0); MMA(1, 0, At, B0); MMA(1, 1, At, B1); BAR; }
	s_setprio 1
	s_waitcnt lgkmcnt(7)
	v_mfma_f32_16x16x32_bf16 v[60:63], v[154:157], v[138:141], v[60:63]
	v_mfma_f32_16x16x32_bf16 v[56:59], v[154:157], v[146:149], v[56:59]
	s_waitcnt lgkmcnt(5)
	v_mfma_f32_16x16x32_bf16 v[52:55], v[172:175], v[138:141], v[52:55]
	v_mfma_f32_16x16x32_bf16 v[48:51], v[172:175], v[146:149], v[48:51]
	s_waitcnt lgkmcnt(3)
	v_mfma_f32_16x16x32_bf16 v[44:47], v[180:183], v[138:141], v[44:47]
	v_mfma_f32_16x16x32_bf16 v[40:43], v[180:183], v[146:149], v[40:43]
	s_waitcnt lgkmcnt(1)
	v_mfma_f32_16x16x32_bf16 v[36:39], v[192:195], v[138:141], v[36:39]
	v_mfma_f32_16x16x32_bf16 v[32:35], v[192:195], v[146:149], v[32:35]
	v_mfma_f32_16x16x32_bf16 v[60:63], v[168:171], v[142:145], v[60:63]
	v_mfma_f32_16x16x32_bf16 v[56:59], v[168:171], v[150:153], v[56:59]
	v_mfma_f32_16x16x32_bf16 v[52:55], v[176:179], v[142:145], v[52:55]
	v_mfma_f32_16x16x32_bf16 v[48:51], v[176:179], v[150:153], v[48:51]
	v_mfma_f32_16x16x32_bf16 v[44:47], v[188:191], v[142:145], v[44:47]
	v_mfma_f32_16x16x32_bf16 v[40:43], v[188:191], v[150:153], v[40:43]
	s_waitcnt lgkmcnt(0)
	v_mfma_f32_16x16x32_bf16 v[36:39], v[196:199], v[142:145], v[36:39]
	v_mfma_f32_16x16x32_bf16 v[32:35], v[196:199], v[150:153], v[32:35]
	s_setprio 0
	s_barrier
	v_readfirstlane_b32 s25, v133
	s_add_i32 s26, s26, 0x80180
	s_mov_b32 m0, s25
	v_readfirstlane_b32 s25, v134
	buffer_load_dwordx4 v161, s[88:91], s26 offen lds
	s_mov_b32 m0, s25
	s_nop 0
	buffer_load_dwordx4 v160, s[88:91], s26 offen lds
	s_waitcnt vmcnt(6)
	s_barrier
	s_setprio 1
	v_mfma_f32_16x16x32_bf16 v[28:31], v[154:157], v[204:207], v[28:31]
	v_mfma_f32_16x16x32_bf16 v[24:27], v[154:157], v[216:219], v[24:27]
	v_mfma_f32_16x16x32_bf16 v[20:23], v[172:175], v[204:207], v[20:23]
	v_mfma_f32_16x16x32_bf16 v[16:19], v[172:175], v[216:219], v[16:19]
	v_mfma_f32_16x16x32_bf16 v[12:15], v[180:183], v[204:207], v[12:15]
	v_mfma_f32_16x16x32_bf16 v[8:11], v[180:183], v[216:219], v[8:11]
	v_mfma_f32_16x16x32_bf16 v[4:7], v[192:195], v[204:207], v[4:7]
	v_mfma_f32_16x16x32_bf16 v[0:3], v[192:195], v[216:219], v[0:3]
	v_mfma_f32_16x16x32_bf16 v[28:31], v[168:171], v[212:215], v[28:31]
	v_mfma_f32_16x16x32_bf16 v[24:27], v[168:171], v[236:239], v[24:27]
	v_mfma_f32_16x16x32_bf16 v[20:23], v[176:179], v[212:215], v[20:23]
	v_mfma_f32_16x16x32_bf16 v[16:19], v[176:179], v[236:239], v[16:19]
	v_mfma_f32_16x16x32_bf16 v[12:15], v[188:191], v[212:215], v[12:15]
	v_mfma_f32_16x16x32_bf16 v[8:11], v[188:191], v[236:239], v[8:11]
	v_mfma_f32_16x16x32_bf16 v[4:7], v[196:199], v[212:215], v[4:7]
	v_mfma_f32_16x16x32_bf16 v[0:3], v[196:199], v[236:239], v[0:3]
	s_setprio 0
	s_add_i32 s23, s23, 2
	s_addk_i32 s24, 0x100
	s_cmp_lt_u32 s23, 28
	s_barrier
	s_cbranch_scc1 .LBB0_778
	s_or_b32 s21, s22, 0x80f80
	v_readfirstlane_b32 s22, v137
	s_mov_b32 s10, s90
	s_mov_b32 s11, s91
	s_mov_b32 m0, s22
	v_readfirstlane_b32 s22, v136
	buffer_load_dwordx4 v161, s[8:11], s21 offen lds
	s_mov_b32 m0, s22
	s_nop 0
	buffer_load_dwordx4 v160, s[8:11], s21 offen lds
	ds_read_b128 v[130:133], v135
	ds_read_b128 v[136:139], v135 offset:1024
	ds_read_b128 v[140:143], v135 offset:2048
	ds_read_b128 v[188:191], v135 offset:3072
	ds_read_b128 v[192:195], v201
	ds_read_b128 v[196:199], v201 offset:1024
	ds_read_b128 v[204:207], v201 offset:2048
	ds_read_b128 v[212:215], v201 offset:3072
	ds_read_b128 v[216:219], v201 offset:4096
	ds_read_b128 v[236:239], v201 offset:5120
	ds_read_b128 v[240:243], v201 offset:6144
	ds_read_b128 v[244:247], v202 offset:7168
	s_barrier
	s_setprio 1
	s_waitcnt lgkmcnt(7)
	v_mfma_f32_16x16x32_bf16 v[124:127], v[192:195], v[130:133], v[124:127]
	v_mfma_f32_16x16x32_bf16 v[120:123], v[192:195], v[140:143], v[120:123]
	s_waitcnt lgkmcnt(5)
	v_mfma_f32_16x16x32_bf16 v[116:119], v[204:207], v[130:133], v[116:119]
	v_mfma_f32_16x16x32_bf16 v[112:115], v[204:207], v[140:143], v[112:115]
	s_waitcnt lgkmcnt(3)
	v_mfma_f32_16x16x32_bf16 v[108:111], v[216:219], v[130:133], v[108:111]
	v_mfma_f32_16x16x32_bf16 v[104:107], v[216:219], v[140:143], v[104:107]
	s_waitcnt lgkmcnt(1)
	v_mfma_f32_16x16x32_bf16 v[100:103], v[240:243], v[130:133], v[100:103]
	v_mfma_f32_16x16x32_bf16 v[96:99], v[240:243], v[140:143], v[96:99]
	v_mfma_f32_16x16x32_bf16 v[144:147], v[196:199], v[136:139], v[124:127]
	v_mfma_f32_16x16x32_bf16 v[148:151], v[196:199], v[188:191], v[120:123]
	v_mfma_f32_16x16x32_bf16 v[152:155], v[212:215], v[136:139], v[116:119]
	v_mfma_f32_16x16x32_bf16 v[156:159], v[212:215], v[188:191], v[112:115]
	v_mfma_f32_16x16x32_bf16 v[168:171], v[236:239], v[136:139], v[108:111]
	v_mfma_f32_16x16x32_bf16 v[172:175], v[236:239], v[188:191], v[104:107]
	s_waitcnt lgkmcnt(0)
	v_mfma_f32_16x16x32_bf16 v[176:179], v[244:247], v[136:139], v[100:103]
	v_mfma_f32_16x16x32_bf16 v[180:183], v[244:247], v[188:191], v[96:99]
	s_setprio 0
	s_barrier
	ds_read_b128 v[248:251], v129
	ds_read_b128 v[228:231], v129 offset:1024
	ds_read_b128 v[224:227], v129 offset:2048
	ds_read_b128 v[220:223], v129 offset:3072
	s_barrier
	s_setprio 1
	s_waitcnt lgkmcnt(3)
	v_mfma_f32_16x16x32_bf16 v[92:95], v[192:195], v[248:251], v[92:95]
	s_waitcnt lgkmcnt(1)
	v_mfma_f32_16x16x32_bf16 v[88:91], v[192:195], v[224:227], v[88:91]
	v_mfma_f32_16x16x32_bf16 v[84:87], v[204:207], v[248:251], v[84:87]
	v_mfma_f32_16x16x32_bf16 v[80:83], v[204:207], v[224:227], v[80:83]
	v_mfma_f32_16x16x32_bf16 v[76:79], v[216:219], v[248:251], v[76:79]
	v_mfma_f32_16x16x32_bf16 v[72:75], v[216:219], v[224:227], v[72:75]
	v_mfma_f32_16x16x32_bf16 v[68:71], v[240:243], v[248:251], v[68:71]
	v_mfma_f32_16x16x32_bf16 v[64:67], v[240:243], v[224:227], v[64:67]
	v_mfma_f32_16x16x32_bf16 v[92:95], v[196:199], v[228:231], v[92:95]
	s_waitcnt lgkmcnt(0)
	v_mfma_f32_16x16x32_bf16 v[88:91], v[196:199], v[220:223], v[88:91]
	v_mfma_f32_16x16x32_bf16 v[96:99], v[212:215], v[228:231], v[84:87]
	v_mfma_f32_16x16x32_bf16 v[100:103], v[212:215], v[220:223], v[80:83]
	v_mfma_f32_16x16x32_bf16 v[76:79], v[236:239], v[228:231], v[76:79]
	v_mfma_f32_16x16x32_bf16 v[104:107], v[236:239], v[220:223], v[72:75]
	v_mfma_f32_16x16x32_bf16 v[68:71], v[244:247], v[228:231], v[68:71]
	v_mfma_f32_16x16x32_bf16 v[64:67], v[244:247], v[220:223], v[64:67]
	s_setprio 0
	s_barrier
; #define WAIT_V(n) asm volatile("s_waitcnt vmcnt(" #n ")" ::: "memory")
; #define WAIT_L(n) asm volatile("s_waitcnt lgkmcnt(" #n ")" ::: "memory")
; #define BAR __builtin_amdgcn_s_barrier()
;     ...
;     LDA(At, 0, 1); WAIT_V(4); BAR; WAIT_L(0); MMA(1, 0, At, B0); MMA(1, 1, At, B1); BAR; }
;   { LDB(B0, 1, 0); LDA(At, 1, 0); WAIT_V(2); BAR;
;     if (has_next) {
;       STAGE(SB(0, 0), Bt, nbcol, 0); STAGE(SA(0, 0), A, nbrow, 0);
;       STAGE(SB(0, 1), Bt, nbcol + HALF, 0); STAGE(SA(0, 1), A, nbrow + HALF, 0);
;     }
;     WAIT_L(0); MMA(0, 0, At, B0); BAR;
;     LDB(B1, 1, 1); if (has_next) { WAIT_V(8); } else { WAIT_V(0); } BAR; WAIT_L(0); MMA(0, 1, At, B1); BAR;
	ds_read_b128 v[72:75], v201 offset:16384
	ds_read_b128 v[80:83], v201 offset:17408
	ds_read_b128 v[84:87], v201 offset:18432
	ds_read_b128 v[192:195], v201 offset:19456
	ds_read_b128 v[196:199], v201 offset:20480
	ds_read_b128 v[204:207], v201 offset:21504
	ds_read_b128 v[212:215], v201 offset:22528
	ds_read_b128 v[216:219], v202 offset:23552
	s_waitcnt vmcnt(4)
	s_barrier
	s_setprio 1
	s_waitcnt lgkmcnt(7)
	v_mfma_f32_16x16x32_bf16 v[60:63], v[72:75], v[130:133], v[60:63]
	v_mfma_f32_16x16x32_bf16 v[56:59], v[72:75], v[140:143], v[56:59]
	s_waitcnt lgkmcnt(5)
	v_mfma_f32_16x16x32_bf16 v[52:55], v[84:87], v[130:133], v[52:55]
	v_mfma_f32_16x16x32_bf16 v[48:51], v[84:87], v[140:143], v[48:51]
	s_waitcnt lgkmcnt(3)
	v_mfma_f32_16x16x32_bf16 v[44:47], v[196:199], v[130:133], v[44:47]
	v_mfma_f32_16x16x32_bf16 v[40:43], v[196:199], v[140:143], v[40:43]
	s_waitcnt lgkmcnt(1)
	v_mfma_f32_16x16x32_bf16 v[36:39], v[212:215], v[130:133], v[36:39]
	v_mfma_f32_16x16x32_bf16 v[32:35], v[212:215], v[140:143], v[32:35]
	v_mfma_f32_16x16x32_bf16 v[108:111], v[80:83], v[136:139], v[60:63]
	v_mfma_f32_16x16x32_bf16 v[112:115], v[80:83], v[188:191], v[56:59]
	v_mfma_f32_16x16x32_bf16 v[52:55], v[192:195], v[136:139], v[52:55]
	v_mfma_f32_16x16x32_bf16 v[116:119], v[192:195], v[188:191], v[48:51]
	v_mfma_f32_16x16x32_bf16 v[44:47], v[204:207], v[136:139], v[44:47]
	v_mfma_f32_16x16x32_bf16 v[120:123], v[204:207], v[188:191], v[40:43]
	s_waitcnt lgkmcnt(0)
	v_mfma_f32_16x16x32_bf16 v[36:39], v[216:219], v[136:139], v[36:39]
	v_mfma_f32_16x16x32_bf16 v[124:127], v[216:219], v[188:191], v[32:35]
	s_setprio 0
	s_setprio 1
	v_mfma_f32_16x16x32_bf16 v[28:31], v[72:75], v[248:251], v[28:31]
	v_mfma_f32_16x16x32_bf16 v[24:27], v[72:75], v[224:227], v[24:27]
	v_mfma_f32_16x16x32_bf16 v[20:23], v[84:87], v[248:251], v[20:23]
	v_mfma_f32_16x16x32_bf16 v[16:19], v[84:87], v[224:227], v[16:19]
	v_mfma_f32_16x16x32_bf16 v[12:15], v[196:199], v[248:251], v[12:15]
	v_mfma_f32_16x16x32_bf16 v[8:11], v[196:199], v[224:227], v[8:11]
	v_mfma_f32_16x16x32_bf16 v[4:7], v[212:215], v[248:251], v[4:7]
	v_mfma_f32_16x16x32_bf16 v[0:3], v[212:215], v[224:227], v[0:3]
	v_mfma_f32_16x16x32_bf16 v[28:31], v[80:83], v[228:231], v[28:31]
	v_mfma_f32_16x16x32_bf16 v[128:131], v[80:83], v[220:223], v[24:27]
	v_mfma_f32_16x16x32_bf16 v[20:23], v[192:195], v[228:231], v[20:23]
	v_mfma_f32_16x16x32_bf16 v[132:135], v[192:195], v[220:223], v[16:19]
	v_mfma_f32_16x16x32_bf16 v[12:15], v[204:207], v[228:231], v[12:15]
	v_mfma_f32_16x16x32_bf16 v[136:139], v[204:207], v[220:223], v[8:11]
	v_mfma_f32_16x16x32_bf16 v[4:7], v[216:219], v[228:231], v[4:7]
	v_mfma_f32_16x16x32_bf16 v[140:143], v[216:219], v[220:223], v[0:3]
	s_setprio 0
	s_barrier
	s_nop 0
	ds_read_b128 v[0:3], v184
	ds_read_b128 v[8:11], v184 offset:1024
	ds_read_b128 v[16:19], v184 offset:2048
	ds_read_b128 v[24:27], v184 offset:3072
	ds_read_b128 v[192:195], v201 offset:32768
	ds_read_b128 v[196:199], v201 offset:33792
	ds_read_b128 v[60:63], v201 offset:34816
	ds_read_b128 v[72:75], v201 offset:35840
	ds_read_b128 v[48:51], v201 offset:36864
	ds_read_b128 v[56:59], v201 offset:37888
	ds_read_b128 v[32:35], v201 offset:38912
	ds_read_b128 v[40:43], v202 offset:39936
	s_waitcnt vmcnt(2)
	s_andn2_b64 vcc, exec, s[12:13]
	s_barrier
	s_cbranch_vccnz .LBB0_781
	v_readfirstlane_b32 s21, v167
	s_lshl_b32 s13, s18, 20
	s_mov_b32 m0, s21
	v_readfirstlane_b32 s21, v186
	buffer_load_dwordx4 v161, s[88:91], s13 offen lds
	s_mov_b32 m0, s21
	v_readfirstlane_b32 s21, v166
	s_lshl_b32 s12, s17, 20
	buffer_load_dwordx4 v160, s[88:91], s13 offen lds
	s_mov_b32 m0, s21
	v_readfirstlane_b32 s21, v165
	buffer_load_dwordx4 v161, s[8:11], s12 offen lds
	s_mov_b32 m0, s21
	v_readfirstlane_b32 s21, v164
	buffer_load_dwordx4 v160, s[8:11], s12 offen lds
	s_bitset1_b32 s13, 19
	s_mov_b32 m0, s21
	v_readfirstlane_b32 s21, v185
	buffer_load_dwordx4 v161, s[88:91], s13 offen lds
	s_mov_b32 m0, s21
	s_bitset1_b32 s12, 19
	buffer_load_dwordx4 v160, s[88:91], s13 offen lds
	v_readfirstlane_b32 s13, v163
	s_mov_b32 m0, s13
	v_readfirstlane_b32 s13, v162
	buffer_load_dwordx4 v161, s[8:11], s12 offen lds
	s_mov_b32 m0, s13
	s_nop 0
	buffer_load_dwordx4 v160, s[8:11], s12 offen lds
.LBB0_781:
	s_setprio 1
	s_waitcnt lgkmcnt(7)
	v_mfma_f32_16x16x32_bf16 v[80:83], v[192:195], v[0:3], v[144:147]
	s_waitcnt lgkmcnt(6)
	v_mfma_f32_16x16x32_bf16 v[184:187], v[196:199], v[8:11], v[80:83]
	v_mfma_f32_16x16x32_bf16 v[80:83], v[192:195], v[16:19], v[148:151]
	v_mfma_f32_16x16x32_bf16 v[188:191], v[196:199], v[24:27], v[80:83]
	s_waitcnt lgkmcnt(5)
	v_mfma_f32_16x16x32_bf16 v[80:83], v[60:63], v[0:3], v[152:155]
	s_waitcnt lgkmcnt(4)
	v_mfma_f32_16x16x32_bf16 v[160:163], v[72:75], v[8:11], v[80:83]
	v_mfma_f32_16x16x32_bf16 v[80:83], v[60:63], v[16:19], v[156:159]
	v_mfma_f32_16x16x32_bf16 v[164:167], v[72:75], v[24:27], v[80:83]
	s_waitcnt lgkmcnt(3)
	v_mfma_f32_16x16x32_bf16 v[80:83], v[48:51], v[0:3], v[168:171]
	s_waitcnt lgkmcnt(2)
	v_mfma_f32_16x16x32_bf16 v[144:147], v[56:59], v[8:11], v[80:83]
	v_mfma_f32_16x16x32_bf16 v[80:83], v[48:51], v[16:19], v[172:175]
	v_mfma_f32_16x16x32_bf16 v[148:151], v[56:59], v[24:27], v[80:83]
	s_waitcnt lgkmcnt(1)
	v_mfma_f32_16x16x32_bf16 v[80:83], v[32:35], v[0:3], v[176:179]
	v_mfma_f32_16x16x32_bf16 v[84:87], v[32:35], v[16:19], v[180:183]
	s_waitcnt lgkmcnt(0)
	v_mfma_f32_16x16x32_bf16 v[80:83], v[40:43], v[8:11], v[80:83]
	v_mfma_f32_16x16x32_bf16 v[84:87], v[40:43], v[24:27], v[84:87]
	s_setprio 0
	s_barrier
	ds_read_b128 v[168:171], v203
	ds_read_b128 v[172:175], v203 offset:1024
	ds_read_b128 v[176:179], v203 offset:2048
	ds_read_b128 v[180:183], v203 offset:3072
	s_mov_b64 s[10:11], -1
	s_and_b64 vcc, exec, s[6:7]
	v_mov_b32_e32 v226, v208
	s_cbranch_vccz .LBB0_783
	s_waitcnt vmcnt(0)
	s_mov_b64 s[10:11], 0

; #define WAIT_V(n) asm volatile("s_waitcnt vmcnt(" #n ")" ::: "memory")
; #define WAIT_L(n) asm volatile("s_waitcnt lgkmcnt(" #n ")" ::: "memory")
; #define BAR __builtin_amdgcn_s_barrier()
;     ...
;     LDB(B1, 1, 1); if (has_next) { WAIT_V(8); } else { WAIT_V(0); } BAR; WAIT_L(0); MMA(0, 1, At, B1); BAR;
;     LDA(At, 1, 1); BAR; WAIT_L(0); MMA(1, 0, At, B0); MMA(1, 1, At, B1); BAR; }
;   if (wr == 0) BAR;
.LBB0_785:
	s_barrier
	s_setprio 1
	s_waitcnt lgkmcnt(1)
	v_mfma_f32_16x16x32_bf16 v[88:91], v[192:195], v[176:179], v[88:91]
	v_mfma_f32_16x16x32_bf16 v[92:95], v[192:195], v[168:171], v[92:95]
	s_waitcnt lgkmcnt(0)
	v_mfma_f32_16x16x32_bf16 v[156:159], v[196:199], v[180:183], v[88:91]
	v_mfma_f32_16x16x32_bf16 v[88:91], v[60:63], v[168:171], v[96:99]
	v_mfma_f32_16x16x32_bf16 v[60:63], v[60:63], v[176:179], v[100:103]
	v_mfma_f32_16x16x32_bf16 v[152:155], v[196:199], v[172:175], v[92:95]
	v_mfma_f32_16x16x32_bf16 v[92:95], v[72:75], v[180:183], v[60:63]
	v_mfma_f32_16x16x32_bf16 v[60:63], v[48:51], v[168:171], v[76:79]
	v_mfma_f32_16x16x32_bf16 v[48:51], v[48:51], v[176:179], v[104:107]
	v_mfma_f32_16x16x32_bf16 v[76:79], v[56:59], v[180:183], v[48:51]
	v_mfma_f32_16x16x32_bf16 v[48:51], v[32:35], v[168:171], v[68:71]
	v_mfma_f32_16x16x32_bf16 v[32:35], v[32:35], v[176:179], v[64:67]
	v_mfma_f32_16x16x32_bf16 v[88:91], v[72:75], v[172:175], v[88:91]
	v_mfma_f32_16x16x32_bf16 v[72:75], v[56:59], v[172:175], v[60:63]
	v_mfma_f32_16x16x32_bf16 v[56:59], v[40:43], v[172:175], v[48:51]
	v_mfma_f32_16x16x32_bf16 v[60:63], v[40:43], v[180:183], v[32:35]
	s_setprio 0
	s_barrier
	ds_read_b128 v[96:99], v201 offset:49152
	ds_read_b128 v[100:103], v201 offset:50176
	ds_read_b128 v[104:107], v201 offset:51200
	ds_read_b128 v[192:195], v201 offset:52224
	ds_read_b128 v[196:199], v201 offset:53248
	ds_read_b128 v[204:207], v201 offset:54272
	ds_read_b128 v[212:215], v201 offset:55296
	ds_read_b128 v[216:219], v202 offset:56320
	s_barrier
	s_setprio 1
	s_waitcnt lgkmcnt(7)
	v_mfma_f32_16x16x32_bf16 v[32:35], v[96:99], v[0:3], v[108:111]
	s_waitcnt lgkmcnt(6)
	v_mfma_f32_16x16x32_bf16 v[64:67], v[100:103], v[8:11], v[32:35]
	v_mfma_f32_16x16x32_bf16 v[32:35], v[96:99], v[16:19], v[112:115]
	v_mfma_f32_16x16x32_bf16 v[68:71], v[100:103], v[24:27], v[32:35]
	s_waitcnt lgkmcnt(5)
	v_mfma_f32_16x16x32_bf16 v[32:35], v[104:107], v[0:3], v[52:55]
	s_waitcnt lgkmcnt(4)
	v_mfma_f32_16x16x32_bf16 v[48:51], v[192:195], v[8:11], v[32:35]
	v_mfma_f32_16x16x32_bf16 v[32:35], v[104:107], v[16:19], v[116:119]
	v_mfma_f32_16x16x32_bf16 v[52:55], v[192:195], v[24:27], v[32:35]
	s_waitcnt lgkmcnt(3)
	v_mfma_f32_16x16x32_bf16 v[32:35], v[196:199], v[0:3], v[44:47]
	s_waitcnt lgkmcnt(2)
	v_mfma_f32_16x16x32_bf16 v[40:43], v[204:207], v[8:11], v[32:35]
	v_mfma_f32_16x16x32_bf16 v[32:35], v[196:199], v[16:19], v[120:123]
	s_waitcnt lgkmcnt(1)
	v_mfma_f32_16x16x32_bf16 v[0:3], v[212:215], v[0:3], v[36:39]
	v_mfma_f32_16x16x32_bf16 v[44:47], v[204:207], v[24:27], v[32:35]
	s_waitcnt lgkmcnt(0)
	v_mfma_f32_16x16x32_bf16 v[32:35], v[216:219], v[8:11], v[0:3]
	v_mfma_f32_16x16x32_bf16 v[0:3], v[212:215], v[16:19], v[124:127]
	v_mfma_f32_16x16x32_bf16 v[36:39], v[216:219], v[24:27], v[0:3]
	s_setprio 0
	s_setprio 1
	v_mfma_f32_16x16x32_bf16 v[0:3], v[96:99], v[168:171], v[28:31]
	v_mfma_f32_16x16x32_bf16 v[24:27], v[100:103], v[172:175], v[0:3]
	v_mfma_f32_16x16x32_bf16 v[0:3], v[96:99], v[176:179], v[128:131]
	v_mfma_f32_16x16x32_bf16 v[28:31], v[100:103], v[180:183], v[0:3]
	v_mfma_f32_16x16x32_bf16 v[0:3], v[104:107], v[168:171], v[20:23]
	v_mfma_f32_16x16x32_bf16 v[16:19], v[192:195], v[172:175], v[0:3]
	v_mfma_f32_16x16x32_bf16 v[0:3], v[104:107], v[176:179], v[132:135]
	v_mfma_f32_16x16x32_bf16 v[20:23], v[192:195], v[180:183], v[0:3]
	v_mfma_f32_16x16x32_bf16 v[0:3], v[196:199], v[168:171], v[12:15]
	v_mfma_f32_16x16x32_bf16 v[8:11], v[204:207], v[172:175], v[0:3]
	v_mfma_f32_16x16x32_bf16 v[0:3], v[196:199], v[176:179], v[136:139]
	v_mfma_f32_16x16x32_bf16 v[12:15], v[204:207], v[180:183], v[0:3]
	v_mfma_f32_16x16x32_bf16 v[0:3], v[212:215], v[168:171], v[4:7]
	v_mfma_f32_16x16x32_bf16 v[4:7], v[212:215], v[176:179], v[140:143]
	v_mfma_f32_16x16x32_bf16 v[0:3], v[216:219], v[172:175], v[0:3]
	v_mfma_f32_16x16x32_bf16 v[4:7], v[216:219], v[180:183], v[4:7]
	s_setprio 0
	s_barrier
	s_and_saveexec_b64 s[10:11], s[4:5]
	s_cbranch_execz .LBB0_764
	s_barrier
	s_branch .LBB0_764
